# scan pass 1 fused into the gate GEMM epilogue (A-tile rows permuted so a lane owns 4 consecutive tokens; ordered DPP combine; scan1 phase skipped)
# speedup vs baseline: 1.0263x; 1.0263x over previous
; #define LAS __attribute__((address_space(3)))
; #define PG8_WAIT_V(n) asm volatile("s_waitcnt vmcnt(" #n ")" ::: "memory")
; #define PG8_BAR __builtin_amdgcn_s_barrier()
; template <class Epi>
; __device__ __forceinline__ void gemm_phase(LAS unsigned char* lds, const Gemm g, const StaticOrder& S_in, const Epi& E, int sw) {
;     ...
;     const int tid = ltid(sw);
;     const int wid = __builtin_amdgcn_readfirstlane(tid >> 6), lane = tid & 63, wr = wid >> 2, wc = wid & 3, fr = lane & 15, fq = lane >> 4;
;     const int K = g.K, nt = K / BK;
;     unsigned voffA[2], voffB[2];
; #pragma unroll
;     for (int i = 0; i < 2; ++i) { int R, C; stage_rc(tid * 16 + i * 8192, R, C); const int Rb = (R & ~31) + perm32(R & 31);
;         voffA[i] = (unsigned)(R * g.lda + C) * 2u; voffB[i] = (unsigned)(Rb * g.ldb + C) * 2u; }
;     const size_t kstep = (size_t)(BK * 2);
;     const size_t hstepA = (size_t)HALF * g.lda * 2, hstepB = (size_t)HALF * g.ldb * 2;
;     const unsigned ldsw = (unsigned)wid * 1024u;
;     const int aoff = lds_byte(wr * 64 + fr, fq * 8), boff = lds_byte(wc * 32 + fr, fq * 8);
;     ...
;     Unit cur, nxt; int ui = 0;
;     if (!S.next(0, cur)) return;
;     f32x4 acc[2][2][4][2];
;     E.init(acc, cur, sw);
;     bf16x8 At[4][2], B0[2][2], B1[2][2];
;     const char* cA = PG8_ABASE(cur); const char* cB = PG8_BBASE(cur);
;     PG8_STAGE(PG8_SB(0, 0), cB, voffB); PG8_STAGE(PG8_SA(0, 0), cA, voffA); PG8_STAGE(PG8_SB(0, 1), cB + hstepB, voffB); PG8_STAGE(PG8_SA(0, 1), cA + hstepA, voffA);
;     if (wr == 1) PG8_BAR;
;     PG8_WAIT_V(4); PG8_BAR;
;     PG8_STAGE(PG8_SB(1, 0), cB + kstep, voffB); PG8_STAGE(PG8_SA(1, 0), cA + kstep, voffA); PG8_STAGE(PG8_SB(1, 1), cB + hstepB + kstep, voffB);
;     PG8_WAIT_V(6); PG8_BAR;
;     __device__ __forceinline__ void init(AccMut acc, const Unit& u, int sw) const {
;         const int tid_ = ltid(sw), lane_ = tid_ & 63, wc = sw & 3, fq = lane_ >> 4;
;         const int c0 = u.pn * 128 + wc * 32 + 8 * fq;
; #pragma unroll
;         for (int n = 0; n < 2; ++n) { const f32x4 ga = *(const LAS f32x4*)(gab + c0 + 4 * n), gx = *(const LAS f32x4*)(gxb + c0 + 4 * n);
; #pragma unroll
;             for (int ai = 0; ai < 2; ++ai)
; #pragma unroll
;                 for (int m = 0; m < 4; ++m) { acc[ai][0][m][n] = ga; acc[ai][1][m][n] = gx; } }
.Lgate_ord0_keep:
.LBB0_421:
	s_andn2_b64 vcc, exec, s[16:17]
	s_cbranch_vccnz .LBB0_497
	v_bfe_i32 v3, v26, 27, 1
	v_lshlrev_b32_e32 v2, 4, v26
	v_lshrrev_b32_e32 v3, 22, v3
	v_add_u32_e32 v3, v2, v3
	v_and_b32_e32 v3, 0xfffffc00, v3
	v_sub_u32_e32 v3, v2, v3
	v_ashrrev_i32_e32 v0, 31, v26
	v_lshrrev_b32_e32 v4, 4, v3
	v_lshrrev_b32_e32 v0, 26, v0
	v_bitop3_b32 v4, v4, v3, 32 bitop3:0x6c
	v_ashrrev_i32_e32 v3, 31, v3
	v_add_u32_e32 v0, v26, v0
	v_lshrrev_b32_e32 v3, 26, v3
	v_ashrrev_i32_e32 v0, 6, v0
	v_add_u32_e32 v3, v4, v3
	v_lshlrev_b32_e32 v5, 3, v0
	v_ashrrev_i32_e32 v3, 6, v3
	v_and_b32_e32 v5, -16, v5
	v_mul_i32_i24_e32 v6, 64, v3
	v_add_u32_e32 v5, v3, v5
	v_sub_u32_e32 v4, v4, v6
	v_lshlrev_b32_e32 v0, 5, v0
	v_ashrrev_i16_sdwa v4, v244, sext(v4) dst_sel:DWORD dst_unused:UNUSED_PAD src0_sel:DWORD src1_sel:BYTE_0
	v_lshlrev_b32_e32 v6, 1, v5
	v_lshrrev_b32_e32 v7, 2, v5
	v_and_b32_e32 v3, 3, v3
	s_mov_b32 s17, 0x7fffe0
	v_and_b32_e32 v0, 32, v0
	v_bfe_i32 v4, v4, 0, 16
	v_and_b32_e32 v6, 24, v6
	v_and_b32_e32 v7, 4, v7
	v_and_or_b32 v3, v5, s17, v3
	v_or3_b32 v3, v3, v7, v6
	v_add_lshl_u32 v0, v0, v4, 1
	v_add_u32_e32 v2, 0x2000, v2
	v_and_b32_e32 v6, 15, v5
	v_bfe_u32 v7, v5, 4, 2
	v_lshl_or_b32 v6, v6, 2, v7
	v_and_b32_e32 v7, 0xffffffc0, v5
	v_or_b32_e32 v6, v6, v7
	v_lshl_add_u32 v130, v6, 12, v0
	v_lshl_add_u32 v0, v3, 9, v0
	v_ashrrev_i32_e32 v3, 31, v2
	v_lshrrev_b32_e32 v3, 22, v3
	v_add_u32_e32 v3, v2, v3
	v_ashrrev_i32_e32 v3, 10, v3
	v_mul_i32_i24_e32 v4, 0x400, v3
	v_sub_u32_e32 v2, v2, v4
	v_lshrrev_b32_e32 v4, 4, v2
	v_bitop3_b32 v2, v4, v2, 32 bitop3:0x6c
	v_ashrrev_i32_e32 v5, 31, v2
	v_lshrrev_b32_e32 v5, 26, v5
	v_lshlrev_b32_e32 v4, 3, v3
	v_add_u32_e32 v5, v2, v5
	v_and_b32_e32 v4, -16, v4
	v_ashrrev_i32_e32 v6, 6, v5
	v_add_u32_e32 v4, v6, v4
	v_and_b32_e32 v6, 3, v6
	v_and_or_b32 v6, v4, s17, v6
	s_ashr_i32 s17, s37, 6
	s_ashr_i32 s16, s37, 8
	s_lshl_b32 s38, s17, 10
	s_lshl_b64 s[0:1], s[0:1], 1
	s_add_u32 s6, s6, s0
	v_and_b32_e32 v5, 0xc0, v5
	s_addc_u32 s7, s7, s1
	v_sub_u32_e32 v2, v2, v5
	s_add_u32 s39, s6, 0xe000000
	v_lshlrev_b32_e32 v3, 5, v3
	v_ashrrev_i16_sdwa v2, v244, sext(v2) dst_sel:DWORD dst_unused:UNUSED_PAD src0_sel:DWORD src1_sel:BYTE_0
	v_lshlrev_b32_e32 v5, 1, v4
	v_lshrrev_b32_e32 v7, 2, v4
	s_addc_u32 s40, s7, 0
	v_and_b32_e32 v3, 32, v3
	v_bfe_i32 v2, v2, 0, 16
	v_and_b32_e32 v5, 24, v5
	v_and_b32_e32 v7, 4, v7
	s_add_u32 s41, s4, 0x1e800000
	v_or3_b32 v5, v6, v7, v5
	v_add_lshl_u32 v2, v3, v2, 1
	s_addc_u32 s42, s5, 0
	s_mov_b32 s4, s75
	s_mov_b32 s5, s81
	v_and_b32_e32 v6, 15, v4
	v_bfe_u32 v7, v4, 4, 2
	v_lshl_or_b32 v6, v6, 2, v7
	v_and_b32_e32 v7, 0xffffffc0, v4
	v_or_b32_e32 v6, v6, v7
	v_lshl_add_u32 v132, v6, 12, v2
	v_lshl_add_u32 v134, v5, 9, v2
	s_ashr_i32 s25, s24, 31
	v_mbcnt_lo_u32_b32 v2, -1, s5
	v_mbcnt_hi_u32_b32 v2, -1, v2
	v_lshl_add_u32 v2, s4, 6, v2
	s_lshl_b32 s4, s22, 7
	v_lshrrev_b32_e32 v2, 1, v2
	v_and_or_b32 v2, v2, 24, s4
	s_ashr_i32 s4, s22, 1
	s_ashr_i32 s5, s4, 31
	s_lshl_b64 s[6:7], s[24:25], 20
	s_add_u32 s18, s39, s6
	s_addc_u32 s19, s40, s7
	s_ashr_i32 s23, s22, 31
	s_lshl_b64 s[6:7], s[22:23], 17
	v_or_b32_e32 v2, s85, v2
	s_add_u32 s28, s41, s6
	v_lshl_add_u32 v2, v2, 2, 0
	s_addc_u32 s29, s42, s7
	s_add_i32 s23, s38, 0
	v_add_u32_e32 v3, 0x20400, v2
	v_add_u32_e32 v6, 0x22400, v2
	s_add_i32 m0, s23, 0x10000
	ds_read_b128 v[10:13], v3
	ds_read_b128 v[14:17], v3 offset:16
	ds_read_b128 v[2:5], v6
	ds_read_b128 v[6:9], v6 offset:16
	global_load_lds_dwordx4 v0, s[28:29]
	s_add_i32 m0, s23, 0x12000
	s_lshl_b64 s[4:5], s[4:5], 9
	s_add_u32 s26, s18, s4
	global_load_lds_dwordx4 v134, s[28:29]
	s_addc_u32 s27, s19, s5
	s_mov_b32 m0, s23
	s_add_i32 s25, s23, 0x2000
	global_load_lds_dwordx4 v130, s[26:27]
	s_mov_b32 m0, s25
	s_add_u32 s4, s28, 0x10000
	global_load_lds_dwordx4 v132, s[26:27]
	s_addc_u32 s5, s29, 0
	s_add_i32 m0, s23, 0x14000
	v_mov_b32_e32 v135, v1
	global_load_lds_dwordx4 v0, s[4:5]
	s_add_i32 m0, s23, 0x16000
	v_mov_b32_e32 v131, v1
	global_load_lds_dwordx4 v134, s[4:5]
	s_add_u32 s4, s26, 0x80000
	s_addc_u32 s5, s27, 0
	s_add_i32 s43, s23, 0x4000
	s_mov_b32 m0, s43
	s_add_i32 s44, s23, 0x6000
	global_load_lds_dwordx4 v130, s[4:5]
	s_mov_b32 m0, s44
	v_mov_b32_e32 v133, v1
	global_load_lds_dwordx4 v132, s[4:5]
	v_lshl_add_u64 v[24:25], s[28:29], 0, v[0:1]
	v_lshl_add_u64 v[22:23], s[28:29], 0, v[134:135]
	v_lshl_add_u64 v[20:21], s[26:27], 0, v[130:131]
	s_cmp_lg_u32 s16, 1
	v_lshl_add_u64 v[18:19], s[26:27], 0, v[132:133]
	s_cbranch_scc1 .LBB0_424
	s_barrier

; #define PG8_STAGE(bufoff, gbase, voff) do { _Pragma("unroll") for (int _i = 0; _i < 2; ++_i) \
;         __builtin_amdgcn_global_load_lds((const __attribute__((address_space(1))) unsigned*)((const char*)(gbase) + (voff)[_i]), (LAS unsigned*)(lds + (bufoff) + ldsw + _i * 8192), 16, 0, 0); } while (0)
; #define PG8_LDA(dst, b, h) do { _Pragma("unroll") for (int m = 0; m < 4; ++m) _Pragma("unroll") for (int k = 0; k < 2; ++k) dst[m][k] = *(const LAS bf16x8*)(lds + PG8_SA(b, h) + aoff + m * 2048 + k * 1024); } while (0)
; #define PG8_LDB(dst, b, h) do { _Pragma("unroll") for (int n = 0; n < 2; ++n) _Pragma("unroll") for (int k = 0; k < 2; ++k) dst[n][k] = *(const LAS bf16x8*)(lds + PG8_SB(b, h) + boff + n * 2048 + k * 1024); } while (0)
; #define PG8_MMA(ai, bj, At, Bt) do { __builtin_amdgcn_s_setprio(1); _Pragma("unroll") for (int m = 0; m < 4; ++m) _Pragma("unroll") for (int n = 0; n < 2; ++n) _Pragma("unroll") for (int k = 0; k < 2; ++k) \
;         acc[ai][bj][m][n] = __builtin_amdgcn_mfma_f32_16x16x32_bf16(Bt[n][k], At[m][k], acc[ai][bj][m][n], 0, 0, 0); __builtin_amdgcn_s_setprio(0); } while (0)
; #define PG8_WAIT_L(n) asm volatile("s_waitcnt lgkmcnt(" #n ")" ::: "memory")
; template <class Epi>
; __device__ __forceinline__ void gemm_phase(LAS unsigned char* lds, const Gemm g, const StaticOrder& S_in, const Epi& E, int sw) {
;     ...
;         const bool has_next = S.next(ui + 1, nxt);
;         const char* nA = has_next ? PG8_ABASE(nxt) : cA; const char* nB = has_next ? PG8_BBASE(nxt) : cB;
;         for (int t = 0; t < nt; t += 2) {
;             const bool last = (t == nt - 2);
;             const char* a1 = cA + (size_t)(t + 1) * kstep;
;             const char* a2 = last ? nA : cA + (size_t)(t + 2) * kstep; const char* b2 = last ? nB : cB + (size_t)(t + 2) * kstep;
;             const char* a3 = a2 + kstep; const char* b3 = b2 + kstep;
;             PG8_LDB(B0, 0, 0); PG8_SCHED; PG8_LDA(At, 0, 0); PG8_STAGE(PG8_SA(1, 1), a1 + hstepA, voffA);
;             PG8_WAIT_L(8); PG8_BAR; PG8_WAIT_L(0); PG8_MMA(0, 0, At, B0); PG8_BAR; PG8_SCHED;
;             PG8_LDB(B1, 0, 1); PG8_STAGE(PG8_SB(0, 0), b2, voffB);
;             PG8_BAR; PG8_WAIT_L(0); PG8_MMA(0, 1, At, B1); PG8_BAR;
;             PG8_LDA(At, 0, 1); PG8_STAGE(PG8_SA(0, 0), a2, voffA);
;             PG8_BAR; PG8_WAIT_L(0); PG8_MMA(1, 0, At, B0); PG8_BAR; PG8_SCHED;
.Lgate_ord_keep:
.LBB0_428:
	s_ashr_i32 s18, s12, 1
	s_ashr_i32 s17, s16, 31
	s_ashr_i32 s19, s18, 31
	s_lshl_b64 s[18:19], s[18:19], 9
	s_lshl_b64 s[20:21], s[16:17], 20
	s_add_u32 s13, s39, s20
	s_addc_u32 s17, s40, s21
	s_add_u32 s18, s13, s18
	s_addc_u32 s19, s17, s19
	s_and_b64 s[20:21], s[4:5], exec
	s_cselect_b32 s35, s19, s27
	s_cselect_b32 s34, s18, s26
	s_ashr_i32 s13, s12, 31
	s_lshl_b64 s[20:21], s[12:13], 17
	s_add_u32 s20, s41, s20
	s_addc_u32 s21, s42, s21
	s_and_b64 s[30:31], s[4:5], exec
	s_cselect_b32 s31, s21, s29
	s_cselect_b32 s30, s20, s28
	s_add_i32 s17, 0, 0x10000
	v_add_u32_e32 v175, s17, v171
	ds_read_b128 v[18:21], v175
	ds_read_b128 v[22:25], v175 offset:1024
	ds_read_b128 v[26:29], v175 offset:2048
	ds_read_b128 v[30:33], v175 offset:3072
	s_add_u32 s48, s26, 0x80080
	s_addc_u32 s49, s27, 0
	s_add_i32 s50, s23, 0xc000
	v_lshl_add_u64 v[66:67], s[48:49], 0, v[130:131]
	s_mov_b32 m0, s50
	s_add_i32 s13, s23, 0xe000
	ds_read_b128 v[34:37], v174
	ds_read_b128 v[38:41], v174 offset:1024
	ds_read_b128 v[42:45], v174 offset:2048
	ds_read_b128 v[46:49], v174 offset:3072
	ds_read_b128 v[50:53], v174 offset:4096
	ds_read_b128 v[54:57], v174 offset:5120
	ds_read_b128 v[58:61], v174 offset:6144
	ds_read_b128 v[62:65], v174 offset:7168
	global_load_lds_dwordx4 v[66:67], off
	v_lshl_add_u64 v[66:67], s[48:49], 0, v[132:133]
	s_mov_b32 m0, s13
	s_nop 0
	global_load_lds_dwordx4 v[66:67], off
	s_waitcnt lgkmcnt(8)
	s_barrier
	s_waitcnt lgkmcnt(0)
	s_setprio 1
	s_waitcnt lgkmcnt(0)
	v_mfma_f32_16x16x32_bf16 v[66:69], v[18:21], v[34:37], v[10:13]
	v_mfma_f32_16x16x32_bf16 v[70:73], v[26:29], v[34:37], v[14:17]
	v_mfma_f32_16x16x32_bf16 v[74:77], v[18:21], v[42:45], v[10:13]
	v_mfma_f32_16x16x32_bf16 v[78:81], v[26:29], v[42:45], v[14:17]
	v_mfma_f32_16x16x32_bf16 v[82:85], v[18:21], v[50:53], v[10:13]
	v_mfma_f32_16x16x32_bf16 v[86:89], v[26:29], v[50:53], v[14:17]
	v_mfma_f32_16x16x32_bf16 v[90:93], v[18:21], v[58:61], v[10:13]
	v_mfma_f32_16x16x32_bf16 v[94:97], v[26:29], v[58:61], v[14:17]
	v_mfma_f32_16x16x32_bf16 v[66:69], v[22:25], v[38:41], v[66:69]
	v_mfma_f32_16x16x32_bf16 v[70:73], v[30:33], v[38:41], v[70:73]
	v_mfma_f32_16x16x32_bf16 v[74:77], v[22:25], v[46:49], v[74:77]
	v_mfma_f32_16x16x32_bf16 v[78:81], v[30:33], v[46:49], v[78:81]
	v_mfma_f32_16x16x32_bf16 v[82:85], v[22:25], v[54:57], v[82:85]
	v_mfma_f32_16x16x32_bf16 v[86:89], v[30:33], v[54:57], v[86:89]
	v_mfma_f32_16x16x32_bf16 v[90:93], v[22:25], v[62:65], v[90:93]
	v_mfma_f32_16x16x32_bf16 v[94:97], v[30:33], v[62:65], v[94:97]
	s_setprio 0
	s_barrier
	s_add_i32 s51, 0, 0x14000
	v_lshl_add_u64 v[168:169], s[28:29], 0, v[0:1]
	s_mov_b64 s[52:53], 0x100
	s_add_i32 s49, s17, s38
	v_add_u32_e32 v212, s51, v171
	v_lshl_add_u64 v[114:115], v[168:169], 0, s[52:53]
	s_mov_b32 m0, s49
	v_lshl_add_u64 v[172:173], s[28:29], 0, v[134:135]
	s_add_i32 s17, s49, 0x2000
	ds_read_b128 v[98:101], v212
	ds_read_b128 v[102:105], v212 offset:1024
	ds_read_b128 v[106:109], v212 offset:2048
	ds_read_b128 v[110:113], v212 offset:3072
	global_load_lds_dwordx4 v[114:115], off
	v_lshl_add_u64 v[114:115], v[172:173], 0, s[52:53]
	s_mov_b32 m0, s17
	s_nop 0
	global_load_lds_dwordx4 v[114:115], off
	s_barrier
	s_waitcnt lgkmcnt(0)
	s_setprio 1
	s_waitcnt lgkmcnt(0)
	v_mfma_f32_16x16x32_bf16 v[114:117], v[98:101], v[34:37], v[2:5]
	v_mfma_f32_16x16x32_bf16 v[34:37], v[106:109], v[34:37], v[6:9]
	v_mfma_f32_16x16x32_bf16 v[114:117], v[102:105], v[38:41], v[114:117]
	v_mfma_f32_16x16x32_bf16 v[34:37], v[110:113], v[38:41], v[34:37]
	v_mfma_f32_16x16x32_bf16 v[38:41], v[98:101], v[42:45], v[2:5]
	v_mfma_f32_16x16x32_bf16 v[42:45], v[106:109], v[42:45], v[6:9]
	v_mfma_f32_16x16x32_bf16 v[38:41], v[102:105], v[46:49], v[38:41]
	v_mfma_f32_16x16x32_bf16 v[42:45], v[110:113], v[46:49], v[42:45]
	v_mfma_f32_16x16x32_bf16 v[46:49], v[98:101], v[50:53], v[2:5]
	v_mfma_f32_16x16x32_bf16 v[50:53], v[106:109], v[50:53], v[6:9]
	v_mfma_f32_16x16x32_bf16 v[46:49], v[102:105], v[54:57], v[46:49]
	v_mfma_f32_16x16x32_bf16 v[50:53], v[110:113], v[54:57], v[50:53]
	v_mfma_f32_16x16x32_bf16 v[54:57], v[98:101], v[58:61], v[2:5]
	v_mfma_f32_16x16x32_bf16 v[58:61], v[106:109], v[58:61], v[6:9]
	v_mfma_f32_16x16x32_bf16 v[54:57], v[102:105], v[62:65], v[54:57]
	v_mfma_f32_16x16x32_bf16 v[58:61], v[110:113], v[62:65], v[58:61]
	s_setprio 0
	v_lshl_add_u64 v[208:209], s[26:27], 0, v[130:131]
	s_mov_b32 m0, s23
	v_lshl_add_u64 v[152:153], v[208:209], 0, s[52:53]
	v_lshl_add_u64 v[210:211], s[26:27], 0, v[132:133]
	s_barrier
	ds_read_b128 v[62:65], v174 offset:16384
	ds_read_b128 v[118:121], v174 offset:17408
	ds_read_b128 v[122:125], v174 offset:18432
	ds_read_b128 v[126:129], v174 offset:19456
	ds_read_b128 v[136:139], v174 offset:20480
	ds_read_b128 v[140:143], v174 offset:21504
	ds_read_b128 v[144:147], v174 offset:22528
	ds_read_b128 v[148:151], v174 offset:23552
	global_load_lds_dwordx4 v[152:153], off
	v_lshl_add_u64 v[152:153], v[210:211], 0, s[52:53]
	s_mov_b32 m0, s25
	s_nop 0
	global_load_lds_dwordx4 v[152:153], off
	s_barrier
; #define PG8_STAGE(bufoff, gbase, voff) do { _Pragma("unroll") for (int _i = 0; _i < 2; ++_i) \
;         __builtin_amdgcn_global_load_lds((const __attribute__((address_space(1))) unsigned*)((const char*)(gbase) + (voff)[_i]), (LAS unsigned*)(lds + (bufoff) + ldsw + _i * 8192), 16, 0, 0); } while (0)
; #define PG8_LDA(dst, b, h) do { _Pragma("unroll") for (int m = 0; m < 4; ++m) _Pragma("unroll") for (int k = 0; k < 2; ++k) dst[m][k] = *(const LAS bf16x8*)(lds + PG8_SA(b, h) + aoff + m * 2048 + k * 1024); } while (0)
; #define PG8_LDB(dst, b, h) do { _Pragma("unroll") for (int n = 0; n < 2; ++n) _Pragma("unroll") for (int k = 0; k < 2; ++k) dst[n][k] = *(const LAS bf16x8*)(lds + PG8_SB(b, h) + boff + n * 2048 + k * 1024); } while (0)
; #define PG8_MMA(ai, bj, At, Bt) do { __builtin_amdgcn_s_setprio(1); _Pragma("unroll") for (int m = 0; m < 4; ++m) _Pragma("unroll") for (int n = 0; n < 2; ++n) _Pragma("unroll") for (int k = 0; k < 2; ++k) \
;         acc[ai][bj][m][n] = __builtin_amdgcn_mfma_f32_16x16x32_bf16(Bt[n][k], At[m][k], acc[ai][bj][m][n], 0, 0, 0); __builtin_amdgcn_s_setprio(0); } while (0)
; #define PG8_WAIT_V(n) asm volatile("s_waitcnt vmcnt(" #n ")" ::: "memory")
; #define PG8_WAIT_L(n) asm volatile("s_waitcnt lgkmcnt(" #n ")" ::: "memory")
; #define PG8_BAR __builtin_amdgcn_s_barrier()
; #define PG8_SCHED __builtin_amdgcn_sched_barrier(0)
; template <class Epi>
; __device__ __forceinline__ void gemm_phase(LAS unsigned char* lds, const Gemm g, const StaticOrder& S_in, const Epi& E, int sw) {
;     ...
;             PG8_WAIT_L(8); PG8_BAR; PG8_WAIT_L(0); PG8_MMA(0, 0, At, B0); PG8_BAR; PG8_SCHED;
;             PG8_LDB(B1, 0, 1); PG8_STAGE(PG8_SB(0, 0), b2, voffB);
;             PG8_BAR; PG8_WAIT_L(0); PG8_MMA(0, 1, At, B1); PG8_BAR;
;             PG8_LDA(At, 0, 1); PG8_STAGE(PG8_SA(0, 0), a2, voffA);
;             PG8_BAR; PG8_WAIT_L(0); PG8_MMA(1, 0, At, B0); PG8_BAR; PG8_SCHED;
;             PG8_STAGE(PG8_SB(0, 1), b2 + hstepB, voffB);
;             PG8_WAIT_V(6); PG8_BAR; PG8_MMA(1, 1, At, B1); PG8_BAR;
;             PG8_LDB(B0, 1, 0); PG8_SCHED; PG8_LDA(At, 1, 0); PG8_STAGE(PG8_SA(0, 1), a2 + hstepA, voffA);
;             PG8_WAIT_L(8); PG8_BAR; PG8_WAIT_L(0); PG8_MMA(0, 0, At, B0); PG8_BAR; PG8_SCHED;
;             PG8_LDB(B1, 1, 1); PG8_STAGE(PG8_SB(1, 0), b3, voffB);
;             PG8_BAR; PG8_WAIT_L(0); PG8_MMA(0, 1, At, B1); PG8_BAR;
	s_waitcnt lgkmcnt(0)
	s_setprio 1
	s_waitcnt lgkmcnt(0)
	v_mfma_f32_16x16x32_bf16 v[152:155], v[18:21], v[62:65], v[10:13]
	v_mfma_f32_16x16x32_bf16 v[156:159], v[26:29], v[62:65], v[14:17]
	v_mfma_f32_16x16x32_bf16 v[160:163], v[18:21], v[122:125], v[10:13]
	v_mfma_f32_16x16x32_bf16 v[164:167], v[26:29], v[122:125], v[14:17]
	v_mfma_f32_16x16x32_bf16 v[176:179], v[18:21], v[136:139], v[10:13]
	v_mfma_f32_16x16x32_bf16 v[180:183], v[26:29], v[136:139], v[14:17]
	v_mfma_f32_16x16x32_bf16 v[10:13], v[18:21], v[144:147], v[10:13]
	v_mfma_f32_16x16x32_bf16 v[14:17], v[26:29], v[144:147], v[14:17]
	v_mfma_f32_16x16x32_bf16 v[152:155], v[22:25], v[118:121], v[152:155]
	v_mfma_f32_16x16x32_bf16 v[156:159], v[30:33], v[118:121], v[156:159]
	v_mfma_f32_16x16x32_bf16 v[160:163], v[22:25], v[126:129], v[160:163]
	v_mfma_f32_16x16x32_bf16 v[164:167], v[30:33], v[126:129], v[164:167]
	v_mfma_f32_16x16x32_bf16 v[10:13], v[22:25], v[148:151], v[10:13]
	v_mfma_f32_16x16x32_bf16 v[14:17], v[30:33], v[148:151], v[14:17]
	v_mfma_f32_16x16x32_bf16 v[176:179], v[22:25], v[140:143], v[176:179]
	v_mfma_f32_16x16x32_bf16 v[180:183], v[30:33], v[140:143], v[180:183]
	s_setprio 0
	s_barrier
	s_add_u32 s52, s28, 0x10100
	s_addc_u32 s53, s29, 0
	s_add_i32 s51, s51, s38
	v_lshl_add_u64 v[18:19], s[52:53], 0, v[0:1]
	s_mov_b32 m0, s51
	s_add_i32 s48, s51, 0x2000
	global_load_lds_dwordx4 v[18:19], off
	v_lshl_add_u64 v[18:19], s[52:53], 0, v[134:135]
	s_mov_b32 m0, s48
	s_nop 0
	global_load_lds_dwordx4 v[18:19], off
	s_waitcnt vmcnt(6)
	s_barrier
	s_setprio 1
	v_mfma_f32_16x16x32_bf16 v[18:21], v[98:101], v[62:65], v[2:5]
	v_mfma_f32_16x16x32_bf16 v[22:25], v[106:109], v[62:65], v[6:9]
	v_mfma_f32_16x16x32_bf16 v[18:21], v[102:105], v[118:121], v[18:21]
	v_mfma_f32_16x16x32_bf16 v[22:25], v[110:113], v[118:121], v[22:25]
	v_mfma_f32_16x16x32_bf16 v[26:29], v[98:101], v[122:125], v[2:5]
	v_mfma_f32_16x16x32_bf16 v[30:33], v[106:109], v[122:125], v[6:9]
	v_mfma_f32_16x16x32_bf16 v[62:65], v[98:101], v[136:139], v[2:5]
	v_mfma_f32_16x16x32_bf16 v[118:121], v[106:109], v[136:139], v[6:9]
	v_mfma_f32_16x16x32_bf16 v[2:5], v[98:101], v[144:147], v[2:5]
	v_mfma_f32_16x16x32_bf16 v[6:9], v[106:109], v[144:147], v[6:9]
	v_mfma_f32_16x16x32_bf16 v[26:29], v[102:105], v[126:129], v[26:29]
	v_mfma_f32_16x16x32_bf16 v[30:33], v[110:113], v[126:129], v[30:33]
	v_mfma_f32_16x16x32_bf16 v[62:65], v[102:105], v[140:143], v[62:65]
	v_mfma_f32_16x16x32_bf16 v[118:121], v[110:113], v[140:143], v[118:121]
	v_mfma_f32_16x16x32_bf16 v[2:5], v[102:105], v[148:151], v[2:5]
	v_mfma_f32_16x16x32_bf16 v[6:9], v[110:113], v[148:151], v[6:9]
	s_setprio 0
	s_add_i32 s54, 0, 0x18000
	v_add_u32_e32 v220, s54, v171
	s_barrier
	ds_read_b128 v[98:101], v220
	ds_read_b128 v[102:105], v220 offset:1024
	ds_read_b128 v[106:109], v220 offset:2048
	ds_read_b128 v[110:113], v220 offset:3072
	s_add_u32 s52, s26, 0x80100
	s_addc_u32 s53, s27, 0
	s_mov_b32 m0, s43
	v_lshl_add_u64 v[192:193], s[52:53], 0, v[130:131]
	ds_read_b128 v[122:125], v174 offset:32768
	ds_read_b128 v[126:129], v174 offset:33792
	ds_read_b128 v[136:139], v174 offset:34816
	ds_read_b128 v[140:143], v174 offset:35840
	ds_read_b128 v[144:147], v174 offset:36864
	ds_read_b128 v[148:151], v174 offset:37888
	ds_read_b128 v[184:187], v174 offset:38912
	ds_read_b128 v[188:191], v174 offset:39936
	global_load_lds_dwordx4 v[192:193], off
	v_lshl_add_u64 v[192:193], s[52:53], 0, v[132:133]
	s_mov_b32 m0, s44
	s_nop 0
	global_load_lds_dwordx4 v[192:193], off
	s_waitcnt lgkmcnt(8)
	s_barrier
	s_waitcnt lgkmcnt(0)
	s_setprio 1
	s_waitcnt lgkmcnt(0)
	v_mfma_f32_16x16x32_bf16 v[66:69], v[98:101], v[122:125], v[66:69]
	v_mfma_f32_16x16x32_bf16 v[70:73], v[106:109], v[122:125], v[70:73]
	v_mfma_f32_16x16x32_bf16 v[74:77], v[98:101], v[136:139], v[74:77]
	v_mfma_f32_16x16x32_bf16 v[78:81], v[106:109], v[136:139], v[78:81]
	v_mfma_f32_16x16x32_bf16 v[82:85], v[98:101], v[144:147], v[82:85]
	v_mfma_f32_16x16x32_bf16 v[86:89], v[106:109], v[144:147], v[86:89]
	v_mfma_f32_16x16x32_bf16 v[90:93], v[98:101], v[184:187], v[90:93]
	v_mfma_f32_16x16x32_bf16 v[94:97], v[106:109], v[184:187], v[94:97]
	v_mfma_f32_16x16x32_bf16 v[66:69], v[102:105], v[126:129], v[66:69]
	v_mfma_f32_16x16x32_bf16 v[70:73], v[110:113], v[126:129], v[70:73]
	v_mfma_f32_16x16x32_bf16 v[74:77], v[102:105], v[140:143], v[74:77]
	v_mfma_f32_16x16x32_bf16 v[78:81], v[110:113], v[140:143], v[78:81]
	v_mfma_f32_16x16x32_bf16 v[82:85], v[102:105], v[148:151], v[82:85]
	v_mfma_f32_16x16x32_bf16 v[86:89], v[110:113], v[148:151], v[86:89]
	v_mfma_f32_16x16x32_bf16 v[90:93], v[102:105], v[188:191], v[90:93]
	v_mfma_f32_16x16x32_bf16 v[94:97], v[110:113], v[188:191], v[94:97]
	s_setprio 0
	s_barrier
	s_add_i32 s56, 0, 0x1c000
	s_mov_b64 s[58:59], 0x180
	s_add_i32 s53, s54, s38
	v_add_u32_e32 v232, s56, v171
	v_lshl_add_u64 v[168:169], v[168:169], 0, s[58:59]
	s_mov_b32 m0, s53
	s_add_i32 s52, s53, 0x2000
	ds_read_b128 v[192:195], v232
	ds_read_b128 v[196:199], v232 offset:1024
	ds_read_b128 v[200:203], v232 offset:2048
	ds_read_b128 v[204:207], v232 offset:3072
	global_load_lds_dwordx4 v[168:169], off
	v_lshl_add_u64 v[168:169], v[172:173], 0, s[58:59]
	s_mov_b32 m0, s52
	s_nop 0
	global_load_lds_dwordx4 v[168:169], off
	s_barrier
; #define PG8_STAGE(bufoff, gbase, voff) do { _Pragma("unroll") for (int _i = 0; _i < 2; ++_i) \
;         __builtin_amdgcn_global_load_lds((const __attribute__((address_space(1))) unsigned*)((const char*)(gbase) + (voff)[_i]), (LAS unsigned*)(lds + (bufoff) + ldsw + _i * 8192), 16, 0, 0); } while (0)
; #define PG8_LDA(dst, b, h) do { _Pragma("unroll") for (int m = 0; m < 4; ++m) _Pragma("unroll") for (int k = 0; k < 2; ++k) dst[m][k] = *(const LAS bf16x8*)(lds + PG8_SA(b, h) + aoff + m * 2048 + k * 1024); } while (0)
; #define PG8_LDB(dst, b, h) do { _Pragma("unroll") for (int n = 0; n < 2; ++n) _Pragma("unroll") for (int k = 0; k < 2; ++k) dst[n][k] = *(const LAS bf16x8*)(lds + PG8_SB(b, h) + boff + n * 2048 + k * 1024); } while (0)
; #define PG8_MMA(ai, bj, At, Bt) do { __builtin_amdgcn_s_setprio(1); _Pragma("unroll") for (int m = 0; m < 4; ++m) _Pragma("unroll") for (int n = 0; n < 2; ++n) _Pragma("unroll") for (int k = 0; k < 2; ++k) \
;         acc[ai][bj][m][n] = __builtin_amdgcn_mfma_f32_16x16x32_bf16(Bt[n][k], At[m][k], acc[ai][bj][m][n], 0, 0, 0); __builtin_amdgcn_s_setprio(0); } while (0)
; #define PG8_WAIT_V(n) asm volatile("s_waitcnt vmcnt(" #n ")" ::: "memory")
; #define PG8_WAIT_L(n) asm volatile("s_waitcnt lgkmcnt(" #n ")" ::: "memory")
; #define PG8_BAR __builtin_amdgcn_s_barrier()
; #define PG8_SCHED __builtin_amdgcn_sched_barrier(0)
; template <class Epi>
; __device__ __forceinline__ void gemm_phase(LAS unsigned char* lds, const Gemm g, const StaticOrder& S_in, const Epi& E, int sw) {
;     ...
;             PG8_WAIT_V(6); PG8_BAR; PG8_MMA(1, 1, At, B1); PG8_BAR;
;             PG8_LDB(B0, 1, 0); PG8_SCHED; PG8_LDA(At, 1, 0); PG8_STAGE(PG8_SA(0, 1), a2 + hstepA, voffA);
;             PG8_WAIT_L(8); PG8_BAR; PG8_WAIT_L(0); PG8_MMA(0, 0, At, B0); PG8_BAR; PG8_SCHED;
;             PG8_LDB(B1, 1, 1); PG8_STAGE(PG8_SB(1, 0), b3, voffB);
;             PG8_BAR; PG8_WAIT_L(0); PG8_MMA(0, 1, At, B1); PG8_BAR;
;             PG8_LDA(At, 1, 1); PG8_STAGE(PG8_SA(1, 0), a3, voffA);
;             PG8_BAR; PG8_WAIT_L(0); PG8_MMA(1, 0, At, B0); PG8_BAR; PG8_SCHED;
;             PG8_STAGE(PG8_SB(1, 1), b3 + hstepB, voffB);
;             PG8_WAIT_V(6); PG8_BAR; PG8_MMA(1, 1, At, B1); PG8_BAR;
	s_waitcnt lgkmcnt(0)
	s_setprio 1
	s_waitcnt lgkmcnt(0)
	v_mfma_f32_16x16x32_bf16 v[114:117], v[192:195], v[122:125], v[114:117]
	v_mfma_f32_16x16x32_bf16 v[34:37], v[200:203], v[122:125], v[34:37]
	v_mfma_f32_16x16x32_bf16 v[38:41], v[192:195], v[136:139], v[38:41]
	v_mfma_f32_16x16x32_bf16 v[42:45], v[200:203], v[136:139], v[42:45]
	v_mfma_f32_16x16x32_bf16 v[46:49], v[192:195], v[144:147], v[46:49]
	v_mfma_f32_16x16x32_bf16 v[50:53], v[200:203], v[144:147], v[50:53]
	v_mfma_f32_16x16x32_bf16 v[54:57], v[192:195], v[184:187], v[54:57]
	v_mfma_f32_16x16x32_bf16 v[58:61], v[200:203], v[184:187], v[58:61]
	v_mfma_f32_16x16x32_bf16 v[114:117], v[196:199], v[126:129], v[114:117]
	v_mfma_f32_16x16x32_bf16 v[34:37], v[204:207], v[126:129], v[34:37]
	v_mfma_f32_16x16x32_bf16 v[38:41], v[196:199], v[140:143], v[38:41]
	v_mfma_f32_16x16x32_bf16 v[42:45], v[204:207], v[140:143], v[42:45]
	v_mfma_f32_16x16x32_bf16 v[46:49], v[196:199], v[148:151], v[46:49]
	v_mfma_f32_16x16x32_bf16 v[50:53], v[204:207], v[148:151], v[50:53]
	v_mfma_f32_16x16x32_bf16 v[54:57], v[196:199], v[188:191], v[54:57]
	v_mfma_f32_16x16x32_bf16 v[58:61], v[204:207], v[188:191], v[58:61]
	s_setprio 0
	s_mov_b32 m0, s45
	v_lshl_add_u64 v[168:169], v[208:209], 0, s[58:59]
	s_barrier
	ds_read_b128 v[122:125], v174 offset:49152
	ds_read_b128 v[126:129], v174 offset:50176
	ds_read_b128 v[136:139], v174 offset:51200
	ds_read_b128 v[140:143], v174 offset:52224
	ds_read_b128 v[144:147], v174 offset:53248
	ds_read_b128 v[148:151], v174 offset:54272
	ds_read_b128 v[184:187], v174 offset:55296
	ds_read_b128 v[188:191], v174 offset:56320
	global_load_lds_dwordx4 v[168:169], off
	v_lshl_add_u64 v[168:169], v[210:211], 0, s[58:59]
	s_mov_b32 m0, s46
	s_nop 0
	global_load_lds_dwordx4 v[168:169], off
	s_barrier
	s_waitcnt lgkmcnt(0)
	s_setprio 1
	s_waitcnt lgkmcnt(0)
	v_mfma_f32_16x16x32_bf16 v[152:155], v[98:101], v[122:125], v[152:155]
	v_mfma_f32_16x16x32_bf16 v[156:159], v[106:109], v[122:125], v[156:159]
	v_mfma_f32_16x16x32_bf16 v[160:163], v[98:101], v[136:139], v[160:163]
	v_mfma_f32_16x16x32_bf16 v[164:167], v[106:109], v[136:139], v[164:167]
	v_mfma_f32_16x16x32_bf16 v[10:13], v[98:101], v[184:187], v[10:13]
	v_mfma_f32_16x16x32_bf16 v[14:17], v[106:109], v[184:187], v[14:17]
	v_mfma_f32_16x16x32_bf16 v[152:155], v[102:105], v[126:129], v[152:155]
	v_mfma_f32_16x16x32_bf16 v[156:159], v[110:113], v[126:129], v[156:159]
	v_mfma_f32_16x16x32_bf16 v[160:163], v[102:105], v[140:143], v[160:163]
	v_mfma_f32_16x16x32_bf16 v[164:167], v[110:113], v[140:143], v[164:167]
	v_mfma_f32_16x16x32_bf16 v[176:179], v[98:101], v[144:147], v[176:179]
	v_mfma_f32_16x16x32_bf16 v[180:183], v[106:109], v[144:147], v[180:183]
	v_mfma_f32_16x16x32_bf16 v[10:13], v[102:105], v[188:191], v[10:13]
	v_mfma_f32_16x16x32_bf16 v[14:17], v[110:113], v[188:191], v[14:17]
	v_mfma_f32_16x16x32_bf16 v[176:179], v[102:105], v[148:151], v[176:179]
	v_mfma_f32_16x16x32_bf16 v[180:183], v[110:113], v[148:151], v[180:183]
	s_setprio 0
	s_barrier
	s_add_u32 s54, s28, 0x10180
	s_addc_u32 s55, s29, 0
	s_add_i32 s29, s56, s38
	v_lshl_add_u64 v[98:99], s[54:55], 0, v[0:1]
	s_mov_b32 m0, s29
	s_add_i32 s28, s29, 0x2000
	global_load_lds_dwordx4 v[98:99], off
	v_lshl_add_u64 v[98:99], s[54:55], 0, v[134:135]
	s_mov_b32 m0, s28
	s_nop 0
	global_load_lds_dwordx4 v[98:99], off
	s_waitcnt vmcnt(6)
	s_barrier
	s_setprio 1
	v_mfma_f32_16x16x32_bf16 v[18:21], v[192:195], v[122:125], v[18:21]
	v_mfma_f32_16x16x32_bf16 v[22:25], v[200:203], v[122:125], v[22:25]
	v_mfma_f32_16x16x32_bf16 v[26:29], v[192:195], v[136:139], v[26:29]
	v_mfma_f32_16x16x32_bf16 v[30:33], v[200:203], v[136:139], v[30:33]
	v_mfma_f32_16x16x32_bf16 v[62:65], v[192:195], v[144:147], v[62:65]
	v_mfma_f32_16x16x32_bf16 v[98:101], v[200:203], v[144:147], v[118:121]
	v_mfma_f32_16x16x32_bf16 v[2:5], v[192:195], v[184:187], v[2:5]
	v_mfma_f32_16x16x32_bf16 v[6:9], v[200:203], v[184:187], v[6:9]
	v_mfma_f32_16x16x32_bf16 v[18:21], v[196:199], v[126:129], v[18:21]
	v_mfma_f32_16x16x32_bf16 v[22:25], v[204:207], v[126:129], v[22:25]
	v_mfma_f32_16x16x32_bf16 v[26:29], v[196:199], v[140:143], v[26:29]
	v_mfma_f32_16x16x32_bf16 v[30:33], v[204:207], v[140:143], v[30:33]
	v_mfma_f32_16x16x32_bf16 v[62:65], v[196:199], v[148:151], v[62:65]
	v_mfma_f32_16x16x32_bf16 v[98:101], v[204:207], v[148:151], v[98:101]
	v_mfma_f32_16x16x32_bf16 v[2:5], v[196:199], v[188:191], v[2:5]
	v_mfma_f32_16x16x32_bf16 v[6:9], v[204:207], v[188:191], v[6:9]
	s_setprio 0
	s_barrier
	ds_read_b128 v[102:105], v175
	ds_read_b128 v[106:109], v175 offset:1024
	ds_read_b128 v[110:113], v175 offset:2048
	ds_read_b128 v[118:121], v175 offset:3072
	s_add_u32 s26, s26, 0x80180
	s_addc_u32 s27, s27, 0
	s_mov_b32 m0, s50
	v_lshl_add_u64 v[168:169], s[26:27], 0, v[130:131]
	ds_read_b128 v[122:125], v174
	ds_read_b128 v[126:129], v174 offset:1024
	ds_read_b128 v[136:139], v174 offset:2048
	ds_read_b128 v[140:143], v174 offset:3072
	ds_read_b128 v[144:147], v174 offset:4096
	ds_read_b128 v[148:151], v174 offset:5120
	ds_read_b128 v[184:187], v174 offset:6144
	ds_read_b128 v[188:191], v174 offset:7168
	global_load_lds_dwordx4 v[168:169], off
	v_lshl_add_u64 v[168:169], s[26:27], 0, v[132:133]
	s_mov_b32 m0, s13
	s_nop 0
	global_load_lds_dwordx4 v[168:169], off
	s_waitcnt lgkmcnt(8)
	s_barrier
; #define PG8_STAGE(bufoff, gbase, voff) do { _Pragma("unroll") for (int _i = 0; _i < 2; ++_i) \
;         __builtin_amdgcn_global_load_lds((const __attribute__((address_space(1))) unsigned*)((const char*)(gbase) + (voff)[_i]), (LAS unsigned*)(lds + (bufoff) + ldsw + _i * 8192), 16, 0, 0); } while (0)
; #define PG8_LDA(dst, b, h) do { _Pragma("unroll") for (int m = 0; m < 4; ++m) _Pragma("unroll") for (int k = 0; k < 2; ++k) dst[m][k] = *(const LAS bf16x8*)(lds + PG8_SA(b, h) + aoff + m * 2048 + k * 1024); } while (0)
; #define PG8_LDB(dst, b, h) do { _Pragma("unroll") for (int n = 0; n < 2; ++n) _Pragma("unroll") for (int k = 0; k < 2; ++k) dst[n][k] = *(const LAS bf16x8*)(lds + PG8_SB(b, h) + boff + n * 2048 + k * 1024); } while (0)
; #define PG8_WAIT_V(n) asm volatile("s_waitcnt vmcnt(" #n ")" ::: "memory")
; #define PG8_WAIT_L(n) asm volatile("s_waitcnt lgkmcnt(" #n ")" ::: "memory")
; #define PG8_BAR __builtin_amdgcn_s_barrier()
; template <class Epi>
; __device__ __forceinline__ void gemm_phase(LAS unsigned char* lds, const Gemm g, const StaticOrder& S_in, const Epi& E, int sw) {
;     ...
;             PG8_LDB(B0, 0, 0); PG8_SCHED; PG8_LDA(At, 0, 0); PG8_STAGE(PG8_SA(1, 1), a1 + hstepA, voffA);
;             PG8_WAIT_L(8); PG8_BAR; PG8_WAIT_L(0); PG8_MMA(0, 0, At, B0); PG8_BAR; PG8_SCHED;
;             PG8_LDB(B1, 0, 1); PG8_STAGE(PG8_SB(0, 0), b2, voffB);
;             PG8_BAR; PG8_WAIT_L(0); PG8_MMA(0, 1, At, B1); PG8_BAR;
;             PG8_LDA(At, 0, 1); PG8_STAGE(PG8_SA(0, 0), a2, voffA);
;             PG8_BAR; PG8_WAIT_L(0); PG8_MMA(1, 0, At, B0); PG8_BAR; PG8_SCHED;
;             PG8_STAGE(PG8_SB(0, 1), b2 + hstepB, voffB);
;             PG8_WAIT_V(6); PG8_BAR; PG8_MMA(1, 1, At, B1); PG8_BAR;
;             PG8_LDB(B0, 1, 0); PG8_SCHED; PG8_LDA(At, 1, 0); PG8_STAGE(PG8_SA(0, 1), a2 + hstepA, voffA);
;             PG8_WAIT_L(8); PG8_BAR; PG8_WAIT_L(0); PG8_MMA(0, 0, At, B0); PG8_BAR; PG8_SCHED;
;             PG8_LDB(B1, 1, 1); PG8_STAGE(PG8_SB(1, 0), b3, voffB);
;             PG8_BAR; PG8_WAIT_L(0); PG8_MMA(0, 1, At, B1); PG8_BAR;
;             PG8_LDA(At, 1, 1); PG8_STAGE(PG8_SA(1, 0), a3, voffA);
;             PG8_BAR; PG8_WAIT_L(0); PG8_MMA(1, 0, At, B0); PG8_BAR; PG8_SCHED;
;             PG8_STAGE(PG8_SB(1, 1), b3 + hstepB, voffB);
;             PG8_WAIT_V(6); PG8_BAR; PG8_MMA(1, 1, At, B1); PG8_BAR;
	s_waitcnt lgkmcnt(0)
	s_setprio 1
	s_waitcnt lgkmcnt(0)
	v_mfma_f32_16x16x32_bf16 v[66:69], v[102:105], v[122:125], v[66:69]
	v_mfma_f32_16x16x32_bf16 v[70:73], v[110:113], v[122:125], v[70:73]
	v_mfma_f32_16x16x32_bf16 v[74:77], v[102:105], v[136:139], v[74:77]
	v_mfma_f32_16x16x32_bf16 v[78:81], v[110:113], v[136:139], v[78:81]
	v_mfma_f32_16x16x32_bf16 v[82:85], v[102:105], v[144:147], v[82:85]
	v_mfma_f32_16x16x32_bf16 v[86:89], v[110:113], v[144:147], v[86:89]
	v_mfma_f32_16x16x32_bf16 v[90:93], v[102:105], v[184:187], v[90:93]
	v_mfma_f32_16x16x32_bf16 v[94:97], v[110:113], v[184:187], v[94:97]
	v_mfma_f32_16x16x32_bf16 v[66:69], v[106:109], v[126:129], v[66:69]
	v_mfma_f32_16x16x32_bf16 v[70:73], v[118:121], v[126:129], v[70:73]
	v_mfma_f32_16x16x32_bf16 v[74:77], v[106:109], v[140:143], v[74:77]
	v_mfma_f32_16x16x32_bf16 v[78:81], v[118:121], v[140:143], v[78:81]
	v_mfma_f32_16x16x32_bf16 v[82:85], v[106:109], v[148:151], v[82:85]
	v_mfma_f32_16x16x32_bf16 v[86:89], v[118:121], v[148:151], v[86:89]
	v_mfma_f32_16x16x32_bf16 v[90:93], v[106:109], v[188:191], v[90:93]
	v_mfma_f32_16x16x32_bf16 v[94:97], v[118:121], v[188:191], v[94:97]
	s_setprio 0
	s_barrier
	s_mov_b32 m0, s49
	v_lshl_add_u64 v[168:169], s[30:31], 0, v[0:1]
	ds_read_b128 v[192:195], v212
	ds_read_b128 v[196:199], v212 offset:1024
	ds_read_b128 v[200:203], v212 offset:2048
	ds_read_b128 v[204:207], v212 offset:3072
	global_load_lds_dwordx4 v[168:169], off
	v_lshl_add_u64 v[172:173], s[30:31], 0, v[134:135]
	s_mov_b32 m0, s17
	s_nop 0
	global_load_lds_dwordx4 v[172:173], off
	s_barrier
	s_waitcnt lgkmcnt(0)
	s_setprio 1
	s_waitcnt lgkmcnt(0)
	v_mfma_f32_16x16x32_bf16 v[50:53], v[200:203], v[144:147], v[50:53]
	v_mfma_f32_16x16x32_bf16 v[38:41], v[192:195], v[136:139], v[38:41]
	v_mfma_f32_16x16x32_bf16 v[42:45], v[200:203], v[136:139], v[42:45]
	v_mfma_f32_16x16x32_bf16 v[136:139], v[204:207], v[148:151], v[50:53]
	v_mfma_f32_16x16x32_bf16 v[50:53], v[192:195], v[184:187], v[54:57]
	v_mfma_f32_16x16x32_bf16 v[34:37], v[200:203], v[122:125], v[34:37]
	v_mfma_f32_16x16x32_bf16 v[38:41], v[196:199], v[140:143], v[38:41]
	v_mfma_f32_16x16x32_bf16 v[42:45], v[204:207], v[140:143], v[42:45]
	v_mfma_f32_16x16x32_bf16 v[46:49], v[192:195], v[144:147], v[46:49]
	v_mfma_f32_16x16x32_bf16 v[140:143], v[196:199], v[188:191], v[50:53]
	v_mfma_f32_16x16x32_bf16 v[50:53], v[200:203], v[184:187], v[58:61]
	v_mfma_f32_16x16x32_bf16 v[114:117], v[192:195], v[122:125], v[114:117]
	v_mfma_f32_16x16x32_bf16 v[34:37], v[204:207], v[126:129], v[34:37]
	v_mfma_f32_16x16x32_bf16 v[46:49], v[196:199], v[148:151], v[46:49]
	v_mfma_f32_16x16x32_bf16 v[144:147], v[204:207], v[188:191], v[50:53]
	v_mfma_f32_16x16x32_bf16 v[208:211], v[196:199], v[126:129], v[114:117]
	s_setprio 0
	s_mov_b32 m0, s23
	v_lshl_add_u64 v[240:241], s[34:35], 0, v[130:131]
	s_barrier
	ds_read_b128 v[50:53], v174 offset:16384
	ds_read_b128 v[54:57], v174 offset:17408
	ds_read_b128 v[58:61], v174 offset:18432
	ds_read_b128 v[114:117], v174 offset:19456
	ds_read_b128 v[122:125], v174 offset:20480
	ds_read_b128 v[126:129], v174 offset:21504
	ds_read_b128 v[148:151], v174 offset:22528
	ds_read_b128 v[184:187], v174 offset:23552
	global_load_lds_dwordx4 v[240:241], off
	v_lshl_add_u64 v[242:243], s[34:35], 0, v[132:133]
	s_mov_b32 m0, s25
	s_nop 0
	global_load_lds_dwordx4 v[242:243], off
	s_barrier
	s_waitcnt lgkmcnt(0)
	s_setprio 1
	s_waitcnt lgkmcnt(0)
	v_mfma_f32_16x16x32_bf16 v[152:155], v[102:105], v[50:53], v[152:155]
	v_mfma_f32_16x16x32_bf16 v[156:159], v[110:113], v[50:53], v[156:159]
	v_mfma_f32_16x16x32_bf16 v[160:163], v[102:105], v[58:61], v[160:163]
	v_mfma_f32_16x16x32_bf16 v[164:167], v[110:113], v[58:61], v[164:167]
	v_mfma_f32_16x16x32_bf16 v[10:13], v[102:105], v[148:151], v[10:13]
	v_mfma_f32_16x16x32_bf16 v[14:17], v[110:113], v[148:151], v[14:17]
	v_mfma_f32_16x16x32_bf16 v[152:155], v[106:109], v[54:57], v[152:155]
	v_mfma_f32_16x16x32_bf16 v[156:159], v[118:121], v[54:57], v[156:159]
	v_mfma_f32_16x16x32_bf16 v[160:163], v[106:109], v[114:117], v[160:163]
	v_mfma_f32_16x16x32_bf16 v[164:167], v[118:121], v[114:117], v[164:167]
	v_mfma_f32_16x16x32_bf16 v[176:179], v[102:105], v[122:125], v[176:179]
	v_mfma_f32_16x16x32_bf16 v[180:183], v[110:113], v[122:125], v[180:183]
	v_mfma_f32_16x16x32_bf16 v[10:13], v[106:109], v[184:187], v[10:13]
	v_mfma_f32_16x16x32_bf16 v[14:17], v[118:121], v[184:187], v[14:17]
	v_mfma_f32_16x16x32_bf16 v[176:179], v[106:109], v[126:129], v[176:179]
	v_mfma_f32_16x16x32_bf16 v[180:183], v[118:121], v[126:129], v[180:183]
	s_setprio 0
	s_barrier
	s_add_u32 s26, s30, 0x10000
	s_addc_u32 s27, s31, 0
	s_mov_b32 m0, s51
	v_lshl_add_u64 v[102:103], s[26:27], 0, v[0:1]
	global_load_lds_dwordx4 v[102:103], off
	v_lshl_add_u64 v[102:103], s[26:27], 0, v[134:135]
	s_mov_b32 m0, s48
	s_nop 0
	global_load_lds_dwordx4 v[102:103], off
	s_waitcnt vmcnt(6)
	s_barrier
	s_setprio 1
	v_mfma_f32_16x16x32_bf16 v[26:29], v[192:195], v[58:61], v[26:29]
	v_mfma_f32_16x16x32_bf16 v[188:191], v[196:199], v[114:117], v[26:29]
	v_mfma_f32_16x16x32_bf16 v[26:29], v[200:203], v[58:61], v[30:33]
	v_mfma_f32_16x16x32_bf16 v[18:21], v[192:195], v[50:53], v[18:21]
	v_mfma_f32_16x16x32_bf16 v[22:25], v[200:203], v[50:53], v[22:25]
	v_mfma_f32_16x16x32_bf16 v[212:215], v[204:207], v[114:117], v[26:29]
	v_mfma_f32_16x16x32_bf16 v[26:29], v[192:195], v[122:125], v[62:65]
	v_mfma_f32_16x16x32_bf16 v[2:5], v[192:195], v[148:151], v[2:5]
	v_mfma_f32_16x16x32_bf16 v[6:9], v[200:203], v[148:151], v[6:9]
	v_mfma_f32_16x16x32_bf16 v[18:21], v[196:199], v[54:57], v[18:21]
	v_mfma_f32_16x16x32_bf16 v[22:25], v[204:207], v[54:57], v[22:25]
	v_mfma_f32_16x16x32_bf16 v[62:65], v[196:199], v[126:129], v[26:29]
	v_mfma_f32_16x16x32_bf16 v[26:29], v[200:203], v[122:125], v[98:101]
	v_mfma_f32_16x16x32_bf16 v[2:5], v[196:199], v[184:187], v[2:5]
	v_mfma_f32_16x16x32_bf16 v[6:9], v[204:207], v[184:187], v[6:9]
	v_mfma_f32_16x16x32_bf16 v[216:219], v[204:207], v[126:129], v[26:29]
	s_setprio 0
	s_barrier
; #define PG8_STAGE(bufoff, gbase, voff) do { _Pragma("unroll") for (int _i = 0; _i < 2; ++_i) \
;         __builtin_amdgcn_global_load_lds((const __attribute__((address_space(1))) unsigned*)((const char*)(gbase) + (voff)[_i]), (LAS unsigned*)(lds + (bufoff) + ldsw + _i * 8192), 16, 0, 0); } while (0)
; #define PG8_LDA(dst, b, h) do { _Pragma("unroll") for (int m = 0; m < 4; ++m) _Pragma("unroll") for (int k = 0; k < 2; ++k) dst[m][k] = *(const LAS bf16x8*)(lds + PG8_SA(b, h) + aoff + m * 2048 + k * 1024); } while (0)
; #define PG8_LDB(dst, b, h) do { _Pragma("unroll") for (int n = 0; n < 2; ++n) _Pragma("unroll") for (int k = 0; k < 2; ++k) dst[n][k] = *(const LAS bf16x8*)(lds + PG8_SB(b, h) + boff + n * 2048 + k * 1024); } while (0)
; #define PG8_MMA(ai, bj, At, Bt) do { __builtin_amdgcn_s_setprio(1); _Pragma("unroll") for (int m = 0; m < 4; ++m) _Pragma("unroll") for (int n = 0; n < 2; ++n) _Pragma("unroll") for (int k = 0; k < 2; ++k) \
;         acc[ai][bj][m][n] = __builtin_amdgcn_mfma_f32_16x16x32_bf16(Bt[n][k], At[m][k], acc[ai][bj][m][n], 0, 0, 0); __builtin_amdgcn_s_setprio(0); } while (0)
; #define PG8_WAIT_V(n) asm volatile("s_waitcnt vmcnt(" #n ")" ::: "memory")
; #define PG8_WAIT_L(n) asm volatile("s_waitcnt lgkmcnt(" #n ")" ::: "memory")
; #define PG8_BAR __builtin_amdgcn_s_barrier()
; #define PG8_SCHED __builtin_amdgcn_sched_barrier(0)
; template <class Epi>
; __device__ __forceinline__ void gemm_phase(LAS unsigned char* lds, const Gemm g, const StaticOrder& S_in, const Epi& E, int sw) {
;     ...
;             PG8_LDB(B0, 1, 0); PG8_SCHED; PG8_LDA(At, 1, 0); PG8_STAGE(PG8_SA(0, 1), a2 + hstepA, voffA);
;             PG8_WAIT_L(8); PG8_BAR; PG8_WAIT_L(0); PG8_MMA(0, 0, At, B0); PG8_BAR; PG8_SCHED;
;             PG8_LDB(B1, 1, 1); PG8_STAGE(PG8_SB(1, 0), b3, voffB);
;             PG8_BAR; PG8_WAIT_L(0); PG8_MMA(0, 1, At, B1); PG8_BAR;
;             PG8_LDA(At, 1, 1); PG8_STAGE(PG8_SA(1, 0), a3, voffA);
;             PG8_BAR; PG8_WAIT_L(0); PG8_MMA(1, 0, At, B0); PG8_BAR; PG8_SCHED;
;             PG8_STAGE(PG8_SB(1, 1), b3 + hstepB, voffB);
;             PG8_WAIT_V(6); PG8_BAR; PG8_MMA(1, 1, At, B1); PG8_BAR;
	s_nop 2
	ds_read_b128 v[26:29], v220
	ds_read_b128 v[30:33], v220 offset:1024
	ds_read_b128 v[148:151], v220 offset:2048
	ds_read_b128 v[184:187], v220 offset:3072
	s_add_u32 s26, s34, 0x80000
	s_addc_u32 s27, s35, 0
	s_mov_b32 m0, s43
	v_lshl_add_u64 v[58:59], s[26:27], 0, v[130:131]
	ds_read_b128 v[50:53], v174 offset:32768
	ds_read_b128 v[54:57], v174 offset:33792
	ds_read_b128 v[98:101], v174 offset:34816
	ds_read_b128 v[102:105], v174 offset:35840
	ds_read_b128 v[110:113], v174 offset:36864
	ds_read_b128 v[192:195], v174 offset:37888
	ds_read_b128 v[196:199], v174 offset:38912
	ds_read_b128 v[200:203], v174 offset:39936
	global_load_lds_dwordx4 v[58:59], off
	v_lshl_add_u64 v[58:59], s[26:27], 0, v[132:133]
	s_mov_b32 m0, s44
	s_nop 0
	global_load_lds_dwordx4 v[58:59], off
	s_waitcnt lgkmcnt(8)
	s_barrier
	s_waitcnt lgkmcnt(0)
	s_setprio 1
	s_waitcnt lgkmcnt(0)
	v_mfma_f32_16x16x32_bf16 v[58:61], v[26:29], v[50:53], v[66:69]
	v_mfma_f32_16x16x32_bf16 v[204:207], v[30:33], v[54:57], v[58:61]
	v_mfma_f32_16x16x32_bf16 v[58:61], v[148:151], v[50:53], v[70:73]
	v_mfma_f32_16x16x32_bf16 v[220:223], v[184:187], v[54:57], v[58:61]
	v_mfma_f32_16x16x32_bf16 v[58:61], v[26:29], v[98:101], v[74:77]
	v_mfma_f32_16x16x32_bf16 v[224:227], v[30:33], v[102:105], v[58:61]
	v_mfma_f32_16x16x32_bf16 v[58:61], v[148:151], v[98:101], v[78:81]
	v_mfma_f32_16x16x32_bf16 v[126:129], v[184:187], v[102:105], v[58:61]
	v_mfma_f32_16x16x32_bf16 v[58:61], v[26:29], v[110:113], v[82:85]
	v_mfma_f32_16x16x32_bf16 v[122:125], v[30:33], v[192:195], v[58:61]
	v_mfma_f32_16x16x32_bf16 v[58:61], v[148:151], v[110:113], v[86:89]
	v_mfma_f32_16x16x32_bf16 v[118:121], v[184:187], v[192:195], v[58:61]
	v_mfma_f32_16x16x32_bf16 v[58:61], v[26:29], v[196:199], v[90:93]
	v_mfma_f32_16x16x32_bf16 v[114:117], v[30:33], v[200:203], v[58:61]
	v_mfma_f32_16x16x32_bf16 v[58:61], v[148:151], v[196:199], v[94:97]
	v_mfma_f32_16x16x32_bf16 v[106:109], v[184:187], v[200:203], v[58:61]
	s_setprio 0
	s_barrier
	s_mov_b32 m0, s53
	s_nop 3
	v_lshl_add_u64 v[58:59], v[168:169], 0, s[86:87]
	ds_read_b128 v[78:81], v232
	ds_read_b128 v[82:85], v232 offset:1024
	ds_read_b128 v[228:231], v232 offset:2048
	ds_read_b128 v[232:235], v232 offset:3072
	global_load_lds_dwordx4 v[58:59], off
	v_lshl_add_u64 v[58:59], v[172:173], 0, s[86:87]
	s_mov_b32 m0, s52
	s_nop 0
	global_load_lds_dwordx4 v[58:59], off
	s_barrier
	s_waitcnt lgkmcnt(0)
	s_setprio 1
	s_waitcnt lgkmcnt(0)
	v_mfma_f32_16x16x32_bf16 v[34:37], v[228:231], v[50:53], v[34:37]
	v_mfma_f32_16x16x32_bf16 v[66:69], v[232:235], v[54:57], v[34:37]
	v_mfma_f32_16x16x32_bf16 v[34:37], v[78:81], v[98:101], v[38:41]
	v_mfma_f32_16x16x32_bf16 v[58:61], v[78:81], v[50:53], v[208:211]
	v_mfma_f32_16x16x32_bf16 v[50:53], v[82:85], v[102:105], v[34:37]
	v_mfma_f32_16x16x32_bf16 v[34:37], v[228:231], v[98:101], v[42:45]
	v_mfma_f32_16x16x32_bf16 v[58:61], v[82:85], v[54:57], v[58:61]
	v_mfma_f32_16x16x32_bf16 v[54:57], v[232:235], v[102:105], v[34:37]
	v_mfma_f32_16x16x32_bf16 v[34:37], v[78:81], v[110:113], v[46:49]
	v_mfma_f32_16x16x32_bf16 v[42:45], v[82:85], v[192:195], v[34:37]
	v_mfma_f32_16x16x32_bf16 v[34:37], v[228:231], v[110:113], v[136:139]
	v_mfma_f32_16x16x32_bf16 v[46:49], v[232:235], v[192:195], v[34:37]
	v_mfma_f32_16x16x32_bf16 v[34:37], v[78:81], v[196:199], v[140:143]
	v_mfma_f32_16x16x32_bf16 v[38:41], v[228:231], v[196:199], v[144:147]
	v_mfma_f32_16x16x32_bf16 v[34:37], v[82:85], v[200:203], v[34:37]
	v_mfma_f32_16x16x32_bf16 v[38:41], v[232:235], v[200:203], v[38:41]
	s_setprio 0
	s_mov_b32 m0, s45
	v_lshl_add_u64 v[70:71], v[240:241], 0, s[86:87]
	s_barrier
	ds_read_b128 v[136:139], v174 offset:49152
	ds_read_b128 v[140:143], v174 offset:50176
	ds_read_b128 v[144:147], v174 offset:51200
	ds_read_b128 v[192:195], v174 offset:52224
	ds_read_b128 v[196:199], v174 offset:53248
	ds_read_b128 v[200:203], v174 offset:54272
	ds_read_b128 v[208:211], v174 offset:55296
	ds_read_b128 v[236:239], v174 offset:56320
	global_load_lds_dwordx4 v[70:71], off
	v_lshl_add_u64 v[70:71], v[242:243], 0, s[86:87]
	s_mov_b32 m0, s46
	s_nop 0
	global_load_lds_dwordx4 v[70:71], off
	s_barrier
	s_waitcnt lgkmcnt(0)
	s_setprio 1
	s_waitcnt lgkmcnt(0)
	v_mfma_f32_16x16x32_bf16 v[70:73], v[26:29], v[136:139], v[152:155]
	v_mfma_f32_16x16x32_bf16 v[110:113], v[30:33], v[140:143], v[70:73]
	v_mfma_f32_16x16x32_bf16 v[70:73], v[148:151], v[136:139], v[156:159]
	v_mfma_f32_16x16x32_bf16 v[102:105], v[184:187], v[140:143], v[70:73]
	v_mfma_f32_16x16x32_bf16 v[70:73], v[26:29], v[144:147], v[160:163]
	v_mfma_f32_16x16x32_bf16 v[98:101], v[30:33], v[192:195], v[70:73]
	v_mfma_f32_16x16x32_bf16 v[70:73], v[148:151], v[144:147], v[164:167]
	v_mfma_f32_16x16x32_bf16 v[94:97], v[184:187], v[192:195], v[70:73]
	v_mfma_f32_16x16x32_bf16 v[70:73], v[26:29], v[196:199], v[176:179]
	v_mfma_f32_16x16x32_bf16 v[10:13], v[26:29], v[208:211], v[10:13]
	v_mfma_f32_16x16x32_bf16 v[90:93], v[30:33], v[200:203], v[70:73]
	v_mfma_f32_16x16x32_bf16 v[70:73], v[148:151], v[196:199], v[180:183]
	v_mfma_f32_16x16x32_bf16 v[74:77], v[30:33], v[236:239], v[10:13]
	v_mfma_f32_16x16x32_bf16 v[10:13], v[148:151], v[208:211], v[14:17]
	v_mfma_f32_16x16x32_bf16 v[86:89], v[184:187], v[200:203], v[70:73]
	v_mfma_f32_16x16x32_bf16 v[70:73], v[184:187], v[236:239], v[10:13]
	s_setprio 0
	s_barrier
	s_add_u32 s26, s30, 0x10080
	s_addc_u32 s27, s31, 0
	s_mov_b32 m0, s29
	s_nop 0
	v_lshl_add_u64 v[10:11], s[26:27], 0, v[0:1]
	global_load_lds_dwordx4 v[10:11], off
	v_lshl_add_u64 v[10:11], s[26:27], 0, v[134:135]
	s_mov_b32 m0, s28
	s_nop 0
	global_load_lds_dwordx4 v[10:11], off
	s_waitcnt vmcnt(6)
	s_barrier
; #define LAS __attribute__((address_space(3)))
; __device__ __forceinline__ unsigned cvt_pk_bf16(float lo, float hi) { unsigned r; asm volatile("v_cvt_pk_bf16_f32 %0, %1, %2" : "=v"(r) : "v"(lo), "v"(hi)); return r; }
; __device__ __forceinline__ int ltid(int sw) { unsigned z = 0u; asm volatile("" : "+s"(sw), "+s"(z)); int t = sw * 64 + (int)__builtin_amdgcn_mbcnt_hi(~0u, __builtin_amdgcn_mbcnt_lo(~0u, z)); asm volatile("" : "+v"(t)); return t; }
;     __device__ __forceinline__ void operator()(AccMut acc, const Unit& u, int sw) const {
;         const int tid_ = ltid(sw), lane_ = tid_ & 63, wr = sw >> 2, wc = sw & 3, fr = lane_ & 15, fq = lane_ >> 4;
;         const int row0 = u.pm * BM + wr * 64 + fr, c0 = u.pn * 128 + wc * 32 + 8 * fq;
;         u32x4 xnext = *(const u32x4*)(XC + (size_t)row0 * E + c0);
;         { f32x4 ns[2];
; #pragma unroll
;           for (int n = 0; n < 2; ++n) ns[n] = *(const LAS f32x4*)(nsp + c0 + 4 * n);
; #pragma unroll
;           for (int ai = 0; ai < 2; ++ai)
; #pragma unroll
;             for (int m = 0; m < 4; ++m) {
; #pragma unroll
;                 for (int n = 0; n < 2; ++n)
; #pragma unroll
;                     for (int jp = 0; jp < 2; ++jp) {
;                         const f32x2 z = (f32x2){acc[ai][0][m][n][2 * jp], acc[ai][0][m][n][2 * jp + 1]} * (-1.44269504f);
;                         f32x2 e; e.x = __builtin_amdgcn_exp2f(z.x); e.y = __builtin_amdgcn_exp2f(z.y); e = e + 1.0f;
;                         f32x2 r; r.x = __builtin_amdgcn_rcpf(e.x); r.y = __builtin_amdgcn_rcpf(e.y);
;                         r = r * (f32x2){ns[n][2 * jp], ns[n][2 * jp + 1]};
;                         acc[ai][0][m][n][2 * jp] = r.x; acc[ai][0][m][n][2 * jp + 1] = r.y; }
;                 const f32x4 l0 = acc[ai][0][m][0], l1 = acc[ai][0][m][1];
;                 u32x4 w; w.x = cvt_pk_bf16(l0[0], l0[1]); w.y = cvt_pk_bf16(l0[2], l0[3]); w.z = cvt_pk_bf16(l1[0], l1[1]); w.w = cvt_pk_bf16(l1[2], l1[3]);
;                 *(u32x4*)(LA + (size_t)(row0 + ai * HALF + m * 16) * E + c0) = w; } }
; __device__ __forceinline__ void scan1_phase(const bf16_t* LA, const bf16_t* BT, int sw, View vw) {
;     ...
;         *(f32x4*)(CP + (size_t)bq * E + 4 * quad) = (f32x4){S[0], S[1], S[2], S[3]};
;         *(f32x4*)(CH + (size_t)bq * E + 4 * quad) = (f32x4){Hc[0], Hc[1], Hc[2], Hc[3]};
	s_setprio 1
	v_mfma_f32_16x16x32_bf16 v[10:13], v[78:81], v[136:139], v[18:21]
	v_mfma_f32_16x16x32_bf16 v[26:29], v[82:85], v[140:143], v[10:13]
	v_mfma_f32_16x16x32_bf16 v[10:13], v[228:231], v[136:139], v[22:25]
	v_mfma_f32_16x16x32_bf16 v[30:33], v[232:235], v[140:143], v[10:13]
	v_mfma_f32_16x16x32_bf16 v[10:13], v[78:81], v[144:147], v[188:191]
	v_mfma_f32_16x16x32_bf16 v[18:21], v[82:85], v[192:195], v[10:13]
	v_mfma_f32_16x16x32_bf16 v[10:13], v[228:231], v[144:147], v[212:215]
	v_mfma_f32_16x16x32_bf16 v[22:25], v[232:235], v[192:195], v[10:13]
	v_mfma_f32_16x16x32_bf16 v[10:13], v[78:81], v[196:199], v[62:65]
	v_mfma_f32_16x16x32_bf16 v[14:17], v[228:231], v[196:199], v[216:219]
	v_mfma_f32_16x16x32_bf16 v[2:5], v[78:81], v[208:211], v[2:5]
	v_mfma_f32_16x16x32_bf16 v[6:9], v[228:231], v[208:211], v[6:9]
	v_mfma_f32_16x16x32_bf16 v[10:13], v[82:85], v[200:203], v[10:13]
	v_mfma_f32_16x16x32_bf16 v[14:17], v[232:235], v[200:203], v[14:17]
	v_mfma_f32_16x16x32_bf16 v[2:5], v[82:85], v[236:239], v[2:5]
	v_mfma_f32_16x16x32_bf16 v[6:9], v[232:235], v[236:239], v[6:9]
	s_setprio 0
	s_barrier
	s_load_dwordx2 s[26:27], s[92:93], 0xa8
	v_mbcnt_lo_u32_b32 v216, -1, 0
	v_mbcnt_hi_u32_b32 v216, -1, v216
	v_mov_b32_e32 v237, 0x20000
	ds_read_b32 v239, v237 offset:48
	ds_read_b32 v237, v237 offset:40
	s_lshl_b32 s13, s24, 8
	s_add_i32 s13, s13, s3
	s_lshl_b32 s17, s22, 7
	s_or_b32 s17, s17, s85
	v_and_b32_e32 v217, 15, v216
	v_lshrrev_b32_e32 v218, 1, v216
	v_and_b32_e32 v218, 24, v218
	v_lshl_or_b32 v217, v217, 2, s13
	v_or_b32_e32 v219, s17, v218
	v_lshlrev_b32_e32 v168, 12, v217
	v_lshlrev_b32_e32 v240, 2, v219
	v_lshl_add_u32 v168, v219, 1, v168
	v_add_u32_e32 v240, 0x24400, v240
	global_load_dwordx4 v[136:139], v168, s[6:7]
	ds_read_b128 v[228:231], v240
	ds_read_b128 v[232:235], v240 offset:16
	v_add_u32_e32 v169, 0x1000, v168
	global_load_dwordx4 v[140:143], v169, s[6:7]
	v_add_u32_e32 v172, 0x2000, v168
	global_load_dwordx4 v[144:147], v172, s[6:7]
	v_add_u32_e32 v173, 0x3000, v168
	global_load_dwordx4 v[148:151], v173, s[6:7]
	v_add_u32_e32 v176, 0x80000, v168
	global_load_dwordx4 v[152:155], v176, s[6:7]
	v_add_u32_e32 v177, 0x81000, v168
	global_load_dwordx4 v[156:159], v177, s[6:7]
	v_add_u32_e32 v178, 0x82000, v168
	global_load_dwordx4 v[160:163], v178, s[6:7]
	v_add_u32_e32 v179, 0x83000, v168
	global_load_dwordx4 v[164:167], v179, s[6:7]
	s_lshl_b32 s17, s24, 2
	s_lshr_b32 s13, s3, 6
	s_add_i32 s17, s17, s13
	s_mov_b32 s24, 0xbe888889
	s_mov_b32 s22, 0xbfaaaaab
	s_mov_b32 s13, 0xbe000000
	v_mov_b32_e32 v236, 0xbf2aaaab
	v_mov_b32_e32 v238, 0
	s_waitcnt lgkmcnt(0)
	v_cmp_ne_u32_e32 vcc, 0, v239
	v_lshlrev_b32_e32 v237, 6, v237
	s_nop 0
	v_cndmask_b32_e32 v237, 0, v237, vcc
	v_add_u32_e32 v237, s17, v237
	v_lshl_add_u32 v237, v237, 11, v219
	v_lshlrev_b32_e32 v237, 2, v237
	v_add_u32_e32 v239, 0x800000, v237
	v_pk_mul_f32 v[180:181], v[204:205], s[74:75] op_sel_hi:[1,0]
	v_pk_mul_f32 v[182:183], v[206:207], s[74:75] op_sel_hi:[1,0]
	v_pk_mul_f32 v[184:185], v[220:221], s[74:75] op_sel_hi:[1,0]
	v_pk_mul_f32 v[186:187], v[222:223], s[74:75] op_sel_hi:[1,0]
	v_exp_f32_e32 v180, v180
	v_exp_f32_e32 v181, v181
	v_exp_f32_e32 v182, v182
	v_exp_f32_e32 v183, v183
	v_exp_f32_e32 v184, v184
	v_exp_f32_e32 v185, v185
	v_exp_f32_e32 v186, v186
	v_exp_f32_e32 v187, v187
	v_pk_add_f32 v[180:181], v[180:181], 1.0 op_sel_hi:[1,0]
	v_pk_add_f32 v[182:183], v[182:183], 1.0 op_sel_hi:[1,0]
	v_pk_add_f32 v[184:185], v[184:185], 1.0 op_sel_hi:[1,0]
	v_pk_add_f32 v[186:187], v[186:187], 1.0 op_sel_hi:[1,0]
	v_rcp_f32_e32 v180, v180
	v_rcp_f32_e32 v181, v181
	v_rcp_f32_e32 v182, v182
	v_rcp_f32_e32 v183, v183
	v_rcp_f32_e32 v184, v184
	v_rcp_f32_e32 v185, v185
	v_rcp_f32_e32 v186, v186
	v_rcp_f32_e32 v187, v187
	v_pk_mul_f32 v[204:205], v[180:181], v[228:229]
	v_pk_mul_f32 v[206:207], v[182:183], v[230:231]
	v_pk_mul_f32 v[220:221], v[184:185], v[232:233]
	v_pk_mul_f32 v[222:223], v[186:187], v[234:235]
	v_min3_f32 v238, v238, v204, v205
	v_min3_f32 v238, v238, v206, v207
	v_min3_f32 v238, v238, v220, v221
	v_min3_f32 v238, v238, v222, v223
	v_cvt_pk_bf16_f32 v208, v204, v205
	v_cvt_pk_bf16_f32 v209, v206, v207
	v_cvt_pk_bf16_f32 v210, v220, v221
	v_cvt_pk_bf16_f32 v211, v222, v223
	global_store_dwordx4 v168, v[208:211], s[8:9]
	v_pk_mul_f32 v[180:181], v[224:225], s[74:75] op_sel_hi:[1,0]
	v_pk_mul_f32 v[182:183], v[226:227], s[74:75] op_sel_hi:[1,0]
	v_pk_mul_f32 v[184:185], v[126:127], s[74:75] op_sel_hi:[1,0]
	v_pk_mul_f32 v[186:187], v[128:129], s[74:75] op_sel_hi:[1,0]
	v_exp_f32_e32 v180, v180
	v_exp_f32_e32 v181, v181
	v_exp_f32_e32 v182, v182
	v_exp_f32_e32 v183, v183
	v_exp_f32_e32 v184, v184
	v_exp_f32_e32 v185, v185
	v_exp_f32_e32 v186, v186
	v_exp_f32_e32 v187, v187
	v_pk_add_f32 v[180:181], v[180:181], 1.0 op_sel_hi:[1,0]
	v_pk_add_f32 v[182:183], v[182:183], 1.0 op_sel_hi:[1,0]
	v_pk_add_f32 v[184:185], v[184:185], 1.0 op_sel_hi:[1,0]
	v_pk_add_f32 v[186:187], v[186:187], 1.0 op_sel_hi:[1,0]
	v_rcp_f32_e32 v180, v180
	v_rcp_f32_e32 v181, v181
	v_rcp_f32_e32 v182, v182
	v_rcp_f32_e32 v183, v183
	v_rcp_f32_e32 v184, v184
	v_rcp_f32_e32 v185, v185
	v_rcp_f32_e32 v186, v186
	v_rcp_f32_e32 v187, v187
	v_pk_mul_f32 v[224:225], v[180:181], v[228:229]
	v_pk_mul_f32 v[226:227], v[182:183], v[230:231]
	v_pk_mul_f32 v[126:127], v[184:185], v[232:233]
	v_pk_mul_f32 v[128:129], v[186:187], v[234:235]
	v_min3_f32 v238, v238, v224, v225
	v_min3_f32 v238, v238, v226, v227
	v_min3_f32 v238, v238, v126, v127
	v_min3_f32 v238, v238, v128, v129
	v_cvt_pk_bf16_f32 v212, v224, v225
	v_cvt_pk_bf16_f32 v213, v226, v227
	v_cvt_pk_bf16_f32 v214, v126, v127
; __device__ __forceinline__ unsigned cvt_pk_bf16(float lo, float hi) { unsigned r; asm volatile("v_cvt_pk_bf16_f32 %0, %1, %2" : "=v"(r) : "v"(lo), "v"(hi)); return r; }
;     __device__ __forceinline__ void operator()(AccMut acc, const Unit& u, int sw) const {
;     ...
;             for (int m = 0; m < 4; ++m) {
; #pragma unroll
;                 for (int n = 0; n < 2; ++n)
; #pragma unroll
;                     for (int jp = 0; jp < 2; ++jp) {
;                         const f32x2 z = (f32x2){acc[ai][0][m][n][2 * jp], acc[ai][0][m][n][2 * jp + 1]} * (-1.44269504f);
;                         f32x2 e; e.x = __builtin_amdgcn_exp2f(z.x); e.y = __builtin_amdgcn_exp2f(z.y); e = e + 1.0f;
;                         f32x2 r; r.x = __builtin_amdgcn_rcpf(e.x); r.y = __builtin_amdgcn_rcpf(e.y);
;                         r = r * (f32x2){ns[n][2 * jp], ns[n][2 * jp + 1]};
;                         acc[ai][0][m][n][2 * jp] = r.x; acc[ai][0][m][n][2 * jp + 1] = r.y; }
;                 const f32x4 l0 = acc[ai][0][m][0], l1 = acc[ai][0][m][1];
;                 u32x4 w; w.x = cvt_pk_bf16(l0[0], l0[1]); w.y = cvt_pk_bf16(l0[2], l0[3]); w.z = cvt_pk_bf16(l1[0], l1[1]); w.w = cvt_pk_bf16(l1[2], l1[3]);
;                 *(u32x4*)(LA + (size_t)(row0 + ai * HALF + m * 16) * E + c0) = w; } }
	v_cvt_pk_bf16_f32 v215, v128, v129
	global_store_dwordx4 v169, v[212:215], s[8:9]
	v_pk_mul_f32 v[180:181], v[122:123], s[74:75] op_sel_hi:[1,0]
	v_pk_mul_f32 v[182:183], v[124:125], s[74:75] op_sel_hi:[1,0]
	v_pk_mul_f32 v[184:185], v[118:119], s[74:75] op_sel_hi:[1,0]
	v_pk_mul_f32 v[186:187], v[120:121], s[74:75] op_sel_hi:[1,0]
	v_exp_f32_e32 v180, v180
	v_exp_f32_e32 v181, v181
	v_exp_f32_e32 v182, v182
	v_exp_f32_e32 v183, v183
	v_exp_f32_e32 v184, v184
	v_exp_f32_e32 v185, v185
	v_exp_f32_e32 v186, v186
	v_exp_f32_e32 v187, v187
	v_pk_add_f32 v[180:181], v[180:181], 1.0 op_sel_hi:[1,0]
	v_pk_add_f32 v[182:183], v[182:183], 1.0 op_sel_hi:[1,0]
	v_pk_add_f32 v[184:185], v[184:185], 1.0 op_sel_hi:[1,0]
	v_pk_add_f32 v[186:187], v[186:187], 1.0 op_sel_hi:[1,0]
	v_rcp_f32_e32 v180, v180
	v_rcp_f32_e32 v181, v181
	v_rcp_f32_e32 v182, v182
	v_rcp_f32_e32 v183, v183
	v_rcp_f32_e32 v184, v184
	v_rcp_f32_e32 v185, v185
	v_rcp_f32_e32 v186, v186
	v_rcp_f32_e32 v187, v187
	v_pk_mul_f32 v[122:123], v[180:181], v[228:229]
	v_pk_mul_f32 v[124:125], v[182:183], v[230:231]
	v_pk_mul_f32 v[118:119], v[184:185], v[232:233]
	v_pk_mul_f32 v[120:121], v[186:187], v[234:235]
	v_min3_f32 v238, v238, v122, v123
	v_min3_f32 v238, v238, v124, v125
	v_min3_f32 v238, v238, v118, v119
	v_min3_f32 v238, v238, v120, v121
	v_cvt_pk_bf16_f32 v208, v122, v123
	v_cvt_pk_bf16_f32 v209, v124, v125
	v_cvt_pk_bf16_f32 v210, v118, v119
	v_cvt_pk_bf16_f32 v211, v120, v121
	global_store_dwordx4 v172, v[208:211], s[8:9]
	v_pk_mul_f32 v[180:181], v[114:115], s[74:75] op_sel_hi:[1,0]
	v_pk_mul_f32 v[182:183], v[116:117], s[74:75] op_sel_hi:[1,0]
	v_pk_mul_f32 v[184:185], v[106:107], s[74:75] op_sel_hi:[1,0]
	v_pk_mul_f32 v[186:187], v[108:109], s[74:75] op_sel_hi:[1,0]
	v_exp_f32_e32 v180, v180
	v_exp_f32_e32 v181, v181
	v_exp_f32_e32 v182, v182
	v_exp_f32_e32 v183, v183
	v_exp_f32_e32 v184, v184
	v_exp_f32_e32 v185, v185
	v_exp_f32_e32 v186, v186
	v_exp_f32_e32 v187, v187
	v_pk_add_f32 v[180:181], v[180:181], 1.0 op_sel_hi:[1,0]
	v_pk_add_f32 v[182:183], v[182:183], 1.0 op_sel_hi:[1,0]
	v_pk_add_f32 v[184:185], v[184:185], 1.0 op_sel_hi:[1,0]
	v_pk_add_f32 v[186:187], v[186:187], 1.0 op_sel_hi:[1,0]
	v_rcp_f32_e32 v180, v180
	v_rcp_f32_e32 v181, v181
	v_rcp_f32_e32 v182, v182
	v_rcp_f32_e32 v183, v183
	v_rcp_f32_e32 v184, v184
	v_rcp_f32_e32 v185, v185
	v_rcp_f32_e32 v186, v186
	v_rcp_f32_e32 v187, v187
	v_pk_mul_f32 v[114:115], v[180:181], v[228:229]
	v_pk_mul_f32 v[116:117], v[182:183], v[230:231]
	v_pk_mul_f32 v[106:107], v[184:185], v[232:233]
	v_pk_mul_f32 v[108:109], v[186:187], v[234:235]
	v_min3_f32 v238, v238, v114, v115
	v_min3_f32 v238, v238, v116, v117
	v_min3_f32 v238, v238, v106, v107
	v_min3_f32 v238, v238, v108, v109
	v_cvt_pk_bf16_f32 v212, v114, v115
	v_cvt_pk_bf16_f32 v213, v116, v117
	v_cvt_pk_bf16_f32 v214, v106, v107
	v_cvt_pk_bf16_f32 v215, v108, v109
	global_store_dwordx4 v173, v[212:215], s[8:9]
	v_pk_mul_f32 v[180:181], v[110:111], s[74:75] op_sel_hi:[1,0]
	v_pk_mul_f32 v[182:183], v[112:113], s[74:75] op_sel_hi:[1,0]
	v_pk_mul_f32 v[184:185], v[102:103], s[74:75] op_sel_hi:[1,0]
	v_pk_mul_f32 v[186:187], v[104:105], s[74:75] op_sel_hi:[1,0]
	v_exp_f32_e32 v180, v180
	v_exp_f32_e32 v181, v181
	v_exp_f32_e32 v182, v182
	v_exp_f32_e32 v183, v183
	v_exp_f32_e32 v184, v184
	v_exp_f32_e32 v185, v185
	v_exp_f32_e32 v186, v186
	v_exp_f32_e32 v187, v187
	v_pk_add_f32 v[180:181], v[180:181], 1.0 op_sel_hi:[1,0]
	v_pk_add_f32 v[182:183], v[182:183], 1.0 op_sel_hi:[1,0]
	v_pk_add_f32 v[184:185], v[184:185], 1.0 op_sel_hi:[1,0]
	v_pk_add_f32 v[186:187], v[186:187], 1.0 op_sel_hi:[1,0]
	v_rcp_f32_e32 v180, v180
	v_rcp_f32_e32 v181, v181
	v_rcp_f32_e32 v182, v182
	v_rcp_f32_e32 v183, v183
	v_rcp_f32_e32 v184, v184
	v_rcp_f32_e32 v185, v185
	v_rcp_f32_e32 v186, v186
	v_rcp_f32_e32 v187, v187
	v_pk_mul_f32 v[110:111], v[180:181], v[228:229]
	v_pk_mul_f32 v[112:113], v[182:183], v[230:231]
	v_pk_mul_f32 v[102:103], v[184:185], v[232:233]
	v_pk_mul_f32 v[104:105], v[186:187], v[234:235]
	v_min3_f32 v238, v238, v110, v111
	v_min3_f32 v238, v238, v112, v113
	v_min3_f32 v238, v238, v102, v103
	v_min3_f32 v238, v238, v104, v105
	v_cvt_pk_bf16_f32 v208, v110, v111
	v_cvt_pk_bf16_f32 v209, v112, v113
	v_cvt_pk_bf16_f32 v210, v102, v103
	v_cvt_pk_bf16_f32 v211, v104, v105
	global_store_dwordx4 v176, v[208:211], s[8:9]
	v_pk_mul_f32 v[180:181], v[98:99], s[74:75] op_sel_hi:[1,0]
	v_pk_mul_f32 v[182:183], v[100:101], s[74:75] op_sel_hi:[1,0]
	v_pk_mul_f32 v[184:185], v[94:95], s[74:75] op_sel_hi:[1,0]
	v_pk_mul_f32 v[186:187], v[96:97], s[74:75] op_sel_hi:[1,0]
	v_exp_f32_e32 v180, v180
	v_exp_f32_e32 v181, v181
	v_exp_f32_e32 v182, v182
	v_exp_f32_e32 v183, v183
	v_exp_f32_e32 v184, v184
	v_exp_f32_e32 v185, v185
	v_exp_f32_e32 v186, v186
	v_exp_f32_e32 v187, v187
	v_pk_add_f32 v[180:181], v[180:181], 1.0 op_sel_hi:[1,0]
	v_pk_add_f32 v[182:183], v[182:183], 1.0 op_sel_hi:[1,0]
	v_pk_add_f32 v[184:185], v[184:185], 1.0 op_sel_hi:[1,0]
	v_pk_add_f32 v[186:187], v[186:187], 1.0 op_sel_hi:[1,0]
	v_rcp_f32_e32 v180, v180
	v_rcp_f32_e32 v181, v181
	v_rcp_f32_e32 v182, v182
	v_rcp_f32_e32 v183, v183
	v_rcp_f32_e32 v184, v184
	v_rcp_f32_e32 v185, v185
	v_rcp_f32_e32 v186, v186
	v_rcp_f32_e32 v187, v187
	v_pk_mul_f32 v[98:99], v[180:181], v[228:229]
	v_pk_mul_f32 v[100:101], v[182:183], v[230:231]
	v_pk_mul_f32 v[94:95], v[184:185], v[232:233]
	v_pk_mul_f32 v[96:97], v[186:187], v[234:235]
	v_min3_f32 v238, v238, v98, v99
	v_min3_f32 v238, v238, v100, v101
	v_min3_f32 v238, v238, v94, v95
	v_min3_f32 v238, v238, v96, v97
	v_cvt_pk_bf16_f32 v212, v98, v99
	v_cvt_pk_bf16_f32 v213, v100, v101
;     __device__ __forceinline__ void operator()(AccMut acc, const Unit& u, int sw) const {
;     ...
;                         const f32x2 z = (f32x2){acc[ai][0][m][n][2 * jp], acc[ai][0][m][n][2 * jp + 1]} * (-1.44269504f);
;                         f32x2 e; e.x = __builtin_amdgcn_exp2f(z.x); e.y = __builtin_amdgcn_exp2f(z.y); e = e + 1.0f;
;                         f32x2 r; r.x = __builtin_amdgcn_rcpf(e.x); r.y = __builtin_amdgcn_rcpf(e.y);
;                         r = r * (f32x2){ns[n][2 * jp], ns[n][2 * jp + 1]};
;                         acc[ai][0][m][n][2 * jp] = r.x; acc[ai][0][m][n][2 * jp + 1] = r.y; }
;                 const f32x4 l0 = acc[ai][0][m][0], l1 = acc[ai][0][m][1];
;                 u32x4 w; w.x = cvt_pk_bf16(l0[0], l0[1]); w.y = cvt_pk_bf16(l0[2], l0[3]); w.z = cvt_pk_bf16(l1[0], l1[1]); w.w = cvt_pk_bf16(l1[2], l1[3]);
;                 *(u32x4*)(LA + (size_t)(row0 + ai * HALF + m * 16) * E + c0) = w; } }
; #pragma unroll
;         for (int ai = 0; ai < 2; ++ai)
; #pragma unroll
;             for (int m = 0; m < 4; ++m) { const size_t off = (size_t)(row0 + ai * HALF + m * 16) * E + c0;
;                 const u32x4 xw = xnext;
;                 if (ai * 4 + m < 7) { const int ai2 = (ai * 4 + m + 1) >> 2, m2 = (ai * 4 + m + 1) & 3; xnext = *(const u32x4*)(XC + (size_t)(row0 + ai2 * HALF + m2 * 16) * E + c0); }
;                 float bt[8];
; #pragma unroll
;                 for (int n = 0; n < 2; ++n)
; #pragma unroll
;                     for (int jp = 0; jp < 2; ++jp) {
;                         const f32x2 z = (f32x2){acc[ai][1][m][n][2 * jp], acc[ai][1][m][n][2 * jp + 1]} * (-1.44269504f);
;                         f32x2 e; e.x = __builtin_amdgcn_exp2f(z.x); e.y = __builtin_amdgcn_exp2f(z.y); e = e + 1.0f;
;                         f32x2 ig; ig.x = __builtin_amdgcn_rcpf(e.x); ig.y = __builtin_amdgcn_rcpf(e.y);
;                         const f32x2 x2 = (f32x2){acc[ai][0][m][n][2 * jp], acc[ai][0][m][n][2 * jp + 1]} * 2.0f;
;                         f32x2 ser = x2 * (1.0f / 120.0f) + (1.0f / 24.0f); ser = ser * x2 + (1.0f / 6.0f); ser = ser * x2 + 0.5f; ser = ser * x2 + 1.0f; ser = ser * (-x2);
;                         f32x2 em = ser;
;                         if (__builtin_expect(__builtin_amdgcn_ballot_w64(x2.x <= -0.25f || x2.y <= -0.25f) != 0ull, 0)) {
	v_cvt_pk_bf16_f32 v214, v94, v95
	v_cvt_pk_bf16_f32 v215, v96, v97
	global_store_dwordx4 v177, v[212:215], s[8:9]
	v_pk_mul_f32 v[180:181], v[90:91], s[74:75] op_sel_hi:[1,0]
	v_pk_mul_f32 v[182:183], v[92:93], s[74:75] op_sel_hi:[1,0]
	v_pk_mul_f32 v[184:185], v[86:87], s[74:75] op_sel_hi:[1,0]
	v_pk_mul_f32 v[186:187], v[88:89], s[74:75] op_sel_hi:[1,0]
	v_exp_f32_e32 v180, v180
	v_exp_f32_e32 v181, v181
	v_exp_f32_e32 v182, v182
	v_exp_f32_e32 v183, v183
	v_exp_f32_e32 v184, v184
	v_exp_f32_e32 v185, v185
	v_exp_f32_e32 v186, v186
	v_exp_f32_e32 v187, v187
	v_pk_add_f32 v[180:181], v[180:181], 1.0 op_sel_hi:[1,0]
	v_pk_add_f32 v[182:183], v[182:183], 1.0 op_sel_hi:[1,0]
	v_pk_add_f32 v[184:185], v[184:185], 1.0 op_sel_hi:[1,0]
	v_pk_add_f32 v[186:187], v[186:187], 1.0 op_sel_hi:[1,0]
	v_rcp_f32_e32 v180, v180
	v_rcp_f32_e32 v181, v181
	v_rcp_f32_e32 v182, v182
	v_rcp_f32_e32 v183, v183
	v_rcp_f32_e32 v184, v184
	v_rcp_f32_e32 v185, v185
	v_rcp_f32_e32 v186, v186
	v_rcp_f32_e32 v187, v187
	v_pk_mul_f32 v[90:91], v[180:181], v[228:229]
	v_pk_mul_f32 v[92:93], v[182:183], v[230:231]
	v_pk_mul_f32 v[86:87], v[184:185], v[232:233]
	v_pk_mul_f32 v[88:89], v[186:187], v[234:235]
	v_min3_f32 v238, v238, v90, v91
	v_min3_f32 v238, v238, v92, v93
	v_min3_f32 v238, v238, v86, v87
	v_min3_f32 v238, v238, v88, v89
	v_cvt_pk_bf16_f32 v208, v90, v91
	v_cvt_pk_bf16_f32 v209, v92, v93
	v_cvt_pk_bf16_f32 v210, v86, v87
	v_cvt_pk_bf16_f32 v211, v88, v89
	global_store_dwordx4 v178, v[208:211], s[8:9]
	v_pk_mul_f32 v[180:181], v[74:75], s[74:75] op_sel_hi:[1,0]
	v_pk_mul_f32 v[182:183], v[76:77], s[74:75] op_sel_hi:[1,0]
	v_pk_mul_f32 v[184:185], v[70:71], s[74:75] op_sel_hi:[1,0]
	v_pk_mul_f32 v[186:187], v[72:73], s[74:75] op_sel_hi:[1,0]
	v_exp_f32_e32 v180, v180
	v_exp_f32_e32 v181, v181
	v_exp_f32_e32 v182, v182
	v_exp_f32_e32 v183, v183
	v_exp_f32_e32 v184, v184
	v_exp_f32_e32 v185, v185
	v_exp_f32_e32 v186, v186
	v_exp_f32_e32 v187, v187
	v_pk_add_f32 v[180:181], v[180:181], 1.0 op_sel_hi:[1,0]
	v_pk_add_f32 v[182:183], v[182:183], 1.0 op_sel_hi:[1,0]
	v_pk_add_f32 v[184:185], v[184:185], 1.0 op_sel_hi:[1,0]
	v_pk_add_f32 v[186:187], v[186:187], 1.0 op_sel_hi:[1,0]
	v_rcp_f32_e32 v180, v180
	v_rcp_f32_e32 v181, v181
	v_rcp_f32_e32 v182, v182
	v_rcp_f32_e32 v183, v183
	v_rcp_f32_e32 v184, v184
	v_rcp_f32_e32 v185, v185
	v_rcp_f32_e32 v186, v186
	v_rcp_f32_e32 v187, v187
	v_pk_mul_f32 v[74:75], v[180:181], v[228:229]
	v_pk_mul_f32 v[76:77], v[182:183], v[230:231]
	v_pk_mul_f32 v[70:71], v[184:185], v[232:233]
	v_pk_mul_f32 v[72:73], v[186:187], v[234:235]
	v_min3_f32 v238, v238, v74, v75
	v_min3_f32 v238, v238, v76, v77
	v_min3_f32 v238, v238, v70, v71
	v_min3_f32 v238, v238, v72, v73
	v_cvt_pk_bf16_f32 v212, v74, v75
	v_cvt_pk_bf16_f32 v213, v76, v77
	v_cvt_pk_bf16_f32 v214, v70, v71
	v_cvt_pk_bf16_f32 v215, v72, v73
	global_store_dwordx4 v179, v[212:215], s[8:9]
	v_cmp_ge_f32_e32 vcc, s13, v238
	s_nop 4
	s_cbranch_vccnz .Lgate_epi_general
	v_pk_mul_f32 v[180:181], v[58:59], s[74:75] op_sel_hi:[1,0]
	v_pk_mul_f32 v[182:183], v[60:61], s[74:75] op_sel_hi:[1,0]
	v_pk_mul_f32 v[184:185], v[66:67], s[74:75] op_sel_hi:[1,0]
	v_pk_mul_f32 v[186:187], v[68:69], s[74:75] op_sel_hi:[1,0]
	v_exp_f32_e32 v180, v180
	v_exp_f32_e32 v181, v181
	v_exp_f32_e32 v182, v182
	v_exp_f32_e32 v183, v183
	v_exp_f32_e32 v184, v184
	v_exp_f32_e32 v185, v185
	v_exp_f32_e32 v186, v186
	v_exp_f32_e32 v187, v187
	v_pk_fma_f32 v[188:189], v[204:205], s[24:25], v[236:237] op_sel_hi:[1,0,0]
	v_pk_fma_f32 v[190:191], v[206:207], s[24:25], v[236:237] op_sel_hi:[1,0,0]
	v_pk_fma_f32 v[192:193], v[220:221], s[24:25], v[236:237] op_sel_hi:[1,0,0]
	v_pk_fma_f32 v[194:195], v[222:223], s[24:25], v[236:237] op_sel_hi:[1,0,0]
	v_pk_add_f32 v[180:181], v[180:181], 1.0 op_sel_hi:[1,0]
	v_pk_add_f32 v[182:183], v[182:183], 1.0 op_sel_hi:[1,0]
	v_pk_add_f32 v[184:185], v[184:185], 1.0 op_sel_hi:[1,0]
	v_pk_add_f32 v[186:187], v[186:187], 1.0 op_sel_hi:[1,0]
	v_rcp_f32_e32 v180, v180
	v_rcp_f32_e32 v181, v181
	v_rcp_f32_e32 v182, v182
	v_rcp_f32_e32 v183, v183
	v_rcp_f32_e32 v184, v184
	v_rcp_f32_e32 v185, v185
	v_rcp_f32_e32 v186, v186
	v_rcp_f32_e32 v187, v187
	v_pk_fma_f32 v[188:189], v[204:205], v[188:189], s[22:23] op_sel_hi:[1,1,0]
	v_pk_fma_f32 v[190:191], v[206:207], v[190:191], s[22:23] op_sel_hi:[1,1,0]
	v_pk_fma_f32 v[192:193], v[220:221], v[192:193], s[22:23] op_sel_hi:[1,1,0]
	v_pk_fma_f32 v[194:195], v[222:223], v[194:195], s[22:23] op_sel_hi:[1,1,0]
	v_pk_fma_f32 v[188:189], v[204:205], v[188:189], -2.0 op_sel_hi:[1,1,0]
	v_pk_fma_f32 v[190:191], v[206:207], v[190:191], -2.0 op_sel_hi:[1,1,0]
	v_pk_fma_f32 v[192:193], v[220:221], v[192:193], -2.0 op_sel_hi:[1,1,0]
	v_pk_fma_f32 v[194:195], v[222:223], v[194:195], -2.0 op_sel_hi:[1,1,0]
	v_pk_fma_f32 v[188:189], v[204:205], v[188:189], -2.0 op_sel_hi:[1,1,0]
	v_pk_fma_f32 v[190:191], v[206:207], v[190:191], -2.0 op_sel_hi:[1,1,0]
	v_pk_fma_f32 v[192:193], v[220:221], v[192:193], -2.0 op_sel_hi:[1,1,0]
	v_pk_fma_f32 v[194:195], v[222:223], v[194:195], -2.0 op_sel_hi:[1,1,0]
	v_pk_mul_f32 v[188:189], v[204:205], v[188:189]
	v_pk_mul_f32 v[190:191], v[206:207], v[190:191]
	v_pk_mul_f32 v[192:193], v[220:221], v[192:193]
	v_pk_mul_f32 v[194:195], v[222:223], v[194:195]
	v_pk_mul_f32 v[228:229], v[204:205], s[74:75] op_sel_hi:[1,0] neg_lo:[0,1] neg_hi:[0,1]
	v_pk_mul_f32 v[230:231], v[206:207], s[74:75] op_sel_hi:[1,0] neg_lo:[0,1] neg_hi:[0,1]
	v_pk_mul_f32 v[232:233], v[220:221], s[74:75] op_sel_hi:[1,0] neg_lo:[0,1] neg_hi:[0,1]
	v_pk_mul_f32 v[234:235], v[222:223], s[74:75] op_sel_hi:[1,0] neg_lo:[0,1] neg_hi:[0,1]
	v_sqrt_f32_e32 v188, v188
	v_sqrt_f32_e32 v189, v189
	v_sqrt_f32_e32 v190, v190
	v_sqrt_f32_e32 v191, v191
	v_sqrt_f32_e32 v192, v192
	v_sqrt_f32_e32 v193, v193
	v_sqrt_f32_e32 v194, v194
	v_sqrt_f32_e32 v195, v195
	v_exp_f32_e32 v58, v228
	v_exp_f32_e32 v59, v229
	v_exp_f32_e32 v60, v230
	v_exp_f32_e32 v61, v231
	v_exp_f32_e32 v66, v232
	v_exp_f32_e32 v67, v233
	v_exp_f32_e32 v68, v234
	v_exp_f32_e32 v69, v235
	s_waitcnt vmcnt(15)
;     __device__ __forceinline__ void operator()(AccMut acc, const Unit& u, int sw) const {
;     ...
;             for (int m = 0; m < 4; ++m) { const size_t off = (size_t)(row0 + ai * HALF + m * 16) * E + c0;
;                 const u32x4 xw = xnext;
;                 if (ai * 4 + m < 7) { const int ai2 = (ai * 4 + m + 1) >> 2, m2 = (ai * 4 + m + 1) & 3; xnext = *(const u32x4*)(XC + (size_t)(row0 + ai2 * HALF + m2 * 16) * E + c0); }
;                 float bt[8];
; #pragma unroll
;                 for (int n = 0; n < 2; ++n)
; #pragma unroll
;                     for (int jp = 0; jp < 2; ++jp) {
;                         const f32x2 z = (f32x2){acc[ai][1][m][n][2 * jp], acc[ai][1][m][n][2 * jp + 1]} * (-1.44269504f);
;                         f32x2 e; e.x = __builtin_amdgcn_exp2f(z.x); e.y = __builtin_amdgcn_exp2f(z.y); e = e + 1.0f;
;                         f32x2 ig; ig.x = __builtin_amdgcn_rcpf(e.x); ig.y = __builtin_amdgcn_rcpf(e.y);
;                         const f32x2 x2 = (f32x2){acc[ai][0][m][n][2 * jp], acc[ai][0][m][n][2 * jp + 1]} * 2.0f;
;                         f32x2 ser = x2 * (1.0f / 120.0f) + (1.0f / 24.0f); ser = ser * x2 + (1.0f / 6.0f); ser = ser * x2 + 0.5f; ser = ser * x2 + 1.0f; ser = ser * (-x2);
;                         f32x2 em = ser;
;                         if (__builtin_expect(__builtin_amdgcn_ballot_w64(x2.x <= -0.25f || x2.y <= -0.25f) != 0ull, 0)) {
;                             em.x = (x2.x > -0.25f) ? ser.x : (1.0f - fexp(x2.x)); em.y = (x2.y > -0.25f) ? ser.y : (1.0f - fexp(x2.y)); }
;                         const unsigned wv = xw[2 * n + jp];
;                         f32x2 sq; sq.x = __builtin_amdgcn_sqrtf(em.x); sq.y = __builtin_amdgcn_sqrtf(em.y);
;                         const f32x2 b2 = sq * ig * (f32x2){bf_lo(wv), bf_hi(wv)};
;                         bt[4 * n + 2 * jp] = b2.x; bt[4 * n + 2 * jp + 1] = b2.y; }
;                 u32x4 w; w.x = cvt_pk_bf16(bt[0], bt[1]); w.y = cvt_pk_bf16(bt[2], bt[3]); w.z = cvt_pk_bf16(bt[4], bt[5]); w.w = cvt_pk_bf16(bt[6], bt[7]);
;                 *(u32x4*)(BT + off) = w; }
; __device__ __forceinline__ void scan1_phase(const bf16_t* LA, const bf16_t* BT, int sw, View vw) {
;     ...
;                 const float l0 = bf_lo(lw[i].x), l1 = bf_hi(lw[i].x), l2 = bf_lo(lw[i].y), l3 = bf_hi(lw[i].y);
;                 S[0] += l0; S[1] += l1; S[2] += l2; S[3] += l3;
	v_lshlrev_b32_e32 v196, 16, v136
	v_and_b32_e32 v197, 0xffff0000, v136
	v_lshlrev_b32_e32 v198, 16, v137
	v_and_b32_e32 v199, 0xffff0000, v137
	v_lshlrev_b32_e32 v200, 16, v138
	v_and_b32_e32 v201, 0xffff0000, v138
	v_lshlrev_b32_e32 v202, 16, v139
	v_and_b32_e32 v203, 0xffff0000, v139
	v_pk_mul_f32 v[188:189], v[188:189], v[180:181]
	v_pk_mul_f32 v[190:191], v[190:191], v[182:183]
	v_pk_mul_f32 v[192:193], v[192:193], v[184:185]
	v_pk_mul_f32 v[194:195], v[194:195], v[186:187]
	v_pk_mul_f32 v[216:217], v[188:189], v[196:197]
	v_pk_mul_f32 v[218:219], v[190:191], v[198:199]
	v_pk_mul_f32 v[240:241], v[192:193], v[200:201]
	v_pk_mul_f32 v[242:243], v[194:195], v[202:203]
	v_cvt_pk_bf16_f32 v208, v216, v217
	v_cvt_pk_bf16_f32 v209, v218, v219
	v_cvt_pk_bf16_f32 v210, v240, v241
	v_cvt_pk_bf16_f32 v211, v242, v243
	global_store_dwordx4 v168, v[208:211], s[10:11]
	v_pk_mul_f32 v[180:181], v[50:51], s[74:75] op_sel_hi:[1,0]
	v_pk_mul_f32 v[182:183], v[52:53], s[74:75] op_sel_hi:[1,0]
	v_pk_mul_f32 v[184:185], v[54:55], s[74:75] op_sel_hi:[1,0]
	v_pk_mul_f32 v[186:187], v[56:57], s[74:75] op_sel_hi:[1,0]
	v_exp_f32_e32 v180, v180
	v_exp_f32_e32 v181, v181
	v_exp_f32_e32 v182, v182
	v_exp_f32_e32 v183, v183
	v_exp_f32_e32 v184, v184
	v_exp_f32_e32 v185, v185
	v_exp_f32_e32 v186, v186
	v_exp_f32_e32 v187, v187
	v_pk_fma_f32 v[188:189], v[224:225], s[24:25], v[236:237] op_sel_hi:[1,0,0]
	v_pk_fma_f32 v[190:191], v[226:227], s[24:25], v[236:237] op_sel_hi:[1,0,0]
	v_pk_fma_f32 v[192:193], v[126:127], s[24:25], v[236:237] op_sel_hi:[1,0,0]
	v_pk_fma_f32 v[194:195], v[128:129], s[24:25], v[236:237] op_sel_hi:[1,0,0]
	v_pk_add_f32 v[180:181], v[180:181], 1.0 op_sel_hi:[1,0]
	v_pk_add_f32 v[182:183], v[182:183], 1.0 op_sel_hi:[1,0]
	v_pk_add_f32 v[184:185], v[184:185], 1.0 op_sel_hi:[1,0]
	v_pk_add_f32 v[186:187], v[186:187], 1.0 op_sel_hi:[1,0]
	v_rcp_f32_e32 v180, v180
	v_rcp_f32_e32 v181, v181
	v_rcp_f32_e32 v182, v182
	v_rcp_f32_e32 v183, v183
	v_rcp_f32_e32 v184, v184
	v_rcp_f32_e32 v185, v185
	v_rcp_f32_e32 v186, v186
	v_rcp_f32_e32 v187, v187
	v_pk_fma_f32 v[188:189], v[224:225], v[188:189], s[22:23] op_sel_hi:[1,1,0]
	v_pk_fma_f32 v[190:191], v[226:227], v[190:191], s[22:23] op_sel_hi:[1,1,0]
	v_pk_fma_f32 v[192:193], v[126:127], v[192:193], s[22:23] op_sel_hi:[1,1,0]
	v_pk_fma_f32 v[194:195], v[128:129], v[194:195], s[22:23] op_sel_hi:[1,1,0]
	v_pk_fma_f32 v[188:189], v[224:225], v[188:189], -2.0 op_sel_hi:[1,1,0]
	v_pk_fma_f32 v[190:191], v[226:227], v[190:191], -2.0 op_sel_hi:[1,1,0]
	v_pk_fma_f32 v[192:193], v[126:127], v[192:193], -2.0 op_sel_hi:[1,1,0]
	v_pk_fma_f32 v[194:195], v[128:129], v[194:195], -2.0 op_sel_hi:[1,1,0]
	v_pk_fma_f32 v[188:189], v[224:225], v[188:189], -2.0 op_sel_hi:[1,1,0]
	v_pk_fma_f32 v[190:191], v[226:227], v[190:191], -2.0 op_sel_hi:[1,1,0]
	v_pk_fma_f32 v[192:193], v[126:127], v[192:193], -2.0 op_sel_hi:[1,1,0]
	v_pk_fma_f32 v[194:195], v[128:129], v[194:195], -2.0 op_sel_hi:[1,1,0]
	v_pk_mul_f32 v[188:189], v[224:225], v[188:189]
	v_pk_mul_f32 v[190:191], v[226:227], v[190:191]
	v_pk_mul_f32 v[192:193], v[126:127], v[192:193]
	v_pk_mul_f32 v[194:195], v[128:129], v[194:195]
	v_pk_mul_f32 v[228:229], v[224:225], s[74:75] op_sel_hi:[1,0] neg_lo:[0,1] neg_hi:[0,1]
	v_pk_mul_f32 v[230:231], v[226:227], s[74:75] op_sel_hi:[1,0] neg_lo:[0,1] neg_hi:[0,1]
	v_pk_mul_f32 v[232:233], v[126:127], s[74:75] op_sel_hi:[1,0] neg_lo:[0,1] neg_hi:[0,1]
	v_pk_mul_f32 v[234:235], v[128:129], s[74:75] op_sel_hi:[1,0] neg_lo:[0,1] neg_hi:[0,1]
	v_sqrt_f32_e32 v188, v188
	v_sqrt_f32_e32 v189, v189
	v_sqrt_f32_e32 v190, v190
	v_sqrt_f32_e32 v191, v191
	v_sqrt_f32_e32 v192, v192
	v_sqrt_f32_e32 v193, v193
	v_sqrt_f32_e32 v194, v194
	v_sqrt_f32_e32 v195, v195
	v_exp_f32_e32 v228, v228
	v_exp_f32_e32 v229, v229
	v_exp_f32_e32 v230, v230
	v_exp_f32_e32 v231, v231
	v_exp_f32_e32 v232, v232
	v_exp_f32_e32 v233, v233
	v_exp_f32_e32 v234, v234
	v_exp_f32_e32 v235, v235
	s_waitcnt vmcnt(15)
	v_lshlrev_b32_e32 v196, 16, v140
	v_and_b32_e32 v197, 0xffff0000, v140
	v_lshlrev_b32_e32 v198, 16, v141
	v_and_b32_e32 v199, 0xffff0000, v141
	v_lshlrev_b32_e32 v200, 16, v142
	v_and_b32_e32 v201, 0xffff0000, v142
	v_lshlrev_b32_e32 v202, 16, v143
	v_and_b32_e32 v203, 0xffff0000, v143
	v_pk_mul_f32 v[188:189], v[188:189], v[180:181]
	v_pk_mul_f32 v[190:191], v[190:191], v[182:183]
	v_pk_mul_f32 v[192:193], v[192:193], v[184:185]
	v_pk_mul_f32 v[194:195], v[194:195], v[186:187]
	v_pk_mul_f32 v[188:189], v[188:189], v[196:197]
	v_pk_mul_f32 v[190:191], v[190:191], v[198:199]
	v_pk_mul_f32 v[192:193], v[192:193], v[200:201]
	v_pk_mul_f32 v[194:195], v[194:195], v[202:203]
	v_cvt_pk_bf16_f32 v212, v188, v189
	v_cvt_pk_bf16_f32 v213, v190, v191
	v_cvt_pk_bf16_f32 v214, v192, v193
	v_cvt_pk_bf16_f32 v215, v194, v195
	global_store_dwordx4 v169, v[212:215], s[10:11]
	v_pk_fma_f32 v[216:217], v[228:229], v[216:217], v[188:189]
	v_pk_fma_f32 v[218:219], v[230:231], v[218:219], v[190:191]
	v_pk_fma_f32 v[240:241], v[232:233], v[240:241], v[192:193]
	v_pk_fma_f32 v[242:243], v[234:235], v[242:243], v[194:195]
	v_pk_mul_f32 v[58:59], v[58:59], v[228:229]
	v_pk_mul_f32 v[60:61], v[60:61], v[230:231]
	v_pk_mul_f32 v[66:67], v[66:67], v[232:233]
	v_pk_mul_f32 v[68:69], v[68:69], v[234:235]
	v_pk_add_f32 v[204:205], v[204:205], v[224:225]
	v_pk_add_f32 v[206:207], v[206:207], v[226:227]
	v_pk_add_f32 v[220:221], v[220:221], v[126:127]
	v_pk_add_f32 v[222:223], v[222:223], v[128:129]
	v_pk_mul_f32 v[180:181], v[42:43], s[74:75] op_sel_hi:[1,0]
	v_pk_mul_f32 v[182:183], v[44:45], s[74:75] op_sel_hi:[1,0]
	v_pk_mul_f32 v[184:185], v[46:47], s[74:75] op_sel_hi:[1,0]
;     __device__ __forceinline__ void operator()(AccMut acc, const Unit& u, int sw) const {
;     ...
;             for (int m = 0; m < 4; ++m) { const size_t off = (size_t)(row0 + ai * HALF + m * 16) * E + c0;
;                 const u32x4 xw = xnext;
;                 if (ai * 4 + m < 7) { const int ai2 = (ai * 4 + m + 1) >> 2, m2 = (ai * 4 + m + 1) & 3; xnext = *(const u32x4*)(XC + (size_t)(row0 + ai2 * HALF + m2 * 16) * E + c0); }
;                 float bt[8];
; #pragma unroll
;                 for (int n = 0; n < 2; ++n)
; #pragma unroll
;                     for (int jp = 0; jp < 2; ++jp) {
;                         const f32x2 z = (f32x2){acc[ai][1][m][n][2 * jp], acc[ai][1][m][n][2 * jp + 1]} * (-1.44269504f);
;                         f32x2 e; e.x = __builtin_amdgcn_exp2f(z.x); e.y = __builtin_amdgcn_exp2f(z.y); e = e + 1.0f;
;                         f32x2 ig; ig.x = __builtin_amdgcn_rcpf(e.x); ig.y = __builtin_amdgcn_rcpf(e.y);
;                         const f32x2 x2 = (f32x2){acc[ai][0][m][n][2 * jp], acc[ai][0][m][n][2 * jp + 1]} * 2.0f;
;                         f32x2 ser = x2 * (1.0f / 120.0f) + (1.0f / 24.0f); ser = ser * x2 + (1.0f / 6.0f); ser = ser * x2 + 0.5f; ser = ser * x2 + 1.0f; ser = ser * (-x2);
;                         f32x2 em = ser;
;                         if (__builtin_expect(__builtin_amdgcn_ballot_w64(x2.x <= -0.25f || x2.y <= -0.25f) != 0ull, 0)) {
;                             em.x = (x2.x > -0.25f) ? ser.x : (1.0f - fexp(x2.x)); em.y = (x2.y > -0.25f) ? ser.y : (1.0f - fexp(x2.y)); }
;                         const unsigned wv = xw[2 * n + jp];
;                         f32x2 sq; sq.x = __builtin_amdgcn_sqrtf(em.x); sq.y = __builtin_amdgcn_sqrtf(em.y);
;                         const f32x2 b2 = sq * ig * (f32x2){bf_lo(wv), bf_hi(wv)};
;                         bt[4 * n + 2 * jp] = b2.x; bt[4 * n + 2 * jp + 1] = b2.y; }
;                 u32x4 w; w.x = cvt_pk_bf16(bt[0], bt[1]); w.y = cvt_pk_bf16(bt[2], bt[3]); w.z = cvt_pk_bf16(bt[4], bt[5]); w.w = cvt_pk_bf16(bt[6], bt[7]);
;                 *(u32x4*)(BT + off) = w; }
; __device__ __forceinline__ void scan1_phase(const bf16_t* LA, const bf16_t* BT, int sw, View vw) {
;     ...
;                 const float l0 = bf_lo(lw[i].x), l1 = bf_hi(lw[i].x), l2 = bf_lo(lw[i].y), l3 = bf_hi(lw[i].y);
;                 S[0] += l0; S[1] += l1; S[2] += l2; S[3] += l3;
	v_pk_mul_f32 v[186:187], v[48:49], s[74:75] op_sel_hi:[1,0]
	v_exp_f32_e32 v180, v180
	v_exp_f32_e32 v181, v181
	v_exp_f32_e32 v182, v182
	v_exp_f32_e32 v183, v183
	v_exp_f32_e32 v184, v184
	v_exp_f32_e32 v185, v185
	v_exp_f32_e32 v186, v186
	v_exp_f32_e32 v187, v187
	v_pk_fma_f32 v[188:189], v[122:123], s[24:25], v[236:237] op_sel_hi:[1,0,0]
	v_pk_fma_f32 v[190:191], v[124:125], s[24:25], v[236:237] op_sel_hi:[1,0,0]
	v_pk_fma_f32 v[192:193], v[118:119], s[24:25], v[236:237] op_sel_hi:[1,0,0]
	v_pk_fma_f32 v[194:195], v[120:121], s[24:25], v[236:237] op_sel_hi:[1,0,0]
	v_pk_add_f32 v[180:181], v[180:181], 1.0 op_sel_hi:[1,0]
	v_pk_add_f32 v[182:183], v[182:183], 1.0 op_sel_hi:[1,0]
	v_pk_add_f32 v[184:185], v[184:185], 1.0 op_sel_hi:[1,0]
	v_pk_add_f32 v[186:187], v[186:187], 1.0 op_sel_hi:[1,0]
	v_rcp_f32_e32 v180, v180
	v_rcp_f32_e32 v181, v181
	v_rcp_f32_e32 v182, v182
	v_rcp_f32_e32 v183, v183
	v_rcp_f32_e32 v184, v184
	v_rcp_f32_e32 v185, v185
	v_rcp_f32_e32 v186, v186
	v_rcp_f32_e32 v187, v187
	v_pk_fma_f32 v[188:189], v[122:123], v[188:189], s[22:23] op_sel_hi:[1,1,0]
	v_pk_fma_f32 v[190:191], v[124:125], v[190:191], s[22:23] op_sel_hi:[1,1,0]
	v_pk_fma_f32 v[192:193], v[118:119], v[192:193], s[22:23] op_sel_hi:[1,1,0]
	v_pk_fma_f32 v[194:195], v[120:121], v[194:195], s[22:23] op_sel_hi:[1,1,0]
	v_pk_fma_f32 v[188:189], v[122:123], v[188:189], -2.0 op_sel_hi:[1,1,0]
	v_pk_fma_f32 v[190:191], v[124:125], v[190:191], -2.0 op_sel_hi:[1,1,0]
	v_pk_fma_f32 v[192:193], v[118:119], v[192:193], -2.0 op_sel_hi:[1,1,0]
	v_pk_fma_f32 v[194:195], v[120:121], v[194:195], -2.0 op_sel_hi:[1,1,0]
	v_pk_fma_f32 v[188:189], v[122:123], v[188:189], -2.0 op_sel_hi:[1,1,0]
	v_pk_fma_f32 v[190:191], v[124:125], v[190:191], -2.0 op_sel_hi:[1,1,0]
	v_pk_fma_f32 v[192:193], v[118:119], v[192:193], -2.0 op_sel_hi:[1,1,0]
	v_pk_fma_f32 v[194:195], v[120:121], v[194:195], -2.0 op_sel_hi:[1,1,0]
	v_pk_mul_f32 v[188:189], v[122:123], v[188:189]
	v_pk_mul_f32 v[190:191], v[124:125], v[190:191]
	v_pk_mul_f32 v[192:193], v[118:119], v[192:193]
	v_pk_mul_f32 v[194:195], v[120:121], v[194:195]
	v_pk_mul_f32 v[228:229], v[122:123], s[74:75] op_sel_hi:[1,0] neg_lo:[0,1] neg_hi:[0,1]
	v_pk_mul_f32 v[230:231], v[124:125], s[74:75] op_sel_hi:[1,0] neg_lo:[0,1] neg_hi:[0,1]
	v_pk_mul_f32 v[232:233], v[118:119], s[74:75] op_sel_hi:[1,0] neg_lo:[0,1] neg_hi:[0,1]
	v_pk_mul_f32 v[234:235], v[120:121], s[74:75] op_sel_hi:[1,0] neg_lo:[0,1] neg_hi:[0,1]
	v_sqrt_f32_e32 v188, v188
	v_sqrt_f32_e32 v189, v189
	v_sqrt_f32_e32 v190, v190
	v_sqrt_f32_e32 v191, v191
	v_sqrt_f32_e32 v192, v192
	v_sqrt_f32_e32 v193, v193
	v_sqrt_f32_e32 v194, v194
	v_sqrt_f32_e32 v195, v195
	v_exp_f32_e32 v228, v228
	v_exp_f32_e32 v229, v229
	v_exp_f32_e32 v230, v230
	v_exp_f32_e32 v231, v231
	v_exp_f32_e32 v232, v232
	v_exp_f32_e32 v233, v233
	v_exp_f32_e32 v234, v234
	v_exp_f32_e32 v235, v235
	s_waitcnt vmcnt(15)
	v_lshlrev_b32_e32 v196, 16, v144
	v_and_b32_e32 v197, 0xffff0000, v144
	v_lshlrev_b32_e32 v198, 16, v145
	v_and_b32_e32 v199, 0xffff0000, v145
	v_lshlrev_b32_e32 v200, 16, v146
	v_and_b32_e32 v201, 0xffff0000, v146
	v_lshlrev_b32_e32 v202, 16, v147
	v_and_b32_e32 v203, 0xffff0000, v147
	v_pk_mul_f32 v[188:189], v[188:189], v[180:181]
	v_pk_mul_f32 v[190:191], v[190:191], v[182:183]
	v_pk_mul_f32 v[192:193], v[192:193], v[184:185]
	v_pk_mul_f32 v[194:195], v[194:195], v[186:187]
	v_pk_mul_f32 v[188:189], v[188:189], v[196:197]
	v_pk_mul_f32 v[190:191], v[190:191], v[198:199]
	v_pk_mul_f32 v[192:193], v[192:193], v[200:201]
	v_pk_mul_f32 v[194:195], v[194:195], v[202:203]
	v_cvt_pk_bf16_f32 v208, v188, v189
	v_cvt_pk_bf16_f32 v209, v190, v191
	v_cvt_pk_bf16_f32 v210, v192, v193
	v_cvt_pk_bf16_f32 v211, v194, v195
	global_store_dwordx4 v172, v[208:211], s[10:11]
	v_pk_fma_f32 v[216:217], v[228:229], v[216:217], v[188:189]
	v_pk_fma_f32 v[218:219], v[230:231], v[218:219], v[190:191]
	v_pk_fma_f32 v[240:241], v[232:233], v[240:241], v[192:193]
	v_pk_fma_f32 v[242:243], v[234:235], v[242:243], v[194:195]
	v_pk_mul_f32 v[58:59], v[58:59], v[228:229]
	v_pk_mul_f32 v[60:61], v[60:61], v[230:231]
	v_pk_mul_f32 v[66:67], v[66:67], v[232:233]
	v_pk_mul_f32 v[68:69], v[68:69], v[234:235]
	v_pk_add_f32 v[204:205], v[204:205], v[122:123]
	v_pk_add_f32 v[206:207], v[206:207], v[124:125]
	v_pk_add_f32 v[220:221], v[220:221], v[118:119]
	v_pk_add_f32 v[222:223], v[222:223], v[120:121]
	v_pk_mul_f32 v[180:181], v[34:35], s[74:75] op_sel_hi:[1,0]
	v_pk_mul_f32 v[182:183], v[36:37], s[74:75] op_sel_hi:[1,0]
	v_pk_mul_f32 v[184:185], v[38:39], s[74:75] op_sel_hi:[1,0]
	v_pk_mul_f32 v[186:187], v[40:41], s[74:75] op_sel_hi:[1,0]
	v_exp_f32_e32 v180, v180
	v_exp_f32_e32 v181, v181
	v_exp_f32_e32 v182, v182
	v_exp_f32_e32 v183, v183
	v_exp_f32_e32 v184, v184
	v_exp_f32_e32 v185, v185
	v_exp_f32_e32 v186, v186
	v_exp_f32_e32 v187, v187
	v_pk_fma_f32 v[188:189], v[114:115], s[24:25], v[236:237] op_sel_hi:[1,0,0]
	v_pk_fma_f32 v[190:191], v[116:117], s[24:25], v[236:237] op_sel_hi:[1,0,0]
	v_pk_fma_f32 v[192:193], v[106:107], s[24:25], v[236:237] op_sel_hi:[1,0,0]
	v_pk_fma_f32 v[194:195], v[108:109], s[24:25], v[236:237] op_sel_hi:[1,0,0]
	v_pk_add_f32 v[180:181], v[180:181], 1.0 op_sel_hi:[1,0]
	v_pk_add_f32 v[182:183], v[182:183], 1.0 op_sel_hi:[1,0]
	v_pk_add_f32 v[184:185], v[184:185], 1.0 op_sel_hi:[1,0]
	v_pk_add_f32 v[186:187], v[186:187], 1.0 op_sel_hi:[1,0]
	v_rcp_f32_e32 v180, v180
	v_rcp_f32_e32 v181, v181
	v_rcp_f32_e32 v182, v182
	v_rcp_f32_e32 v183, v183
	v_rcp_f32_e32 v184, v184
	v_rcp_f32_e32 v185, v185
	v_rcp_f32_e32 v186, v186
	v_rcp_f32_e32 v187, v187
	v_pk_fma_f32 v[188:189], v[114:115], v[188:189], s[22:23] op_sel_hi:[1,1,0]
;     __device__ __forceinline__ void operator()(AccMut acc, const Unit& u, int sw) const {
;     ...
;             for (int m = 0; m < 4; ++m) { const size_t off = (size_t)(row0 + ai * HALF + m * 16) * E + c0;
;                 const u32x4 xw = xnext;
;                 if (ai * 4 + m < 7) { const int ai2 = (ai * 4 + m + 1) >> 2, m2 = (ai * 4 + m + 1) & 3; xnext = *(const u32x4*)(XC + (size_t)(row0 + ai2 * HALF + m2 * 16) * E + c0); }
;                 float bt[8];
; #pragma unroll
;                 for (int n = 0; n < 2; ++n)
; #pragma unroll
;                     for (int jp = 0; jp < 2; ++jp) {
;                         const f32x2 z = (f32x2){acc[ai][1][m][n][2 * jp], acc[ai][1][m][n][2 * jp + 1]} * (-1.44269504f);
;                         f32x2 e; e.x = __builtin_amdgcn_exp2f(z.x); e.y = __builtin_amdgcn_exp2f(z.y); e = e + 1.0f;
;                         f32x2 ig; ig.x = __builtin_amdgcn_rcpf(e.x); ig.y = __builtin_amdgcn_rcpf(e.y);
;                         const f32x2 x2 = (f32x2){acc[ai][0][m][n][2 * jp], acc[ai][0][m][n][2 * jp + 1]} * 2.0f;
;                         f32x2 ser = x2 * (1.0f / 120.0f) + (1.0f / 24.0f); ser = ser * x2 + (1.0f / 6.0f); ser = ser * x2 + 0.5f; ser = ser * x2 + 1.0f; ser = ser * (-x2);
;                         f32x2 em = ser;
;                         if (__builtin_expect(__builtin_amdgcn_ballot_w64(x2.x <= -0.25f || x2.y <= -0.25f) != 0ull, 0)) {
;                             em.x = (x2.x > -0.25f) ? ser.x : (1.0f - fexp(x2.x)); em.y = (x2.y > -0.25f) ? ser.y : (1.0f - fexp(x2.y)); }
;                         const unsigned wv = xw[2 * n + jp];
;                         f32x2 sq; sq.x = __builtin_amdgcn_sqrtf(em.x); sq.y = __builtin_amdgcn_sqrtf(em.y);
;                         const f32x2 b2 = sq * ig * (f32x2){bf_lo(wv), bf_hi(wv)};
;                         bt[4 * n + 2 * jp] = b2.x; bt[4 * n + 2 * jp + 1] = b2.y; }
;                 u32x4 w; w.x = cvt_pk_bf16(bt[0], bt[1]); w.y = cvt_pk_bf16(bt[2], bt[3]); w.z = cvt_pk_bf16(bt[4], bt[5]); w.w = cvt_pk_bf16(bt[6], bt[7]);
;                 *(u32x4*)(BT + off) = w; }
; __device__ __forceinline__ void scan1_phase(const bf16_t* LA, const bf16_t* BT, int sw, View vw) {
;     ...
;                 const float l0 = bf_lo(lw[i].x), l1 = bf_hi(lw[i].x), l2 = bf_lo(lw[i].y), l3 = bf_hi(lw[i].y);
;                 S[0] += l0; S[1] += l1; S[2] += l2; S[3] += l3;
	v_pk_fma_f32 v[190:191], v[116:117], v[190:191], s[22:23] op_sel_hi:[1,1,0]
	v_pk_fma_f32 v[192:193], v[106:107], v[192:193], s[22:23] op_sel_hi:[1,1,0]
	v_pk_fma_f32 v[194:195], v[108:109], v[194:195], s[22:23] op_sel_hi:[1,1,0]
	v_pk_fma_f32 v[188:189], v[114:115], v[188:189], -2.0 op_sel_hi:[1,1,0]
	v_pk_fma_f32 v[190:191], v[116:117], v[190:191], -2.0 op_sel_hi:[1,1,0]
	v_pk_fma_f32 v[192:193], v[106:107], v[192:193], -2.0 op_sel_hi:[1,1,0]
	v_pk_fma_f32 v[194:195], v[108:109], v[194:195], -2.0 op_sel_hi:[1,1,0]
	v_pk_fma_f32 v[188:189], v[114:115], v[188:189], -2.0 op_sel_hi:[1,1,0]
	v_pk_fma_f32 v[190:191], v[116:117], v[190:191], -2.0 op_sel_hi:[1,1,0]
	v_pk_fma_f32 v[192:193], v[106:107], v[192:193], -2.0 op_sel_hi:[1,1,0]
	v_pk_fma_f32 v[194:195], v[108:109], v[194:195], -2.0 op_sel_hi:[1,1,0]
	v_pk_mul_f32 v[188:189], v[114:115], v[188:189]
	v_pk_mul_f32 v[190:191], v[116:117], v[190:191]
	v_pk_mul_f32 v[192:193], v[106:107], v[192:193]
	v_pk_mul_f32 v[194:195], v[108:109], v[194:195]
	v_pk_mul_f32 v[228:229], v[114:115], s[74:75] op_sel_hi:[1,0] neg_lo:[0,1] neg_hi:[0,1]
	v_pk_mul_f32 v[230:231], v[116:117], s[74:75] op_sel_hi:[1,0] neg_lo:[0,1] neg_hi:[0,1]
	v_pk_mul_f32 v[232:233], v[106:107], s[74:75] op_sel_hi:[1,0] neg_lo:[0,1] neg_hi:[0,1]
	v_pk_mul_f32 v[234:235], v[108:109], s[74:75] op_sel_hi:[1,0] neg_lo:[0,1] neg_hi:[0,1]
	v_sqrt_f32_e32 v188, v188
	v_sqrt_f32_e32 v189, v189
	v_sqrt_f32_e32 v190, v190
	v_sqrt_f32_e32 v191, v191
	v_sqrt_f32_e32 v192, v192
	v_sqrt_f32_e32 v193, v193
	v_sqrt_f32_e32 v194, v194
	v_sqrt_f32_e32 v195, v195
	v_exp_f32_e32 v228, v228
	v_exp_f32_e32 v229, v229
	v_exp_f32_e32 v230, v230
	v_exp_f32_e32 v231, v231
	v_exp_f32_e32 v232, v232
	v_exp_f32_e32 v233, v233
	v_exp_f32_e32 v234, v234
	v_exp_f32_e32 v235, v235
	s_waitcnt vmcnt(15)
	v_lshlrev_b32_e32 v196, 16, v148
	v_and_b32_e32 v197, 0xffff0000, v148
	v_lshlrev_b32_e32 v198, 16, v149
	v_and_b32_e32 v199, 0xffff0000, v149
	v_lshlrev_b32_e32 v200, 16, v150
	v_and_b32_e32 v201, 0xffff0000, v150
	v_lshlrev_b32_e32 v202, 16, v151
	v_and_b32_e32 v203, 0xffff0000, v151
	v_pk_mul_f32 v[188:189], v[188:189], v[180:181]
	v_pk_mul_f32 v[190:191], v[190:191], v[182:183]
	v_pk_mul_f32 v[192:193], v[192:193], v[184:185]
	v_pk_mul_f32 v[194:195], v[194:195], v[186:187]
	v_pk_mul_f32 v[188:189], v[188:189], v[196:197]
	v_pk_mul_f32 v[190:191], v[190:191], v[198:199]
	v_pk_mul_f32 v[192:193], v[192:193], v[200:201]
	v_pk_mul_f32 v[194:195], v[194:195], v[202:203]
	v_cvt_pk_bf16_f32 v212, v188, v189
	v_cvt_pk_bf16_f32 v213, v190, v191
	v_cvt_pk_bf16_f32 v214, v192, v193
	v_cvt_pk_bf16_f32 v215, v194, v195
	global_store_dwordx4 v173, v[212:215], s[10:11]
	v_pk_fma_f32 v[216:217], v[228:229], v[216:217], v[188:189]
	v_pk_fma_f32 v[218:219], v[230:231], v[218:219], v[190:191]
	v_pk_fma_f32 v[240:241], v[232:233], v[240:241], v[192:193]
	v_pk_fma_f32 v[242:243], v[234:235], v[242:243], v[194:195]
	v_pk_mul_f32 v[58:59], v[58:59], v[228:229]
	v_pk_mul_f32 v[60:61], v[60:61], v[230:231]
	v_pk_mul_f32 v[66:67], v[66:67], v[232:233]
	v_pk_mul_f32 v[68:69], v[68:69], v[234:235]
	v_pk_add_f32 v[204:205], v[204:205], v[114:115]
	v_pk_add_f32 v[206:207], v[206:207], v[116:117]
	v_pk_add_f32 v[220:221], v[220:221], v[106:107]
	v_pk_add_f32 v[222:223], v[222:223], v[108:109]
	v_fmac_f32_dpp v216, v216, v58 row_shr:1 row_mask:0xf bank_mask:0xf
	v_fmac_f32_dpp v217, v217, v59 row_shr:1 row_mask:0xf bank_mask:0xf
	v_fmac_f32_dpp v218, v218, v60 row_shr:1 row_mask:0xf bank_mask:0xf
	v_fmac_f32_dpp v219, v219, v61 row_shr:1 row_mask:0xf bank_mask:0xf
	v_fmac_f32_dpp v240, v240, v66 row_shr:1 row_mask:0xf bank_mask:0xf
	v_fmac_f32_dpp v241, v241, v67 row_shr:1 row_mask:0xf bank_mask:0xf
	v_fmac_f32_dpp v242, v242, v68 row_shr:1 row_mask:0xf bank_mask:0xf
	v_fmac_f32_dpp v243, v243, v69 row_shr:1 row_mask:0xf bank_mask:0xf
	v_mul_f32_dpp v58, v58, v58 row_shr:1 row_mask:0xf bank_mask:0xf
	v_mul_f32_dpp v59, v59, v59 row_shr:1 row_mask:0xf bank_mask:0xf
	v_mul_f32_dpp v60, v60, v60 row_shr:1 row_mask:0xf bank_mask:0xf
	v_mul_f32_dpp v61, v61, v61 row_shr:1 row_mask:0xf bank_mask:0xf
	v_mul_f32_dpp v66, v66, v66 row_shr:1 row_mask:0xf bank_mask:0xf
	v_mul_f32_dpp v67, v67, v67 row_shr:1 row_mask:0xf bank_mask:0xf
	v_mul_f32_dpp v68, v68, v68 row_shr:1 row_mask:0xf bank_mask:0xf
	v_mul_f32_dpp v69, v69, v69 row_shr:1 row_mask:0xf bank_mask:0xf
	v_add_f32_dpp v204, v204, v204 row_shr:1 row_mask:0xf bank_mask:0xf
	v_add_f32_dpp v205, v205, v205 row_shr:1 row_mask:0xf bank_mask:0xf
	v_add_f32_dpp v206, v206, v206 row_shr:1 row_mask:0xf bank_mask:0xf
	v_add_f32_dpp v207, v207, v207 row_shr:1 row_mask:0xf bank_mask:0xf
	v_add_f32_dpp v220, v220, v220 row_shr:1 row_mask:0xf bank_mask:0xf
	v_add_f32_dpp v221, v221, v221 row_shr:1 row_mask:0xf bank_mask:0xf
	v_add_f32_dpp v222, v222, v222 row_shr:1 row_mask:0xf bank_mask:0xf
	v_add_f32_dpp v223, v223, v223 row_shr:1 row_mask:0xf bank_mask:0xf
	v_fmac_f32_dpp v216, v216, v58 row_shr:2 row_mask:0xf bank_mask:0xf
	v_fmac_f32_dpp v217, v217, v59 row_shr:2 row_mask:0xf bank_mask:0xf
	v_fmac_f32_dpp v218, v218, v60 row_shr:2 row_mask:0xf bank_mask:0xf
	v_fmac_f32_dpp v219, v219, v61 row_shr:2 row_mask:0xf bank_mask:0xf
	v_fmac_f32_dpp v240, v240, v66 row_shr:2 row_mask:0xf bank_mask:0xf
	v_fmac_f32_dpp v241, v241, v67 row_shr:2 row_mask:0xf bank_mask:0xf
	v_fmac_f32_dpp v242, v242, v68 row_shr:2 row_mask:0xf bank_mask:0xf
	v_fmac_f32_dpp v243, v243, v69 row_shr:2 row_mask:0xf bank_mask:0xf
	v_mul_f32_dpp v58, v58, v58 row_shr:2 row_mask:0xf bank_mask:0xf
	v_mul_f32_dpp v59, v59, v59 row_shr:2 row_mask:0xf bank_mask:0xf
; __device__ __forceinline__ float bf_lo(unsigned w) { return __uint_as_float(w << 16); }
; __device__ __forceinline__ float bf_hi(unsigned w) { return __uint_as_float(w & 0xffff0000u); }
; __device__ __forceinline__ float fexp(float x) { return __builtin_amdgcn_exp2f(1.44269504f * x); }
;     __device__ __forceinline__ void operator()(AccMut acc, const Unit& u, int sw) const {
;     ...
;                     for (int jp = 0; jp < 2; ++jp) {
;                         const f32x2 z = (f32x2){acc[ai][1][m][n][2 * jp], acc[ai][1][m][n][2 * jp + 1]} * (-1.44269504f);
;                         f32x2 e; e.x = __builtin_amdgcn_exp2f(z.x); e.y = __builtin_amdgcn_exp2f(z.y); e = e + 1.0f;
;                         f32x2 ig; ig.x = __builtin_amdgcn_rcpf(e.x); ig.y = __builtin_amdgcn_rcpf(e.y);
;                         const f32x2 x2 = (f32x2){acc[ai][0][m][n][2 * jp], acc[ai][0][m][n][2 * jp + 1]} * 2.0f;
;                         f32x2 ser = x2 * (1.0f / 120.0f) + (1.0f / 24.0f); ser = ser * x2 + (1.0f / 6.0f); ser = ser * x2 + 0.5f; ser = ser * x2 + 1.0f; ser = ser * (-x2);
;                         f32x2 em = ser;
;                         if (__builtin_expect(__builtin_amdgcn_ballot_w64(x2.x <= -0.25f || x2.y <= -0.25f) != 0ull, 0)) {
;                             em.x = (x2.x > -0.25f) ? ser.x : (1.0f - fexp(x2.x)); em.y = (x2.y > -0.25f) ? ser.y : (1.0f - fexp(x2.y)); }
; __device__ __forceinline__ void scan1_phase(const bf16_t* LA, const bf16_t* BT, int sw, View vw) {
;     ...
;             for (int i = 0; i < 8; ++i) {
;                 const float l0 = bf_lo(lw[i].x), l1 = bf_hi(lw[i].x), l2 = bf_lo(lw[i].y), l3 = bf_hi(lw[i].y);
;                 S[0] += l0; S[1] += l1; S[2] += l2; S[3] += l3;
;                 Hc[0] = fexp(l0) * Hc[0] + bf_lo(bw[i].x); Hc[1] = fexp(l1) * Hc[1] + bf_hi(bw[i].x); Hc[2] = fexp(l2) * Hc[2] + bf_lo(bw[i].y); Hc[3] = fexp(l3) * Hc[3] + bf_hi(bw[i].y); }
;         }
;         *(f32x4*)(CP + (size_t)bq * E + 4 * quad) = (f32x4){S[0], S[1], S[2], S[3]};
;         *(f32x4*)(CH + (size_t)bq * E + 4 * quad) = (f32x4){Hc[0], Hc[1], Hc[2], Hc[3]};
	v_mul_f32_dpp v60, v60, v60 row_shr:2 row_mask:0xf bank_mask:0xf
	v_mul_f32_dpp v61, v61, v61 row_shr:2 row_mask:0xf bank_mask:0xf
	v_mul_f32_dpp v66, v66, v66 row_shr:2 row_mask:0xf bank_mask:0xf
	v_mul_f32_dpp v67, v67, v67 row_shr:2 row_mask:0xf bank_mask:0xf
	v_mul_f32_dpp v68, v68, v68 row_shr:2 row_mask:0xf bank_mask:0xf
	v_mul_f32_dpp v69, v69, v69 row_shr:2 row_mask:0xf bank_mask:0xf
	v_add_f32_dpp v204, v204, v204 row_shr:2 row_mask:0xf bank_mask:0xf
	v_add_f32_dpp v205, v205, v205 row_shr:2 row_mask:0xf bank_mask:0xf
	v_add_f32_dpp v206, v206, v206 row_shr:2 row_mask:0xf bank_mask:0xf
	v_add_f32_dpp v207, v207, v207 row_shr:2 row_mask:0xf bank_mask:0xf
	v_add_f32_dpp v220, v220, v220 row_shr:2 row_mask:0xf bank_mask:0xf
	v_add_f32_dpp v221, v221, v221 row_shr:2 row_mask:0xf bank_mask:0xf
	v_add_f32_dpp v222, v222, v222 row_shr:2 row_mask:0xf bank_mask:0xf
	v_add_f32_dpp v223, v223, v223 row_shr:2 row_mask:0xf bank_mask:0xf
	v_fmac_f32_dpp v216, v216, v58 row_shr:4 row_mask:0xf bank_mask:0xf
	v_fmac_f32_dpp v217, v217, v59 row_shr:4 row_mask:0xf bank_mask:0xf
	v_fmac_f32_dpp v218, v218, v60 row_shr:4 row_mask:0xf bank_mask:0xf
	v_fmac_f32_dpp v219, v219, v61 row_shr:4 row_mask:0xf bank_mask:0xf
	v_fmac_f32_dpp v240, v240, v66 row_shr:4 row_mask:0xf bank_mask:0xf
	v_fmac_f32_dpp v241, v241, v67 row_shr:4 row_mask:0xf bank_mask:0xf
	v_fmac_f32_dpp v242, v242, v68 row_shr:4 row_mask:0xf bank_mask:0xf
	v_fmac_f32_dpp v243, v243, v69 row_shr:4 row_mask:0xf bank_mask:0xf
	v_mul_f32_dpp v58, v58, v58 row_shr:4 row_mask:0xf bank_mask:0xf
	v_mul_f32_dpp v59, v59, v59 row_shr:4 row_mask:0xf bank_mask:0xf
	v_mul_f32_dpp v60, v60, v60 row_shr:4 row_mask:0xf bank_mask:0xf
	v_mul_f32_dpp v61, v61, v61 row_shr:4 row_mask:0xf bank_mask:0xf
	v_mul_f32_dpp v66, v66, v66 row_shr:4 row_mask:0xf bank_mask:0xf
	v_mul_f32_dpp v67, v67, v67 row_shr:4 row_mask:0xf bank_mask:0xf
	v_mul_f32_dpp v68, v68, v68 row_shr:4 row_mask:0xf bank_mask:0xf
	v_mul_f32_dpp v69, v69, v69 row_shr:4 row_mask:0xf bank_mask:0xf
	v_add_f32_dpp v204, v204, v204 row_shr:4 row_mask:0xf bank_mask:0xf
	v_add_f32_dpp v205, v205, v205 row_shr:4 row_mask:0xf bank_mask:0xf
	v_add_f32_dpp v206, v206, v206 row_shr:4 row_mask:0xf bank_mask:0xf
	v_add_f32_dpp v207, v207, v207 row_shr:4 row_mask:0xf bank_mask:0xf
	v_add_f32_dpp v220, v220, v220 row_shr:4 row_mask:0xf bank_mask:0xf
	v_add_f32_dpp v221, v221, v221 row_shr:4 row_mask:0xf bank_mask:0xf
	v_add_f32_dpp v222, v222, v222 row_shr:4 row_mask:0xf bank_mask:0xf
	v_add_f32_dpp v223, v223, v223 row_shr:4 row_mask:0xf bank_mask:0xf
	v_fmac_f32_dpp v216, v216, v58 row_shr:8 row_mask:0xf bank_mask:0xf
	v_fmac_f32_dpp v217, v217, v59 row_shr:8 row_mask:0xf bank_mask:0xf
	v_fmac_f32_dpp v218, v218, v60 row_shr:8 row_mask:0xf bank_mask:0xf
	v_fmac_f32_dpp v219, v219, v61 row_shr:8 row_mask:0xf bank_mask:0xf
	v_fmac_f32_dpp v240, v240, v66 row_shr:8 row_mask:0xf bank_mask:0xf
	v_fmac_f32_dpp v241, v241, v67 row_shr:8 row_mask:0xf bank_mask:0xf
	v_fmac_f32_dpp v242, v242, v68 row_shr:8 row_mask:0xf bank_mask:0xf
	v_fmac_f32_dpp v243, v243, v69 row_shr:8 row_mask:0xf bank_mask:0xf
	v_add_f32_dpp v204, v204, v204 row_shr:8 row_mask:0xf bank_mask:0xf
	v_add_f32_dpp v205, v205, v205 row_shr:8 row_mask:0xf bank_mask:0xf
	v_add_f32_dpp v206, v206, v206 row_shr:8 row_mask:0xf bank_mask:0xf
	v_add_f32_dpp v207, v207, v207 row_shr:8 row_mask:0xf bank_mask:0xf
	v_add_f32_dpp v220, v220, v220 row_shr:8 row_mask:0xf bank_mask:0xf
	v_add_f32_dpp v221, v221, v221 row_shr:8 row_mask:0xf bank_mask:0xf
	v_add_f32_dpp v222, v222, v222 row_shr:8 row_mask:0xf bank_mask:0xf
	v_add_f32_dpp v223, v223, v223 row_shr:8 row_mask:0xf bank_mask:0xf
	v_mbcnt_lo_u32_b32 v180, -1, 0
	v_mbcnt_hi_u32_b32 v180, -1, v180
	v_and_b32_e32 v180, 15, v180
	v_cmp_eq_u32_e32 vcc, 15, v180
	v_add_u32_e32 v181, 0x0, v239
	v_add_u32_e32 v182, 0x400000, v239
	s_mov_b64 exec, vcc
	global_store_dwordx4 v181, v[204:207], s[26:27]
	global_store_dwordx4 v181, v[220:223], s[26:27] offset:16
	global_store_dwordx4 v182, v[216:219], s[26:27]
	global_store_dwordx4 v182, v[240:243], s[26:27] offset:16
	s_mov_b64 exec, -1
	v_pk_mul_f32 v[180:181], v[26:27], s[74:75] op_sel_hi:[1,0]
	v_pk_mul_f32 v[182:183], v[28:29], s[74:75] op_sel_hi:[1,0]
	v_pk_mul_f32 v[184:185], v[30:31], s[74:75] op_sel_hi:[1,0]
	v_pk_mul_f32 v[186:187], v[32:33], s[74:75] op_sel_hi:[1,0]
	v_exp_f32_e32 v180, v180
	v_exp_f32_e32 v181, v181
	v_exp_f32_e32 v182, v182
	v_exp_f32_e32 v183, v183
	v_exp_f32_e32 v184, v184
	v_exp_f32_e32 v185, v185
	v_exp_f32_e32 v186, v186
	v_exp_f32_e32 v187, v187
	v_pk_fma_f32 v[188:189], v[110:111], s[24:25], v[236:237] op_sel_hi:[1,0,0]
	v_pk_fma_f32 v[190:191], v[112:113], s[24:25], v[236:237] op_sel_hi:[1,0,0]
	v_pk_fma_f32 v[192:193], v[102:103], s[24:25], v[236:237] op_sel_hi:[1,0,0]
	v_pk_fma_f32 v[194:195], v[104:105], s[24:25], v[236:237] op_sel_hi:[1,0,0]
	v_pk_add_f32 v[180:181], v[180:181], 1.0 op_sel_hi:[1,0]
	v_pk_add_f32 v[182:183], v[182:183], 1.0 op_sel_hi:[1,0]
	v_pk_add_f32 v[184:185], v[184:185], 1.0 op_sel_hi:[1,0]
	v_pk_add_f32 v[186:187], v[186:187], 1.0 op_sel_hi:[1,0]
	v_rcp_f32_e32 v180, v180
	v_rcp_f32_e32 v181, v181
	v_rcp_f32_e32 v182, v182
	v_rcp_f32_e32 v183, v183
	v_rcp_f32_e32 v184, v184
	v_rcp_f32_e32 v185, v185
	v_rcp_f32_e32 v186, v186
	v_rcp_f32_e32 v187, v187
	v_pk_fma_f32 v[188:189], v[110:111], v[188:189], s[22:23] op_sel_hi:[1,1,0]
	v_pk_fma_f32 v[190:191], v[112:113], v[190:191], s[22:23] op_sel_hi:[1,1,0]
	v_pk_fma_f32 v[192:193], v[102:103], v[192:193], s[22:23] op_sel_hi:[1,1,0]
	v_pk_fma_f32 v[194:195], v[104:105], v[194:195], s[22:23] op_sel_hi:[1,1,0]
;     __device__ __forceinline__ void operator()(AccMut acc, const Unit& u, int sw) const {
;     ...
;             for (int m = 0; m < 4; ++m) { const size_t off = (size_t)(row0 + ai * HALF + m * 16) * E + c0;
;                 const u32x4 xw = xnext;
;                 if (ai * 4 + m < 7) { const int ai2 = (ai * 4 + m + 1) >> 2, m2 = (ai * 4 + m + 1) & 3; xnext = *(const u32x4*)(XC + (size_t)(row0 + ai2 * HALF + m2 * 16) * E + c0); }
;                 float bt[8];
; #pragma unroll
;                 for (int n = 0; n < 2; ++n)
; #pragma unroll
;                     for (int jp = 0; jp < 2; ++jp) {
;                         const f32x2 z = (f32x2){acc[ai][1][m][n][2 * jp], acc[ai][1][m][n][2 * jp + 1]} * (-1.44269504f);
;                         f32x2 e; e.x = __builtin_amdgcn_exp2f(z.x); e.y = __builtin_amdgcn_exp2f(z.y); e = e + 1.0f;
;                         f32x2 ig; ig.x = __builtin_amdgcn_rcpf(e.x); ig.y = __builtin_amdgcn_rcpf(e.y);
;                         const f32x2 x2 = (f32x2){acc[ai][0][m][n][2 * jp], acc[ai][0][m][n][2 * jp + 1]} * 2.0f;
;                         f32x2 ser = x2 * (1.0f / 120.0f) + (1.0f / 24.0f); ser = ser * x2 + (1.0f / 6.0f); ser = ser * x2 + 0.5f; ser = ser * x2 + 1.0f; ser = ser * (-x2);
;                         f32x2 em = ser;
;                         if (__builtin_expect(__builtin_amdgcn_ballot_w64(x2.x <= -0.25f || x2.y <= -0.25f) != 0ull, 0)) {
;                             em.x = (x2.x > -0.25f) ? ser.x : (1.0f - fexp(x2.x)); em.y = (x2.y > -0.25f) ? ser.y : (1.0f - fexp(x2.y)); }
;                         const unsigned wv = xw[2 * n + jp];
;                         f32x2 sq; sq.x = __builtin_amdgcn_sqrtf(em.x); sq.y = __builtin_amdgcn_sqrtf(em.y);
;                         const f32x2 b2 = sq * ig * (f32x2){bf_lo(wv), bf_hi(wv)};
;                         bt[4 * n + 2 * jp] = b2.x; bt[4 * n + 2 * jp + 1] = b2.y; }
;                 u32x4 w; w.x = cvt_pk_bf16(bt[0], bt[1]); w.y = cvt_pk_bf16(bt[2], bt[3]); w.z = cvt_pk_bf16(bt[4], bt[5]); w.w = cvt_pk_bf16(bt[6], bt[7]);
;                 *(u32x4*)(BT + off) = w; }
; __device__ __forceinline__ void scan1_phase(const bf16_t* LA, const bf16_t* BT, int sw, View vw) {
;     ...
;                 const float l0 = bf_lo(lw[i].x), l1 = bf_hi(lw[i].x), l2 = bf_lo(lw[i].y), l3 = bf_hi(lw[i].y);
;                 S[0] += l0; S[1] += l1; S[2] += l2; S[3] += l3;
	v_pk_fma_f32 v[188:189], v[110:111], v[188:189], -2.0 op_sel_hi:[1,1,0]
	v_pk_fma_f32 v[190:191], v[112:113], v[190:191], -2.0 op_sel_hi:[1,1,0]
	v_pk_fma_f32 v[192:193], v[102:103], v[192:193], -2.0 op_sel_hi:[1,1,0]
	v_pk_fma_f32 v[194:195], v[104:105], v[194:195], -2.0 op_sel_hi:[1,1,0]
	v_pk_fma_f32 v[188:189], v[110:111], v[188:189], -2.0 op_sel_hi:[1,1,0]
	v_pk_fma_f32 v[190:191], v[112:113], v[190:191], -2.0 op_sel_hi:[1,1,0]
	v_pk_fma_f32 v[192:193], v[102:103], v[192:193], -2.0 op_sel_hi:[1,1,0]
	v_pk_fma_f32 v[194:195], v[104:105], v[194:195], -2.0 op_sel_hi:[1,1,0]
	v_pk_mul_f32 v[188:189], v[110:111], v[188:189]
	v_pk_mul_f32 v[190:191], v[112:113], v[190:191]
	v_pk_mul_f32 v[192:193], v[102:103], v[192:193]
	v_pk_mul_f32 v[194:195], v[104:105], v[194:195]
	v_pk_mul_f32 v[228:229], v[110:111], s[74:75] op_sel_hi:[1,0] neg_lo:[0,1] neg_hi:[0,1]
	v_pk_mul_f32 v[230:231], v[112:113], s[74:75] op_sel_hi:[1,0] neg_lo:[0,1] neg_hi:[0,1]
	v_pk_mul_f32 v[232:233], v[102:103], s[74:75] op_sel_hi:[1,0] neg_lo:[0,1] neg_hi:[0,1]
	v_pk_mul_f32 v[234:235], v[104:105], s[74:75] op_sel_hi:[1,0] neg_lo:[0,1] neg_hi:[0,1]
	v_sqrt_f32_e32 v188, v188
	v_sqrt_f32_e32 v189, v189
	v_sqrt_f32_e32 v190, v190
	v_sqrt_f32_e32 v191, v191
	v_sqrt_f32_e32 v192, v192
	v_sqrt_f32_e32 v193, v193
	v_sqrt_f32_e32 v194, v194
	v_sqrt_f32_e32 v195, v195
	v_exp_f32_e32 v26, v228
	v_exp_f32_e32 v27, v229
	v_exp_f32_e32 v28, v230
	v_exp_f32_e32 v29, v231
	v_exp_f32_e32 v30, v232
	v_exp_f32_e32 v31, v233
	v_exp_f32_e32 v32, v234
	v_exp_f32_e32 v33, v235
	s_waitcnt vmcnt(19)
	v_lshlrev_b32_e32 v196, 16, v152
	v_and_b32_e32 v197, 0xffff0000, v152
	v_lshlrev_b32_e32 v198, 16, v153
	v_and_b32_e32 v199, 0xffff0000, v153
	v_lshlrev_b32_e32 v200, 16, v154
	v_and_b32_e32 v201, 0xffff0000, v154
	v_lshlrev_b32_e32 v202, 16, v155
	v_and_b32_e32 v203, 0xffff0000, v155
	v_pk_mul_f32 v[188:189], v[188:189], v[180:181]
	v_pk_mul_f32 v[190:191], v[190:191], v[182:183]
	v_pk_mul_f32 v[192:193], v[192:193], v[184:185]
	v_pk_mul_f32 v[194:195], v[194:195], v[186:187]
	v_pk_mul_f32 v[216:217], v[188:189], v[196:197]
	v_pk_mul_f32 v[218:219], v[190:191], v[198:199]
	v_pk_mul_f32 v[240:241], v[192:193], v[200:201]
	v_pk_mul_f32 v[242:243], v[194:195], v[202:203]
	v_cvt_pk_bf16_f32 v208, v216, v217
	v_cvt_pk_bf16_f32 v209, v218, v219
	v_cvt_pk_bf16_f32 v210, v240, v241
	v_cvt_pk_bf16_f32 v211, v242, v243
	global_store_dwordx4 v176, v[208:211], s[10:11]
	v_pk_mul_f32 v[180:181], v[18:19], s[74:75] op_sel_hi:[1,0]
	v_pk_mul_f32 v[182:183], v[20:21], s[74:75] op_sel_hi:[1,0]
	v_pk_mul_f32 v[184:185], v[22:23], s[74:75] op_sel_hi:[1,0]
	v_pk_mul_f32 v[186:187], v[24:25], s[74:75] op_sel_hi:[1,0]
	v_exp_f32_e32 v180, v180
	v_exp_f32_e32 v181, v181
	v_exp_f32_e32 v182, v182
	v_exp_f32_e32 v183, v183
	v_exp_f32_e32 v184, v184
	v_exp_f32_e32 v185, v185
	v_exp_f32_e32 v186, v186
	v_exp_f32_e32 v187, v187
	v_pk_fma_f32 v[188:189], v[98:99], s[24:25], v[236:237] op_sel_hi:[1,0,0]
	v_pk_fma_f32 v[190:191], v[100:101], s[24:25], v[236:237] op_sel_hi:[1,0,0]
	v_pk_fma_f32 v[192:193], v[94:95], s[24:25], v[236:237] op_sel_hi:[1,0,0]
	v_pk_fma_f32 v[194:195], v[96:97], s[24:25], v[236:237] op_sel_hi:[1,0,0]
	v_pk_add_f32 v[180:181], v[180:181], 1.0 op_sel_hi:[1,0]
	v_pk_add_f32 v[182:183], v[182:183], 1.0 op_sel_hi:[1,0]
	v_pk_add_f32 v[184:185], v[184:185], 1.0 op_sel_hi:[1,0]
	v_pk_add_f32 v[186:187], v[186:187], 1.0 op_sel_hi:[1,0]
	v_rcp_f32_e32 v180, v180
	v_rcp_f32_e32 v181, v181
	v_rcp_f32_e32 v182, v182
	v_rcp_f32_e32 v183, v183
	v_rcp_f32_e32 v184, v184
	v_rcp_f32_e32 v185, v185
	v_rcp_f32_e32 v186, v186
	v_rcp_f32_e32 v187, v187
	v_pk_fma_f32 v[188:189], v[98:99], v[188:189], s[22:23] op_sel_hi:[1,1,0]
	v_pk_fma_f32 v[190:191], v[100:101], v[190:191], s[22:23] op_sel_hi:[1,1,0]
	v_pk_fma_f32 v[192:193], v[94:95], v[192:193], s[22:23] op_sel_hi:[1,1,0]
	v_pk_fma_f32 v[194:195], v[96:97], v[194:195], s[22:23] op_sel_hi:[1,1,0]
	v_pk_fma_f32 v[188:189], v[98:99], v[188:189], -2.0 op_sel_hi:[1,1,0]
	v_pk_fma_f32 v[190:191], v[100:101], v[190:191], -2.0 op_sel_hi:[1,1,0]
	v_pk_fma_f32 v[192:193], v[94:95], v[192:193], -2.0 op_sel_hi:[1,1,0]
	v_pk_fma_f32 v[194:195], v[96:97], v[194:195], -2.0 op_sel_hi:[1,1,0]
	v_pk_fma_f32 v[188:189], v[98:99], v[188:189], -2.0 op_sel_hi:[1,1,0]
	v_pk_fma_f32 v[190:191], v[100:101], v[190:191], -2.0 op_sel_hi:[1,1,0]
	v_pk_fma_f32 v[192:193], v[94:95], v[192:193], -2.0 op_sel_hi:[1,1,0]
	v_pk_fma_f32 v[194:195], v[96:97], v[194:195], -2.0 op_sel_hi:[1,1,0]
	v_pk_mul_f32 v[188:189], v[98:99], v[188:189]
	v_pk_mul_f32 v[190:191], v[100:101], v[190:191]
	v_pk_mul_f32 v[192:193], v[94:95], v[192:193]
	v_pk_mul_f32 v[194:195], v[96:97], v[194:195]
	v_pk_mul_f32 v[228:229], v[98:99], s[74:75] op_sel_hi:[1,0] neg_lo:[0,1] neg_hi:[0,1]
	v_pk_mul_f32 v[230:231], v[100:101], s[74:75] op_sel_hi:[1,0] neg_lo:[0,1] neg_hi:[0,1]
	v_pk_mul_f32 v[232:233], v[94:95], s[74:75] op_sel_hi:[1,0] neg_lo:[0,1] neg_hi:[0,1]
	v_pk_mul_f32 v[234:235], v[96:97], s[74:75] op_sel_hi:[1,0] neg_lo:[0,1] neg_hi:[0,1]
	v_sqrt_f32_e32 v188, v188
	v_sqrt_f32_e32 v189, v189
	v_sqrt_f32_e32 v190, v190
	v_sqrt_f32_e32 v191, v191
	v_sqrt_f32_e32 v192, v192
	v_sqrt_f32_e32 v193, v193
	v_sqrt_f32_e32 v194, v194
	v_sqrt_f32_e32 v195, v195
	v_exp_f32_e32 v228, v228
	v_exp_f32_e32 v229, v229
	v_exp_f32_e32 v230, v230
	v_exp_f32_e32 v231, v231
	v_exp_f32_e32 v232, v232
	v_exp_f32_e32 v233, v233
	v_exp_f32_e32 v234, v234
	v_exp_f32_e32 v235, v235
	s_waitcnt vmcnt(19)
;     __device__ __forceinline__ void operator()(AccMut acc, const Unit& u, int sw) const {
;     ...
;             for (int m = 0; m < 4; ++m) { const size_t off = (size_t)(row0 + ai * HALF + m * 16) * E + c0;
;                 const u32x4 xw = xnext;
;                 if (ai * 4 + m < 7) { const int ai2 = (ai * 4 + m + 1) >> 2, m2 = (ai * 4 + m + 1) & 3; xnext = *(const u32x4*)(XC + (size_t)(row0 + ai2 * HALF + m2 * 16) * E + c0); }
;                 float bt[8];
; #pragma unroll
;                 for (int n = 0; n < 2; ++n)
; #pragma unroll
;                     for (int jp = 0; jp < 2; ++jp) {
;                         const f32x2 z = (f32x2){acc[ai][1][m][n][2 * jp], acc[ai][1][m][n][2 * jp + 1]} * (-1.44269504f);
;                         f32x2 e; e.x = __builtin_amdgcn_exp2f(z.x); e.y = __builtin_amdgcn_exp2f(z.y); e = e + 1.0f;
;                         f32x2 ig; ig.x = __builtin_amdgcn_rcpf(e.x); ig.y = __builtin_amdgcn_rcpf(e.y);
;                         const f32x2 x2 = (f32x2){acc[ai][0][m][n][2 * jp], acc[ai][0][m][n][2 * jp + 1]} * 2.0f;
;                         f32x2 ser = x2 * (1.0f / 120.0f) + (1.0f / 24.0f); ser = ser * x2 + (1.0f / 6.0f); ser = ser * x2 + 0.5f; ser = ser * x2 + 1.0f; ser = ser * (-x2);
;                         f32x2 em = ser;
;                         if (__builtin_expect(__builtin_amdgcn_ballot_w64(x2.x <= -0.25f || x2.y <= -0.25f) != 0ull, 0)) {
;                             em.x = (x2.x > -0.25f) ? ser.x : (1.0f - fexp(x2.x)); em.y = (x2.y > -0.25f) ? ser.y : (1.0f - fexp(x2.y)); }
;                         const unsigned wv = xw[2 * n + jp];
;                         f32x2 sq; sq.x = __builtin_amdgcn_sqrtf(em.x); sq.y = __builtin_amdgcn_sqrtf(em.y);
;                         const f32x2 b2 = sq * ig * (f32x2){bf_lo(wv), bf_hi(wv)};
;                         bt[4 * n + 2 * jp] = b2.x; bt[4 * n + 2 * jp + 1] = b2.y; }
;                 u32x4 w; w.x = cvt_pk_bf16(bt[0], bt[1]); w.y = cvt_pk_bf16(bt[2], bt[3]); w.z = cvt_pk_bf16(bt[4], bt[5]); w.w = cvt_pk_bf16(bt[6], bt[7]);
;                 *(u32x4*)(BT + off) = w; }
; __device__ __forceinline__ void scan1_phase(const bf16_t* LA, const bf16_t* BT, int sw, View vw) {
;     ...
;                 const float l0 = bf_lo(lw[i].x), l1 = bf_hi(lw[i].x), l2 = bf_lo(lw[i].y), l3 = bf_hi(lw[i].y);
;                 S[0] += l0; S[1] += l1; S[2] += l2; S[3] += l3;
	v_lshlrev_b32_e32 v196, 16, v156
	v_and_b32_e32 v197, 0xffff0000, v156
	v_lshlrev_b32_e32 v198, 16, v157
	v_and_b32_e32 v199, 0xffff0000, v157
	v_lshlrev_b32_e32 v200, 16, v158
	v_and_b32_e32 v201, 0xffff0000, v158
	v_lshlrev_b32_e32 v202, 16, v159
	v_and_b32_e32 v203, 0xffff0000, v159
	v_pk_mul_f32 v[188:189], v[188:189], v[180:181]
	v_pk_mul_f32 v[190:191], v[190:191], v[182:183]
	v_pk_mul_f32 v[192:193], v[192:193], v[184:185]
	v_pk_mul_f32 v[194:195], v[194:195], v[186:187]
	v_pk_mul_f32 v[188:189], v[188:189], v[196:197]
	v_pk_mul_f32 v[190:191], v[190:191], v[198:199]
	v_pk_mul_f32 v[192:193], v[192:193], v[200:201]
	v_pk_mul_f32 v[194:195], v[194:195], v[202:203]
	v_cvt_pk_bf16_f32 v212, v188, v189
	v_cvt_pk_bf16_f32 v213, v190, v191
	v_cvt_pk_bf16_f32 v214, v192, v193
	v_cvt_pk_bf16_f32 v215, v194, v195
	global_store_dwordx4 v177, v[212:215], s[10:11]
	v_pk_fma_f32 v[216:217], v[228:229], v[216:217], v[188:189]
	v_pk_fma_f32 v[218:219], v[230:231], v[218:219], v[190:191]
	v_pk_fma_f32 v[240:241], v[232:233], v[240:241], v[192:193]
	v_pk_fma_f32 v[242:243], v[234:235], v[242:243], v[194:195]
	v_pk_mul_f32 v[26:27], v[26:27], v[228:229]
	v_pk_mul_f32 v[28:29], v[28:29], v[230:231]
	v_pk_mul_f32 v[30:31], v[30:31], v[232:233]
	v_pk_mul_f32 v[32:33], v[32:33], v[234:235]
	v_pk_add_f32 v[110:111], v[110:111], v[98:99]
	v_pk_add_f32 v[112:113], v[112:113], v[100:101]
	v_pk_add_f32 v[102:103], v[102:103], v[94:95]
	v_pk_add_f32 v[104:105], v[104:105], v[96:97]
	v_pk_mul_f32 v[180:181], v[10:11], s[74:75] op_sel_hi:[1,0]
	v_pk_mul_f32 v[182:183], v[12:13], s[74:75] op_sel_hi:[1,0]
	v_pk_mul_f32 v[184:185], v[14:15], s[74:75] op_sel_hi:[1,0]
	v_pk_mul_f32 v[186:187], v[16:17], s[74:75] op_sel_hi:[1,0]
	v_exp_f32_e32 v180, v180
	v_exp_f32_e32 v181, v181
	v_exp_f32_e32 v182, v182
	v_exp_f32_e32 v183, v183
	v_exp_f32_e32 v184, v184
	v_exp_f32_e32 v185, v185
	v_exp_f32_e32 v186, v186
	v_exp_f32_e32 v187, v187
	v_pk_fma_f32 v[188:189], v[90:91], s[24:25], v[236:237] op_sel_hi:[1,0,0]
	v_pk_fma_f32 v[190:191], v[92:93], s[24:25], v[236:237] op_sel_hi:[1,0,0]
	v_pk_fma_f32 v[192:193], v[86:87], s[24:25], v[236:237] op_sel_hi:[1,0,0]
	v_pk_fma_f32 v[194:195], v[88:89], s[24:25], v[236:237] op_sel_hi:[1,0,0]
	v_pk_add_f32 v[180:181], v[180:181], 1.0 op_sel_hi:[1,0]
	v_pk_add_f32 v[182:183], v[182:183], 1.0 op_sel_hi:[1,0]
	v_pk_add_f32 v[184:185], v[184:185], 1.0 op_sel_hi:[1,0]
	v_pk_add_f32 v[186:187], v[186:187], 1.0 op_sel_hi:[1,0]
	v_rcp_f32_e32 v180, v180
	v_rcp_f32_e32 v181, v181
	v_rcp_f32_e32 v182, v182
	v_rcp_f32_e32 v183, v183
	v_rcp_f32_e32 v184, v184
	v_rcp_f32_e32 v185, v185
	v_rcp_f32_e32 v186, v186
	v_rcp_f32_e32 v187, v187
	v_pk_fma_f32 v[188:189], v[90:91], v[188:189], s[22:23] op_sel_hi:[1,1,0]
	v_pk_fma_f32 v[190:191], v[92:93], v[190:191], s[22:23] op_sel_hi:[1,1,0]
	v_pk_fma_f32 v[192:193], v[86:87], v[192:193], s[22:23] op_sel_hi:[1,1,0]
	v_pk_fma_f32 v[194:195], v[88:89], v[194:195], s[22:23] op_sel_hi:[1,1,0]
	v_pk_fma_f32 v[188:189], v[90:91], v[188:189], -2.0 op_sel_hi:[1,1,0]
	v_pk_fma_f32 v[190:191], v[92:93], v[190:191], -2.0 op_sel_hi:[1,1,0]
	v_pk_fma_f32 v[192:193], v[86:87], v[192:193], -2.0 op_sel_hi:[1,1,0]
	v_pk_fma_f32 v[194:195], v[88:89], v[194:195], -2.0 op_sel_hi:[1,1,0]
	v_pk_fma_f32 v[188:189], v[90:91], v[188:189], -2.0 op_sel_hi:[1,1,0]
	v_pk_fma_f32 v[190:191], v[92:93], v[190:191], -2.0 op_sel_hi:[1,1,0]
	v_pk_fma_f32 v[192:193], v[86:87], v[192:193], -2.0 op_sel_hi:[1,1,0]
	v_pk_fma_f32 v[194:195], v[88:89], v[194:195], -2.0 op_sel_hi:[1,1,0]
	v_pk_mul_f32 v[188:189], v[90:91], v[188:189]
	v_pk_mul_f32 v[190:191], v[92:93], v[190:191]
	v_pk_mul_f32 v[192:193], v[86:87], v[192:193]
	v_pk_mul_f32 v[194:195], v[88:89], v[194:195]
	v_pk_mul_f32 v[228:229], v[90:91], s[74:75] op_sel_hi:[1,0] neg_lo:[0,1] neg_hi:[0,1]
	v_pk_mul_f32 v[230:231], v[92:93], s[74:75] op_sel_hi:[1,0] neg_lo:[0,1] neg_hi:[0,1]
	v_pk_mul_f32 v[232:233], v[86:87], s[74:75] op_sel_hi:[1,0] neg_lo:[0,1] neg_hi:[0,1]
	v_pk_mul_f32 v[234:235], v[88:89], s[74:75] op_sel_hi:[1,0] neg_lo:[0,1] neg_hi:[0,1]
	v_sqrt_f32_e32 v188, v188
	v_sqrt_f32_e32 v189, v189
	v_sqrt_f32_e32 v190, v190
	v_sqrt_f32_e32 v191, v191
	v_sqrt_f32_e32 v192, v192
	v_sqrt_f32_e32 v193, v193
	v_sqrt_f32_e32 v194, v194
	v_sqrt_f32_e32 v195, v195
	v_exp_f32_e32 v228, v228
	v_exp_f32_e32 v229, v229
	v_exp_f32_e32 v230, v230
	v_exp_f32_e32 v231, v231
	v_exp_f32_e32 v232, v232
	v_exp_f32_e32 v233, v233
	v_exp_f32_e32 v234, v234
	v_exp_f32_e32 v235, v235
	s_waitcnt vmcnt(19)
;     __device__ __forceinline__ void operator()(AccMut acc, const Unit& u, int sw) const {
;     ...
;             for (int m = 0; m < 4; ++m) { const size_t off = (size_t)(row0 + ai * HALF + m * 16) * E + c0;
;                 const u32x4 xw = xnext;
;                 if (ai * 4 + m < 7) { const int ai2 = (ai * 4 + m + 1) >> 2, m2 = (ai * 4 + m + 1) & 3; xnext = *(const u32x4*)(XC + (size_t)(row0 + ai2 * HALF + m2 * 16) * E + c0); }
;                 float bt[8];
; #pragma unroll
;                 for (int n = 0; n < 2; ++n)
; #pragma unroll
;                     for (int jp = 0; jp < 2; ++jp) {
;                         const f32x2 z = (f32x2){acc[ai][1][m][n][2 * jp], acc[ai][1][m][n][2 * jp + 1]} * (-1.44269504f);
;                         f32x2 e; e.x = __builtin_amdgcn_exp2f(z.x); e.y = __builtin_amdgcn_exp2f(z.y); e = e + 1.0f;
;                         f32x2 ig; ig.x = __builtin_amdgcn_rcpf(e.x); ig.y = __builtin_amdgcn_rcpf(e.y);
;                         const f32x2 x2 = (f32x2){acc[ai][0][m][n][2 * jp], acc[ai][0][m][n][2 * jp + 1]} * 2.0f;
;                         f32x2 ser = x2 * (1.0f / 120.0f) + (1.0f / 24.0f); ser = ser * x2 + (1.0f / 6.0f); ser = ser * x2 + 0.5f; ser = ser * x2 + 1.0f; ser = ser * (-x2);
;                         f32x2 em = ser;
;                         if (__builtin_expect(__builtin_amdgcn_ballot_w64(x2.x <= -0.25f || x2.y <= -0.25f) != 0ull, 0)) {
;                             em.x = (x2.x > -0.25f) ? ser.x : (1.0f - fexp(x2.x)); em.y = (x2.y > -0.25f) ? ser.y : (1.0f - fexp(x2.y)); }
;                         const unsigned wv = xw[2 * n + jp];
;                         f32x2 sq; sq.x = __builtin_amdgcn_sqrtf(em.x); sq.y = __builtin_amdgcn_sqrtf(em.y);
;                         const f32x2 b2 = sq * ig * (f32x2){bf_lo(wv), bf_hi(wv)};
;                         bt[4 * n + 2 * jp] = b2.x; bt[4 * n + 2 * jp + 1] = b2.y; }
;                 u32x4 w; w.x = cvt_pk_bf16(bt[0], bt[1]); w.y = cvt_pk_bf16(bt[2], bt[3]); w.z = cvt_pk_bf16(bt[4], bt[5]); w.w = cvt_pk_bf16(bt[6], bt[7]);
;                 *(u32x4*)(BT + off) = w; }
; __device__ __forceinline__ void scan1_phase(const bf16_t* LA, const bf16_t* BT, int sw, View vw) {
;     ...
;                 const float l0 = bf_lo(lw[i].x), l1 = bf_hi(lw[i].x), l2 = bf_lo(lw[i].y), l3 = bf_hi(lw[i].y);
;                 S[0] += l0; S[1] += l1; S[2] += l2; S[3] += l3;
	v_lshlrev_b32_e32 v196, 16, v160
	v_and_b32_e32 v197, 0xffff0000, v160
	v_lshlrev_b32_e32 v198, 16, v161
	v_and_b32_e32 v199, 0xffff0000, v161
	v_lshlrev_b32_e32 v200, 16, v162
	v_and_b32_e32 v201, 0xffff0000, v162
	v_lshlrev_b32_e32 v202, 16, v163
	v_and_b32_e32 v203, 0xffff0000, v163
	v_pk_mul_f32 v[188:189], v[188:189], v[180:181]
	v_pk_mul_f32 v[190:191], v[190:191], v[182:183]
	v_pk_mul_f32 v[192:193], v[192:193], v[184:185]
	v_pk_mul_f32 v[194:195], v[194:195], v[186:187]
	v_pk_mul_f32 v[188:189], v[188:189], v[196:197]
	v_pk_mul_f32 v[190:191], v[190:191], v[198:199]
	v_pk_mul_f32 v[192:193], v[192:193], v[200:201]
	v_pk_mul_f32 v[194:195], v[194:195], v[202:203]
	v_cvt_pk_bf16_f32 v208, v188, v189
	v_cvt_pk_bf16_f32 v209, v190, v191
	v_cvt_pk_bf16_f32 v210, v192, v193
	v_cvt_pk_bf16_f32 v211, v194, v195
	global_store_dwordx4 v178, v[208:211], s[10:11]
	v_pk_fma_f32 v[216:217], v[228:229], v[216:217], v[188:189]
	v_pk_fma_f32 v[218:219], v[230:231], v[218:219], v[190:191]
	v_pk_fma_f32 v[240:241], v[232:233], v[240:241], v[192:193]
	v_pk_fma_f32 v[242:243], v[234:235], v[242:243], v[194:195]
	v_pk_mul_f32 v[26:27], v[26:27], v[228:229]
	v_pk_mul_f32 v[28:29], v[28:29], v[230:231]
	v_pk_mul_f32 v[30:31], v[30:31], v[232:233]
	v_pk_mul_f32 v[32:33], v[32:33], v[234:235]
	v_pk_add_f32 v[110:111], v[110:111], v[90:91]
	v_pk_add_f32 v[112:113], v[112:113], v[92:93]
	v_pk_add_f32 v[102:103], v[102:103], v[86:87]
	v_pk_add_f32 v[104:105], v[104:105], v[88:89]
	v_pk_mul_f32 v[180:181], v[2:3], s[74:75] op_sel_hi:[1,0]
	v_pk_mul_f32 v[182:183], v[4:5], s[74:75] op_sel_hi:[1,0]
	v_pk_mul_f32 v[184:185], v[6:7], s[74:75] op_sel_hi:[1,0]
	v_pk_mul_f32 v[186:187], v[8:9], s[74:75] op_sel_hi:[1,0]
	v_exp_f32_e32 v180, v180
	v_exp_f32_e32 v181, v181
	v_exp_f32_e32 v182, v182
	v_exp_f32_e32 v183, v183
	v_exp_f32_e32 v184, v184
	v_exp_f32_e32 v185, v185
	v_exp_f32_e32 v186, v186
	v_exp_f32_e32 v187, v187
	v_pk_fma_f32 v[188:189], v[74:75], s[24:25], v[236:237] op_sel_hi:[1,0,0]
	v_pk_fma_f32 v[190:191], v[76:77], s[24:25], v[236:237] op_sel_hi:[1,0,0]
	v_pk_fma_f32 v[192:193], v[70:71], s[24:25], v[236:237] op_sel_hi:[1,0,0]
	v_pk_fma_f32 v[194:195], v[72:73], s[24:25], v[236:237] op_sel_hi:[1,0,0]
	v_pk_add_f32 v[180:181], v[180:181], 1.0 op_sel_hi:[1,0]
	v_pk_add_f32 v[182:183], v[182:183], 1.0 op_sel_hi:[1,0]
	v_pk_add_f32 v[184:185], v[184:185], 1.0 op_sel_hi:[1,0]
	v_pk_add_f32 v[186:187], v[186:187], 1.0 op_sel_hi:[1,0]
	v_rcp_f32_e32 v180, v180
	v_rcp_f32_e32 v181, v181
	v_rcp_f32_e32 v182, v182
	v_rcp_f32_e32 v183, v183
	v_rcp_f32_e32 v184, v184
	v_rcp_f32_e32 v185, v185
	v_rcp_f32_e32 v186, v186
	v_rcp_f32_e32 v187, v187
	v_pk_fma_f32 v[188:189], v[74:75], v[188:189], s[22:23] op_sel_hi:[1,1,0]
	v_pk_fma_f32 v[190:191], v[76:77], v[190:191], s[22:23] op_sel_hi:[1,1,0]
	v_pk_fma_f32 v[192:193], v[70:71], v[192:193], s[22:23] op_sel_hi:[1,1,0]
	v_pk_fma_f32 v[194:195], v[72:73], v[194:195], s[22:23] op_sel_hi:[1,1,0]
	v_pk_fma_f32 v[188:189], v[74:75], v[188:189], -2.0 op_sel_hi:[1,1,0]
	v_pk_fma_f32 v[190:191], v[76:77], v[190:191], -2.0 op_sel_hi:[1,1,0]
	v_pk_fma_f32 v[192:193], v[70:71], v[192:193], -2.0 op_sel_hi:[1,1,0]
	v_pk_fma_f32 v[194:195], v[72:73], v[194:195], -2.0 op_sel_hi:[1,1,0]
	v_pk_fma_f32 v[188:189], v[74:75], v[188:189], -2.0 op_sel_hi:[1,1,0]
	v_pk_fma_f32 v[190:191], v[76:77], v[190:191], -2.0 op_sel_hi:[1,1,0]
	v_pk_fma_f32 v[192:193], v[70:71], v[192:193], -2.0 op_sel_hi:[1,1,0]
	v_pk_fma_f32 v[194:195], v[72:73], v[194:195], -2.0 op_sel_hi:[1,1,0]
	v_pk_mul_f32 v[188:189], v[74:75], v[188:189]
	v_pk_mul_f32 v[190:191], v[76:77], v[190:191]
	v_pk_mul_f32 v[192:193], v[70:71], v[192:193]
	v_pk_mul_f32 v[194:195], v[72:73], v[194:195]
	v_pk_mul_f32 v[228:229], v[74:75], s[74:75] op_sel_hi:[1,0] neg_lo:[0,1] neg_hi:[0,1]
	v_pk_mul_f32 v[230:231], v[76:77], s[74:75] op_sel_hi:[1,0] neg_lo:[0,1] neg_hi:[0,1]
	v_pk_mul_f32 v[232:233], v[70:71], s[74:75] op_sel_hi:[1,0] neg_lo:[0,1] neg_hi:[0,1]
	v_pk_mul_f32 v[234:235], v[72:73], s[74:75] op_sel_hi:[1,0] neg_lo:[0,1] neg_hi:[0,1]
	v_sqrt_f32_e32 v188, v188
	v_sqrt_f32_e32 v189, v189
	v_sqrt_f32_e32 v190, v190
	v_sqrt_f32_e32 v191, v191
	v_sqrt_f32_e32 v192, v192
	v_sqrt_f32_e32 v193, v193
	v_sqrt_f32_e32 v194, v194
	v_sqrt_f32_e32 v195, v195
	v_exp_f32_e32 v228, v228
	v_exp_f32_e32 v229, v229
	v_exp_f32_e32 v230, v230
	v_exp_f32_e32 v231, v231
	v_exp_f32_e32 v232, v232
	v_exp_f32_e32 v233, v233
	v_exp_f32_e32 v234, v234
	v_exp_f32_e32 v235, v235
	s_waitcnt vmcnt(19)
;     __device__ __forceinline__ void operator()(AccMut acc, const Unit& u, int sw) const {
;     ...
;             for (int m = 0; m < 4; ++m) { const size_t off = (size_t)(row0 + ai * HALF + m * 16) * E + c0;
;                 const u32x4 xw = xnext;
;                 if (ai * 4 + m < 7) { const int ai2 = (ai * 4 + m + 1) >> 2, m2 = (ai * 4 + m + 1) & 3; xnext = *(const u32x4*)(XC + (size_t)(row0 + ai2 * HALF + m2 * 16) * E + c0); }
;                 float bt[8];
; #pragma unroll
;                 for (int n = 0; n < 2; ++n)
; #pragma unroll
;                     for (int jp = 0; jp < 2; ++jp) {
;                         const f32x2 z = (f32x2){acc[ai][1][m][n][2 * jp], acc[ai][1][m][n][2 * jp + 1]} * (-1.44269504f);
;                         f32x2 e; e.x = __builtin_amdgcn_exp2f(z.x); e.y = __builtin_amdgcn_exp2f(z.y); e = e + 1.0f;
;                         f32x2 ig; ig.x = __builtin_amdgcn_rcpf(e.x); ig.y = __builtin_amdgcn_rcpf(e.y);
;                         const f32x2 x2 = (f32x2){acc[ai][0][m][n][2 * jp], acc[ai][0][m][n][2 * jp + 1]} * 2.0f;
;                         f32x2 ser = x2 * (1.0f / 120.0f) + (1.0f / 24.0f); ser = ser * x2 + (1.0f / 6.0f); ser = ser * x2 + 0.5f; ser = ser * x2 + 1.0f; ser = ser * (-x2);
;                         f32x2 em = ser;
;                         if (__builtin_expect(__builtin_amdgcn_ballot_w64(x2.x <= -0.25f || x2.y <= -0.25f) != 0ull, 0)) {
;                             em.x = (x2.x > -0.25f) ? ser.x : (1.0f - fexp(x2.x)); em.y = (x2.y > -0.25f) ? ser.y : (1.0f - fexp(x2.y)); }
;                         const unsigned wv = xw[2 * n + jp];
;                         f32x2 sq; sq.x = __builtin_amdgcn_sqrtf(em.x); sq.y = __builtin_amdgcn_sqrtf(em.y);
;                         const f32x2 b2 = sq * ig * (f32x2){bf_lo(wv), bf_hi(wv)};
;                         bt[4 * n + 2 * jp] = b2.x; bt[4 * n + 2 * jp + 1] = b2.y; }
;                 u32x4 w; w.x = cvt_pk_bf16(bt[0], bt[1]); w.y = cvt_pk_bf16(bt[2], bt[3]); w.z = cvt_pk_bf16(bt[4], bt[5]); w.w = cvt_pk_bf16(bt[6], bt[7]);
;                 *(u32x4*)(BT + off) = w; }
; __device__ __forceinline__ void scan1_phase(const bf16_t* LA, const bf16_t* BT, int sw, View vw) {
;     ...
;             for (int i = 0; i < 8; ++i) {
;                 const float l0 = bf_lo(lw[i].x), l1 = bf_hi(lw[i].x), l2 = bf_lo(lw[i].y), l3 = bf_hi(lw[i].y);
	v_lshlrev_b32_e32 v196, 16, v164
	v_and_b32_e32 v197, 0xffff0000, v164
	v_lshlrev_b32_e32 v198, 16, v165
	v_and_b32_e32 v199, 0xffff0000, v165
	v_lshlrev_b32_e32 v200, 16, v166
	v_and_b32_e32 v201, 0xffff0000, v166
	v_lshlrev_b32_e32 v202, 16, v167
	v_and_b32_e32 v203, 0xffff0000, v167
	v_pk_mul_f32 v[188:189], v[188:189], v[180:181]
	v_pk_mul_f32 v[190:191], v[190:191], v[182:183]
	v_pk_mul_f32 v[192:193], v[192:193], v[184:185]
	v_pk_mul_f32 v[194:195], v[194:195], v[186:187]
	v_pk_mul_f32 v[188:189], v[188:189], v[196:197]
	v_pk_mul_f32 v[190:191], v[190:191], v[198:199]
	v_pk_mul_f32 v[192:193], v[192:193], v[200:201]
	v_pk_mul_f32 v[194:195], v[194:195], v[202:203]
	v_cvt_pk_bf16_f32 v212, v188, v189
	v_cvt_pk_bf16_f32 v213, v190, v191
	v_cvt_pk_bf16_f32 v214, v192, v193
	v_cvt_pk_bf16_f32 v215, v194, v195
	global_store_dwordx4 v179, v[212:215], s[10:11]
	v_pk_fma_f32 v[216:217], v[228:229], v[216:217], v[188:189]
	v_pk_fma_f32 v[218:219], v[230:231], v[218:219], v[190:191]
	v_pk_fma_f32 v[240:241], v[232:233], v[240:241], v[192:193]
	v_pk_fma_f32 v[242:243], v[234:235], v[242:243], v[194:195]
	v_pk_mul_f32 v[26:27], v[26:27], v[228:229]
	v_pk_mul_f32 v[28:29], v[28:29], v[230:231]
	v_pk_mul_f32 v[30:31], v[30:31], v[232:233]
	v_pk_mul_f32 v[32:33], v[32:33], v[234:235]
	v_pk_add_f32 v[110:111], v[110:111], v[74:75]
	v_pk_add_f32 v[112:113], v[112:113], v[76:77]
	v_pk_add_f32 v[102:103], v[102:103], v[70:71]
	v_pk_add_f32 v[104:105], v[104:105], v[72:73]
	v_fmac_f32_dpp v216, v216, v26 row_shr:1 row_mask:0xf bank_mask:0xf
	v_fmac_f32_dpp v217, v217, v27 row_shr:1 row_mask:0xf bank_mask:0xf
	v_fmac_f32_dpp v218, v218, v28 row_shr:1 row_mask:0xf bank_mask:0xf
	v_fmac_f32_dpp v219, v219, v29 row_shr:1 row_mask:0xf bank_mask:0xf
	v_fmac_f32_dpp v240, v240, v30 row_shr:1 row_mask:0xf bank_mask:0xf
	v_fmac_f32_dpp v241, v241, v31 row_shr:1 row_mask:0xf bank_mask:0xf
	v_fmac_f32_dpp v242, v242, v32 row_shr:1 row_mask:0xf bank_mask:0xf
	v_fmac_f32_dpp v243, v243, v33 row_shr:1 row_mask:0xf bank_mask:0xf
	v_mul_f32_dpp v26, v26, v26 row_shr:1 row_mask:0xf bank_mask:0xf
	v_mul_f32_dpp v27, v27, v27 row_shr:1 row_mask:0xf bank_mask:0xf
	v_mul_f32_dpp v28, v28, v28 row_shr:1 row_mask:0xf bank_mask:0xf
	v_mul_f32_dpp v29, v29, v29 row_shr:1 row_mask:0xf bank_mask:0xf
	v_mul_f32_dpp v30, v30, v30 row_shr:1 row_mask:0xf bank_mask:0xf
	v_mul_f32_dpp v31, v31, v31 row_shr:1 row_mask:0xf bank_mask:0xf
	v_mul_f32_dpp v32, v32, v32 row_shr:1 row_mask:0xf bank_mask:0xf
	v_mul_f32_dpp v33, v33, v33 row_shr:1 row_mask:0xf bank_mask:0xf
	v_add_f32_dpp v110, v110, v110 row_shr:1 row_mask:0xf bank_mask:0xf
	v_add_f32_dpp v111, v111, v111 row_shr:1 row_mask:0xf bank_mask:0xf
	v_add_f32_dpp v112, v112, v112 row_shr:1 row_mask:0xf bank_mask:0xf
	v_add_f32_dpp v113, v113, v113 row_shr:1 row_mask:0xf bank_mask:0xf
	v_add_f32_dpp v102, v102, v102 row_shr:1 row_mask:0xf bank_mask:0xf
	v_add_f32_dpp v103, v103, v103 row_shr:1 row_mask:0xf bank_mask:0xf
	v_add_f32_dpp v104, v104, v104 row_shr:1 row_mask:0xf bank_mask:0xf
	v_add_f32_dpp v105, v105, v105 row_shr:1 row_mask:0xf bank_mask:0xf
	v_fmac_f32_dpp v216, v216, v26 row_shr:2 row_mask:0xf bank_mask:0xf
	v_fmac_f32_dpp v217, v217, v27 row_shr:2 row_mask:0xf bank_mask:0xf
	v_fmac_f32_dpp v218, v218, v28 row_shr:2 row_mask:0xf bank_mask:0xf
	v_fmac_f32_dpp v219, v219, v29 row_shr:2 row_mask:0xf bank_mask:0xf
	v_fmac_f32_dpp v240, v240, v30 row_shr:2 row_mask:0xf bank_mask:0xf
	v_fmac_f32_dpp v241, v241, v31 row_shr:2 row_mask:0xf bank_mask:0xf
	v_fmac_f32_dpp v242, v242, v32 row_shr:2 row_mask:0xf bank_mask:0xf
	v_fmac_f32_dpp v243, v243, v33 row_shr:2 row_mask:0xf bank_mask:0xf
	v_mul_f32_dpp v26, v26, v26 row_shr:2 row_mask:0xf bank_mask:0xf
	v_mul_f32_dpp v27, v27, v27 row_shr:2 row_mask:0xf bank_mask:0xf
	v_mul_f32_dpp v28, v28, v28 row_shr:2 row_mask:0xf bank_mask:0xf
	v_mul_f32_dpp v29, v29, v29 row_shr:2 row_mask:0xf bank_mask:0xf
	v_mul_f32_dpp v30, v30, v30 row_shr:2 row_mask:0xf bank_mask:0xf
; __device__ __forceinline__ float bf_lo(unsigned w) { return __uint_as_float(w << 16); }
; __device__ __forceinline__ float bf_hi(unsigned w) { return __uint_as_float(w & 0xffff0000u); }
; __device__ __forceinline__ float fexp(float x) { return __builtin_amdgcn_exp2f(1.44269504f * x); }
; __device__ __forceinline__ void scan1_phase(const bf16_t* LA, const bf16_t* BT, int sw, View vw) {
;     ...
;             for (int i = 0; i < 8; ++i) {
;                 const float l0 = bf_lo(lw[i].x), l1 = bf_hi(lw[i].x), l2 = bf_lo(lw[i].y), l3 = bf_hi(lw[i].y);
;                 S[0] += l0; S[1] += l1; S[2] += l2; S[3] += l3;
;                 Hc[0] = fexp(l0) * Hc[0] + bf_lo(bw[i].x); Hc[1] = fexp(l1) * Hc[1] + bf_hi(bw[i].x); Hc[2] = fexp(l2) * Hc[2] + bf_lo(bw[i].y); Hc[3] = fexp(l3) * Hc[3] + bf_hi(bw[i].y); }
;         }
;         *(f32x4*)(CP + (size_t)bq * E + 4 * quad) = (f32x4){S[0], S[1], S[2], S[3]};
;         *(f32x4*)(CH + (size_t)bq * E + 4 * quad) = (f32x4){Hc[0], Hc[1], Hc[2], Hc[3]};
	v_mul_f32_dpp v31, v31, v31 row_shr:2 row_mask:0xf bank_mask:0xf
	v_mul_f32_dpp v32, v32, v32 row_shr:2 row_mask:0xf bank_mask:0xf
	v_mul_f32_dpp v33, v33, v33 row_shr:2 row_mask:0xf bank_mask:0xf
	v_add_f32_dpp v110, v110, v110 row_shr:2 row_mask:0xf bank_mask:0xf
	v_add_f32_dpp v111, v111, v111 row_shr:2 row_mask:0xf bank_mask:0xf
	v_add_f32_dpp v112, v112, v112 row_shr:2 row_mask:0xf bank_mask:0xf
	v_add_f32_dpp v113, v113, v113 row_shr:2 row_mask:0xf bank_mask:0xf
	v_add_f32_dpp v102, v102, v102 row_shr:2 row_mask:0xf bank_mask:0xf
	v_add_f32_dpp v103, v103, v103 row_shr:2 row_mask:0xf bank_mask:0xf
	v_add_f32_dpp v104, v104, v104 row_shr:2 row_mask:0xf bank_mask:0xf
	v_add_f32_dpp v105, v105, v105 row_shr:2 row_mask:0xf bank_mask:0xf
	v_fmac_f32_dpp v216, v216, v26 row_shr:4 row_mask:0xf bank_mask:0xf
	v_fmac_f32_dpp v217, v217, v27 row_shr:4 row_mask:0xf bank_mask:0xf
	v_fmac_f32_dpp v218, v218, v28 row_shr:4 row_mask:0xf bank_mask:0xf
	v_fmac_f32_dpp v219, v219, v29 row_shr:4 row_mask:0xf bank_mask:0xf
	v_fmac_f32_dpp v240, v240, v30 row_shr:4 row_mask:0xf bank_mask:0xf
	v_fmac_f32_dpp v241, v241, v31 row_shr:4 row_mask:0xf bank_mask:0xf
	v_fmac_f32_dpp v242, v242, v32 row_shr:4 row_mask:0xf bank_mask:0xf
	v_fmac_f32_dpp v243, v243, v33 row_shr:4 row_mask:0xf bank_mask:0xf
	v_mul_f32_dpp v26, v26, v26 row_shr:4 row_mask:0xf bank_mask:0xf
	v_mul_f32_dpp v27, v27, v27 row_shr:4 row_mask:0xf bank_mask:0xf
	v_mul_f32_dpp v28, v28, v28 row_shr:4 row_mask:0xf bank_mask:0xf
	v_mul_f32_dpp v29, v29, v29 row_shr:4 row_mask:0xf bank_mask:0xf
	v_mul_f32_dpp v30, v30, v30 row_shr:4 row_mask:0xf bank_mask:0xf
	v_mul_f32_dpp v31, v31, v31 row_shr:4 row_mask:0xf bank_mask:0xf
	v_mul_f32_dpp v32, v32, v32 row_shr:4 row_mask:0xf bank_mask:0xf
	v_mul_f32_dpp v33, v33, v33 row_shr:4 row_mask:0xf bank_mask:0xf
	v_add_f32_dpp v110, v110, v110 row_shr:4 row_mask:0xf bank_mask:0xf
	v_add_f32_dpp v111, v111, v111 row_shr:4 row_mask:0xf bank_mask:0xf
	v_add_f32_dpp v112, v112, v112 row_shr:4 row_mask:0xf bank_mask:0xf
	v_add_f32_dpp v113, v113, v113 row_shr:4 row_mask:0xf bank_mask:0xf
	v_add_f32_dpp v102, v102, v102 row_shr:4 row_mask:0xf bank_mask:0xf
	v_add_f32_dpp v103, v103, v103 row_shr:4 row_mask:0xf bank_mask:0xf
	v_add_f32_dpp v104, v104, v104 row_shr:4 row_mask:0xf bank_mask:0xf
	v_add_f32_dpp v105, v105, v105 row_shr:4 row_mask:0xf bank_mask:0xf
	v_fmac_f32_dpp v216, v216, v26 row_shr:8 row_mask:0xf bank_mask:0xf
	v_fmac_f32_dpp v217, v217, v27 row_shr:8 row_mask:0xf bank_mask:0xf
	v_fmac_f32_dpp v218, v218, v28 row_shr:8 row_mask:0xf bank_mask:0xf
	v_fmac_f32_dpp v219, v219, v29 row_shr:8 row_mask:0xf bank_mask:0xf
	v_fmac_f32_dpp v240, v240, v30 row_shr:8 row_mask:0xf bank_mask:0xf
	v_fmac_f32_dpp v241, v241, v31 row_shr:8 row_mask:0xf bank_mask:0xf
	v_fmac_f32_dpp v242, v242, v32 row_shr:8 row_mask:0xf bank_mask:0xf
	v_fmac_f32_dpp v243, v243, v33 row_shr:8 row_mask:0xf bank_mask:0xf
	v_add_f32_dpp v110, v110, v110 row_shr:8 row_mask:0xf bank_mask:0xf
	v_add_f32_dpp v111, v111, v111 row_shr:8 row_mask:0xf bank_mask:0xf
	v_add_f32_dpp v112, v112, v112 row_shr:8 row_mask:0xf bank_mask:0xf
	v_add_f32_dpp v113, v113, v113 row_shr:8 row_mask:0xf bank_mask:0xf
	v_add_f32_dpp v102, v102, v102 row_shr:8 row_mask:0xf bank_mask:0xf
	v_add_f32_dpp v103, v103, v103 row_shr:8 row_mask:0xf bank_mask:0xf
	v_add_f32_dpp v104, v104, v104 row_shr:8 row_mask:0xf bank_mask:0xf
	v_add_f32_dpp v105, v105, v105 row_shr:8 row_mask:0xf bank_mask:0xf
	v_mbcnt_lo_u32_b32 v180, -1, 0
	v_mbcnt_hi_u32_b32 v180, -1, v180
	v_and_b32_e32 v180, 15, v180
	v_cmp_eq_u32_e32 vcc, 15, v180
	v_add_u32_e32 v181, 0x4000, v239
	v_add_u32_e32 v182, 0x404000, v239
	s_mov_b64 exec, vcc
	global_store_dwordx4 v181, v[110:113], s[26:27]
	global_store_dwordx4 v181, v[102:105], s[26:27] offset:16
	global_store_dwordx4 v182, v[216:219], s[26:27]
	global_store_dwordx4 v182, v[240:243], s[26:27] offset:16
	s_mov_b64 exec, -1

; __device__ __forceinline__ float bf_lo(unsigned w) { return __uint_as_float(w << 16); }
; __device__ __forceinline__ float bf_hi(unsigned w) { return __uint_as_float(w & 0xffff0000u); }
; __device__ __forceinline__ float fexp(float x) { return __builtin_amdgcn_exp2f(1.44269504f * x); }
;     __device__ __forceinline__ void operator()(AccMut acc, const Unit& u, int sw) const {
;     ...
;                 if (ai * 4 + m < 7) { const int ai2 = (ai * 4 + m + 1) >> 2, m2 = (ai * 4 + m + 1) & 3; xnext = *(const u32x4*)(XC + (size_t)(row0 + ai2 * HALF + m2 * 16) * E + c0); }
;                 float bt[8];
; #pragma unroll
;                 for (int n = 0; n < 2; ++n)
; #pragma unroll
;                     for (int jp = 0; jp < 2; ++jp) {
;                         const f32x2 z = (f32x2){acc[ai][1][m][n][2 * jp], acc[ai][1][m][n][2 * jp + 1]} * (-1.44269504f);
;                         f32x2 e; e.x = __builtin_amdgcn_exp2f(z.x); e.y = __builtin_amdgcn_exp2f(z.y); e = e + 1.0f;
;                         f32x2 ig; ig.x = __builtin_amdgcn_rcpf(e.x); ig.y = __builtin_amdgcn_rcpf(e.y);
;                         const f32x2 x2 = (f32x2){acc[ai][0][m][n][2 * jp], acc[ai][0][m][n][2 * jp + 1]} * 2.0f;
;                         f32x2 ser = x2 * (1.0f / 120.0f) + (1.0f / 24.0f); ser = ser * x2 + (1.0f / 6.0f); ser = ser * x2 + 0.5f; ser = ser * x2 + 1.0f; ser = ser * (-x2);
;                         f32x2 em = ser;
;                         if (__builtin_expect(__builtin_amdgcn_ballot_w64(x2.x <= -0.25f || x2.y <= -0.25f) != 0ull, 0)) {
;                             em.x = (x2.x > -0.25f) ? ser.x : (1.0f - fexp(x2.x)); em.y = (x2.y > -0.25f) ? ser.y : (1.0f - fexp(x2.y)); }
;                         const unsigned wv = xw[2 * n + jp];
;                         f32x2 sq; sq.x = __builtin_amdgcn_sqrtf(em.x); sq.y = __builtin_amdgcn_sqrtf(em.y);
; __device__ __forceinline__ void scan1_phase(const bf16_t* LA, const bf16_t* BT, int sw, View vw) {
;     ...
;             for (int i = 0; i < 8; ++i) {
;                 const float l0 = bf_lo(lw[i].x), l1 = bf_hi(lw[i].x), l2 = bf_lo(lw[i].y), l3 = bf_hi(lw[i].y);
;                 S[0] += l0; S[1] += l1; S[2] += l2; S[3] += l3;
;                 Hc[0] = fexp(l0) * Hc[0] + bf_lo(bw[i].x); Hc[1] = fexp(l1) * Hc[1] + bf_hi(bw[i].x); Hc[2] = fexp(l2) * Hc[2] + bf_lo(bw[i].y); Hc[3] = fexp(l3) * Hc[3] + bf_hi(bw[i].y); }
.Lgate_epi_general:
	s_mov_b32 s17, 0x4038aa3b
	v_pk_mul_f32 v[180:181], v[58:59], s[74:75] op_sel_hi:[1,0]
	v_pk_mul_f32 v[182:183], v[60:61], s[74:75] op_sel_hi:[1,0]
	v_pk_mul_f32 v[184:185], v[66:67], s[74:75] op_sel_hi:[1,0]
	v_pk_mul_f32 v[186:187], v[68:69], s[74:75] op_sel_hi:[1,0]
	v_exp_f32_e32 v180, v180
	v_exp_f32_e32 v181, v181
	v_exp_f32_e32 v182, v182
	v_exp_f32_e32 v183, v183
	v_exp_f32_e32 v184, v184
	v_exp_f32_e32 v185, v185
	v_exp_f32_e32 v186, v186
	v_exp_f32_e32 v187, v187
	v_pk_fma_f32 v[188:189], v[204:205], s[24:25], v[236:237] op_sel_hi:[1,0,0]
	v_pk_fma_f32 v[190:191], v[206:207], s[24:25], v[236:237] op_sel_hi:[1,0,0]
	v_pk_fma_f32 v[192:193], v[220:221], s[24:25], v[236:237] op_sel_hi:[1,0,0]
	v_pk_fma_f32 v[194:195], v[222:223], s[24:25], v[236:237] op_sel_hi:[1,0,0]
	v_pk_add_f32 v[180:181], v[180:181], 1.0 op_sel_hi:[1,0]
	v_pk_add_f32 v[182:183], v[182:183], 1.0 op_sel_hi:[1,0]
	v_pk_add_f32 v[184:185], v[184:185], 1.0 op_sel_hi:[1,0]
	v_pk_add_f32 v[186:187], v[186:187], 1.0 op_sel_hi:[1,0]
	v_rcp_f32_e32 v180, v180
	v_rcp_f32_e32 v181, v181
	v_rcp_f32_e32 v182, v182
	v_rcp_f32_e32 v183, v183
	v_rcp_f32_e32 v184, v184
	v_rcp_f32_e32 v185, v185
	v_rcp_f32_e32 v186, v186
	v_rcp_f32_e32 v187, v187
	v_pk_fma_f32 v[188:189], v[204:205], v[188:189], s[22:23] op_sel_hi:[1,1,0]
	v_pk_fma_f32 v[190:191], v[206:207], v[190:191], s[22:23] op_sel_hi:[1,1,0]
	v_pk_fma_f32 v[192:193], v[220:221], v[192:193], s[22:23] op_sel_hi:[1,1,0]
	v_pk_fma_f32 v[194:195], v[222:223], v[194:195], s[22:23] op_sel_hi:[1,1,0]
	v_pk_fma_f32 v[188:189], v[204:205], v[188:189], -2.0 op_sel_hi:[1,1,0]
	v_pk_fma_f32 v[190:191], v[206:207], v[190:191], -2.0 op_sel_hi:[1,1,0]
	v_pk_fma_f32 v[192:193], v[220:221], v[192:193], -2.0 op_sel_hi:[1,1,0]
	v_pk_fma_f32 v[194:195], v[222:223], v[194:195], -2.0 op_sel_hi:[1,1,0]
	v_pk_fma_f32 v[188:189], v[204:205], v[188:189], -2.0 op_sel_hi:[1,1,0]
	v_pk_fma_f32 v[190:191], v[206:207], v[190:191], -2.0 op_sel_hi:[1,1,0]
	v_pk_fma_f32 v[192:193], v[220:221], v[192:193], -2.0 op_sel_hi:[1,1,0]
	v_pk_fma_f32 v[194:195], v[222:223], v[194:195], -2.0 op_sel_hi:[1,1,0]
	v_pk_mul_f32 v[188:189], v[204:205], v[188:189]
	v_pk_mul_f32 v[190:191], v[206:207], v[190:191]
	v_pk_mul_f32 v[192:193], v[220:221], v[192:193]
	v_pk_mul_f32 v[194:195], v[222:223], v[194:195]
	v_mul_f32_e32 v196, s17, v204
	v_mul_f32_e32 v197, s17, v205
	v_mul_f32_e32 v198, s17, v206
	v_mul_f32_e32 v199, s17, v207
	v_mul_f32_e32 v200, s17, v220
	v_mul_f32_e32 v201, s17, v221
	v_mul_f32_e32 v202, s17, v222
	v_mul_f32_e32 v203, s17, v223
	v_exp_f32_e32 v196, v196
	v_exp_f32_e32 v197, v197
	v_exp_f32_e32 v198, v198
	v_exp_f32_e32 v199, v199
	v_exp_f32_e32 v200, v200
	v_exp_f32_e32 v201, v201
	v_exp_f32_e32 v202, v202
	v_exp_f32_e32 v203, v203
	v_pk_add_f32 v[196:197], v[196:197], 1.0 op_sel_hi:[1,0] neg_lo:[1,0] neg_hi:[1,0]
	v_pk_add_f32 v[198:199], v[198:199], 1.0 op_sel_hi:[1,0] neg_lo:[1,0] neg_hi:[1,0]
	v_pk_add_f32 v[200:201], v[200:201], 1.0 op_sel_hi:[1,0] neg_lo:[1,0] neg_hi:[1,0]
	v_pk_add_f32 v[202:203], v[202:203], 1.0 op_sel_hi:[1,0] neg_lo:[1,0] neg_hi:[1,0]
	v_cmp_lt_f32_e32 vcc, s13, v204
	s_nop 1
	v_cndmask_b32_e32 v188, v196, v188, vcc
	v_cmp_lt_f32_e32 vcc, s13, v205
	s_nop 1
	v_cndmask_b32_e32 v189, v197, v189, vcc
	v_cmp_lt_f32_e32 vcc, s13, v206
	s_nop 1
	v_cndmask_b32_e32 v190, v198, v190, vcc
	v_cmp_lt_f32_e32 vcc, s13, v207
	s_nop 1
	v_cndmask_b32_e32 v191, v199, v191, vcc
	v_cmp_lt_f32_e32 vcc, s13, v220
	s_nop 1
	v_cndmask_b32_e32 v192, v200, v192, vcc
	v_cmp_lt_f32_e32 vcc, s13, v221
	s_nop 1
	v_cndmask_b32_e32 v193, v201, v193, vcc
	v_cmp_lt_f32_e32 vcc, s13, v222
	s_nop 1
	v_cndmask_b32_e32 v194, v202, v194, vcc
	v_cmp_lt_f32_e32 vcc, s13, v223
	s_nop 1
	v_cndmask_b32_e32 v195, v203, v195, vcc
	v_pk_mul_f32 v[228:229], v[204:205], s[74:75] op_sel_hi:[1,0] neg_lo:[0,1] neg_hi:[0,1]
	v_pk_mul_f32 v[230:231], v[206:207], s[74:75] op_sel_hi:[1,0] neg_lo:[0,1] neg_hi:[0,1]
	v_pk_mul_f32 v[232:233], v[220:221], s[74:75] op_sel_hi:[1,0] neg_lo:[0,1] neg_hi:[0,1]
	v_pk_mul_f32 v[234:235], v[222:223], s[74:75] op_sel_hi:[1,0] neg_lo:[0,1] neg_hi:[0,1]
	v_sqrt_f32_e32 v188, v188
	v_sqrt_f32_e32 v189, v189
	v_sqrt_f32_e32 v190, v190
	v_sqrt_f32_e32 v191, v191
	v_sqrt_f32_e32 v192, v192
	v_sqrt_f32_e32 v193, v193
	v_sqrt_f32_e32 v194, v194
	v_sqrt_f32_e32 v195, v195
	v_exp_f32_e32 v58, v228
	v_exp_f32_e32 v59, v229
	v_exp_f32_e32 v60, v230
	v_exp_f32_e32 v61, v231
	v_exp_f32_e32 v66, v232
	v_exp_f32_e32 v67, v233
	v_exp_f32_e32 v68, v234
	v_exp_f32_e32 v69, v235
	s_waitcnt vmcnt(15)
; __device__ __forceinline__ unsigned cvt_pk_bf16(float lo, float hi) { unsigned r; asm volatile("v_cvt_pk_bf16_f32 %0, %1, %2" : "=v"(r) : "v"(lo), "v"(hi)); return r; }
; __device__ __forceinline__ float bf_lo(unsigned w) { return __uint_as_float(w << 16); }
; __device__ __forceinline__ float bf_hi(unsigned w) { return __uint_as_float(w & 0xffff0000u); }
; __device__ __forceinline__ float fexp(float x) { return __builtin_amdgcn_exp2f(1.44269504f * x); }
;     __device__ __forceinline__ void operator()(AccMut acc, const Unit& u, int sw) const {
;     ...
;                 float bt[8];
; #pragma unroll
;                 for (int n = 0; n < 2; ++n)
; #pragma unroll
;                     for (int jp = 0; jp < 2; ++jp) {
;                         const f32x2 z = (f32x2){acc[ai][1][m][n][2 * jp], acc[ai][1][m][n][2 * jp + 1]} * (-1.44269504f);
;                         f32x2 e; e.x = __builtin_amdgcn_exp2f(z.x); e.y = __builtin_amdgcn_exp2f(z.y); e = e + 1.0f;
;                         f32x2 ig; ig.x = __builtin_amdgcn_rcpf(e.x); ig.y = __builtin_amdgcn_rcpf(e.y);
;                         const f32x2 x2 = (f32x2){acc[ai][0][m][n][2 * jp], acc[ai][0][m][n][2 * jp + 1]} * 2.0f;
;                         f32x2 ser = x2 * (1.0f / 120.0f) + (1.0f / 24.0f); ser = ser * x2 + (1.0f / 6.0f); ser = ser * x2 + 0.5f; ser = ser * x2 + 1.0f; ser = ser * (-x2);
;                         f32x2 em = ser;
;                         if (__builtin_expect(__builtin_amdgcn_ballot_w64(x2.x <= -0.25f || x2.y <= -0.25f) != 0ull, 0)) {
;                             em.x = (x2.x > -0.25f) ? ser.x : (1.0f - fexp(x2.x)); em.y = (x2.y > -0.25f) ? ser.y : (1.0f - fexp(x2.y)); }
;                         const unsigned wv = xw[2 * n + jp];
;                         f32x2 sq; sq.x = __builtin_amdgcn_sqrtf(em.x); sq.y = __builtin_amdgcn_sqrtf(em.y);
;                         const f32x2 b2 = sq * ig * (f32x2){bf_lo(wv), bf_hi(wv)};
;                         bt[4 * n + 2 * jp] = b2.x; bt[4 * n + 2 * jp + 1] = b2.y; }
;                 u32x4 w; w.x = cvt_pk_bf16(bt[0], bt[1]); w.y = cvt_pk_bf16(bt[2], bt[3]); w.z = cvt_pk_bf16(bt[4], bt[5]); w.w = cvt_pk_bf16(bt[6], bt[7]);
;                 *(u32x4*)(BT + off) = w; }
	v_lshlrev_b32_e32 v196, 16, v136
	v_and_b32_e32 v197, 0xffff0000, v136
	v_lshlrev_b32_e32 v198, 16, v137
	v_and_b32_e32 v199, 0xffff0000, v137
	v_lshlrev_b32_e32 v200, 16, v138
	v_and_b32_e32 v201, 0xffff0000, v138
	v_lshlrev_b32_e32 v202, 16, v139
	v_and_b32_e32 v203, 0xffff0000, v139
	v_pk_mul_f32 v[188:189], v[188:189], v[180:181]
	v_pk_mul_f32 v[190:191], v[190:191], v[182:183]
	v_pk_mul_f32 v[192:193], v[192:193], v[184:185]
	v_pk_mul_f32 v[194:195], v[194:195], v[186:187]
	v_pk_mul_f32 v[216:217], v[188:189], v[196:197]
	v_pk_mul_f32 v[218:219], v[190:191], v[198:199]
	v_pk_mul_f32 v[240:241], v[192:193], v[200:201]
	v_pk_mul_f32 v[242:243], v[194:195], v[202:203]
	v_cvt_pk_bf16_f32 v208, v216, v217
	v_cvt_pk_bf16_f32 v209, v218, v219
	v_cvt_pk_bf16_f32 v210, v240, v241
	v_cvt_pk_bf16_f32 v211, v242, v243
	global_store_dwordx4 v168, v[208:211], s[10:11]
	v_pk_mul_f32 v[180:181], v[50:51], s[74:75] op_sel_hi:[1,0]
	v_pk_mul_f32 v[182:183], v[52:53], s[74:75] op_sel_hi:[1,0]
	v_pk_mul_f32 v[184:185], v[54:55], s[74:75] op_sel_hi:[1,0]
	v_pk_mul_f32 v[186:187], v[56:57], s[74:75] op_sel_hi:[1,0]
	v_exp_f32_e32 v180, v180
	v_exp_f32_e32 v181, v181
	v_exp_f32_e32 v182, v182
	v_exp_f32_e32 v183, v183
	v_exp_f32_e32 v184, v184
	v_exp_f32_e32 v185, v185
	v_exp_f32_e32 v186, v186
	v_exp_f32_e32 v187, v187
	v_pk_fma_f32 v[188:189], v[224:225], s[24:25], v[236:237] op_sel_hi:[1,0,0]
	v_pk_fma_f32 v[190:191], v[226:227], s[24:25], v[236:237] op_sel_hi:[1,0,0]
	v_pk_fma_f32 v[192:193], v[126:127], s[24:25], v[236:237] op_sel_hi:[1,0,0]
	v_pk_fma_f32 v[194:195], v[128:129], s[24:25], v[236:237] op_sel_hi:[1,0,0]
	v_pk_add_f32 v[180:181], v[180:181], 1.0 op_sel_hi:[1,0]
	v_pk_add_f32 v[182:183], v[182:183], 1.0 op_sel_hi:[1,0]
	v_pk_add_f32 v[184:185], v[184:185], 1.0 op_sel_hi:[1,0]
	v_pk_add_f32 v[186:187], v[186:187], 1.0 op_sel_hi:[1,0]
	v_rcp_f32_e32 v180, v180
	v_rcp_f32_e32 v181, v181
	v_rcp_f32_e32 v182, v182
	v_rcp_f32_e32 v183, v183
	v_rcp_f32_e32 v184, v184
	v_rcp_f32_e32 v185, v185
	v_rcp_f32_e32 v186, v186
	v_rcp_f32_e32 v187, v187
	v_pk_fma_f32 v[188:189], v[224:225], v[188:189], s[22:23] op_sel_hi:[1,1,0]
	v_pk_fma_f32 v[190:191], v[226:227], v[190:191], s[22:23] op_sel_hi:[1,1,0]
	v_pk_fma_f32 v[192:193], v[126:127], v[192:193], s[22:23] op_sel_hi:[1,1,0]
	v_pk_fma_f32 v[194:195], v[128:129], v[194:195], s[22:23] op_sel_hi:[1,1,0]
	v_pk_fma_f32 v[188:189], v[224:225], v[188:189], -2.0 op_sel_hi:[1,1,0]
	v_pk_fma_f32 v[190:191], v[226:227], v[190:191], -2.0 op_sel_hi:[1,1,0]
	v_pk_fma_f32 v[192:193], v[126:127], v[192:193], -2.0 op_sel_hi:[1,1,0]
	v_pk_fma_f32 v[194:195], v[128:129], v[194:195], -2.0 op_sel_hi:[1,1,0]
	v_pk_fma_f32 v[188:189], v[224:225], v[188:189], -2.0 op_sel_hi:[1,1,0]
	v_pk_fma_f32 v[190:191], v[226:227], v[190:191], -2.0 op_sel_hi:[1,1,0]
	v_pk_fma_f32 v[192:193], v[126:127], v[192:193], -2.0 op_sel_hi:[1,1,0]
	v_pk_fma_f32 v[194:195], v[128:129], v[194:195], -2.0 op_sel_hi:[1,1,0]
	v_pk_mul_f32 v[188:189], v[224:225], v[188:189]
	v_pk_mul_f32 v[190:191], v[226:227], v[190:191]
	v_pk_mul_f32 v[192:193], v[126:127], v[192:193]
	v_pk_mul_f32 v[194:195], v[128:129], v[194:195]
	v_mul_f32_e32 v196, s17, v224
	v_mul_f32_e32 v197, s17, v225
	v_mul_f32_e32 v198, s17, v226
	v_mul_f32_e32 v199, s17, v227
	v_mul_f32_e32 v200, s17, v126
	v_mul_f32_e32 v201, s17, v127
	v_mul_f32_e32 v202, s17, v128
	v_mul_f32_e32 v203, s17, v129
	v_exp_f32_e32 v196, v196
	v_exp_f32_e32 v197, v197
	v_exp_f32_e32 v198, v198
	v_exp_f32_e32 v199, v199
	v_exp_f32_e32 v200, v200
	v_exp_f32_e32 v201, v201
	v_exp_f32_e32 v202, v202
	v_exp_f32_e32 v203, v203
	v_pk_add_f32 v[196:197], v[196:197], 1.0 op_sel_hi:[1,0] neg_lo:[1,0] neg_hi:[1,0]
	v_pk_add_f32 v[198:199], v[198:199], 1.0 op_sel_hi:[1,0] neg_lo:[1,0] neg_hi:[1,0]
	v_pk_add_f32 v[200:201], v[200:201], 1.0 op_sel_hi:[1,0] neg_lo:[1,0] neg_hi:[1,0]
	v_pk_add_f32 v[202:203], v[202:203], 1.0 op_sel_hi:[1,0] neg_lo:[1,0] neg_hi:[1,0]
	v_cmp_lt_f32_e32 vcc, s13, v224
	s_nop 1
	v_cndmask_b32_e32 v188, v196, v188, vcc
	v_cmp_lt_f32_e32 vcc, s13, v225
	s_nop 1
	v_cndmask_b32_e32 v189, v197, v189, vcc
	v_cmp_lt_f32_e32 vcc, s13, v226
	s_nop 1
	v_cndmask_b32_e32 v190, v198, v190, vcc
	v_cmp_lt_f32_e32 vcc, s13, v227
	s_nop 1
	v_cndmask_b32_e32 v191, v199, v191, vcc
	v_cmp_lt_f32_e32 vcc, s13, v126
	s_nop 1
	v_cndmask_b32_e32 v192, v200, v192, vcc
	v_cmp_lt_f32_e32 vcc, s13, v127
	s_nop 1
	v_cndmask_b32_e32 v193, v201, v193, vcc
	v_cmp_lt_f32_e32 vcc, s13, v128
	s_nop 1
	v_cndmask_b32_e32 v194, v202, v194, vcc
	v_cmp_lt_f32_e32 vcc, s13, v129
	s_nop 1
	v_cndmask_b32_e32 v195, v203, v195, vcc
	v_pk_mul_f32 v[228:229], v[224:225], s[74:75] op_sel_hi:[1,0] neg_lo:[0,1] neg_hi:[0,1]
	v_pk_mul_f32 v[230:231], v[226:227], s[74:75] op_sel_hi:[1,0] neg_lo:[0,1] neg_hi:[0,1]
	v_pk_mul_f32 v[232:233], v[126:127], s[74:75] op_sel_hi:[1,0] neg_lo:[0,1] neg_hi:[0,1]
	v_pk_mul_f32 v[234:235], v[128:129], s[74:75] op_sel_hi:[1,0] neg_lo:[0,1] neg_hi:[0,1]
	v_sqrt_f32_e32 v188, v188
	v_sqrt_f32_e32 v189, v189
	v_sqrt_f32_e32 v190, v190
	v_sqrt_f32_e32 v191, v191
	v_sqrt_f32_e32 v192, v192
	v_sqrt_f32_e32 v193, v193
	v_sqrt_f32_e32 v194, v194
	v_sqrt_f32_e32 v195, v195
	v_exp_f32_e32 v228, v228
	v_exp_f32_e32 v229, v229
	v_exp_f32_e32 v230, v230
	v_exp_f32_e32 v231, v231
	v_exp_f32_e32 v232, v232
	v_exp_f32_e32 v233, v233
	v_exp_f32_e32 v234, v234
	v_exp_f32_e32 v235, v235
	s_waitcnt vmcnt(15)
; __device__ __forceinline__ unsigned cvt_pk_bf16(float lo, float hi) { unsigned r; asm volatile("v_cvt_pk_bf16_f32 %0, %1, %2" : "=v"(r) : "v"(lo), "v"(hi)); return r; }
; __device__ __forceinline__ float bf_lo(unsigned w) { return __uint_as_float(w << 16); }
; __device__ __forceinline__ float bf_hi(unsigned w) { return __uint_as_float(w & 0xffff0000u); }
; __device__ __forceinline__ float fexp(float x) { return __builtin_amdgcn_exp2f(1.44269504f * x); }
;     __device__ __forceinline__ void operator()(AccMut acc, const Unit& u, int sw) const {
;     ...
;                         const unsigned wv = xw[2 * n + jp];
;                         f32x2 sq; sq.x = __builtin_amdgcn_sqrtf(em.x); sq.y = __builtin_amdgcn_sqrtf(em.y);
;                         const f32x2 b2 = sq * ig * (f32x2){bf_lo(wv), bf_hi(wv)};
;                         bt[4 * n + 2 * jp] = b2.x; bt[4 * n + 2 * jp + 1] = b2.y; }
;                 u32x4 w; w.x = cvt_pk_bf16(bt[0], bt[1]); w.y = cvt_pk_bf16(bt[2], bt[3]); w.z = cvt_pk_bf16(bt[4], bt[5]); w.w = cvt_pk_bf16(bt[6], bt[7]);
;                 *(u32x4*)(BT + off) = w; }
; __device__ __forceinline__ void scan1_phase(const bf16_t* LA, const bf16_t* BT, int sw, View vw) {
;     ...
;             for (int i = 0; i < 8; ++i) {
;                 const float l0 = bf_lo(lw[i].x), l1 = bf_hi(lw[i].x), l2 = bf_lo(lw[i].y), l3 = bf_hi(lw[i].y);
;                 S[0] += l0; S[1] += l1; S[2] += l2; S[3] += l3;
;                 Hc[0] = fexp(l0) * Hc[0] + bf_lo(bw[i].x); Hc[1] = fexp(l1) * Hc[1] + bf_hi(bw[i].x); Hc[2] = fexp(l2) * Hc[2] + bf_lo(bw[i].y); Hc[3] = fexp(l3) * Hc[3] + bf_hi(bw[i].y); }
	v_lshlrev_b32_e32 v196, 16, v140
	v_and_b32_e32 v197, 0xffff0000, v140
	v_lshlrev_b32_e32 v198, 16, v141
	v_and_b32_e32 v199, 0xffff0000, v141
	v_lshlrev_b32_e32 v200, 16, v142
	v_and_b32_e32 v201, 0xffff0000, v142
	v_lshlrev_b32_e32 v202, 16, v143
	v_and_b32_e32 v203, 0xffff0000, v143
	v_pk_mul_f32 v[188:189], v[188:189], v[180:181]
	v_pk_mul_f32 v[190:191], v[190:191], v[182:183]
	v_pk_mul_f32 v[192:193], v[192:193], v[184:185]
	v_pk_mul_f32 v[194:195], v[194:195], v[186:187]
	v_pk_mul_f32 v[188:189], v[188:189], v[196:197]
	v_pk_mul_f32 v[190:191], v[190:191], v[198:199]
	v_pk_mul_f32 v[192:193], v[192:193], v[200:201]
	v_pk_mul_f32 v[194:195], v[194:195], v[202:203]
	v_cvt_pk_bf16_f32 v212, v188, v189
	v_cvt_pk_bf16_f32 v213, v190, v191
	v_cvt_pk_bf16_f32 v214, v192, v193
	v_cvt_pk_bf16_f32 v215, v194, v195
	global_store_dwordx4 v169, v[212:215], s[10:11]
	v_pk_fma_f32 v[216:217], v[228:229], v[216:217], v[188:189]
	v_pk_fma_f32 v[218:219], v[230:231], v[218:219], v[190:191]
	v_pk_fma_f32 v[240:241], v[232:233], v[240:241], v[192:193]
	v_pk_fma_f32 v[242:243], v[234:235], v[242:243], v[194:195]
	v_pk_mul_f32 v[58:59], v[58:59], v[228:229]
	v_pk_mul_f32 v[60:61], v[60:61], v[230:231]
	v_pk_mul_f32 v[66:67], v[66:67], v[232:233]
	v_pk_mul_f32 v[68:69], v[68:69], v[234:235]
	v_pk_add_f32 v[204:205], v[204:205], v[224:225]
	v_pk_add_f32 v[206:207], v[206:207], v[226:227]
	v_pk_add_f32 v[220:221], v[220:221], v[126:127]
	v_pk_add_f32 v[222:223], v[222:223], v[128:129]
	v_pk_mul_f32 v[180:181], v[42:43], s[74:75] op_sel_hi:[1,0]
	v_pk_mul_f32 v[182:183], v[44:45], s[74:75] op_sel_hi:[1,0]
	v_pk_mul_f32 v[184:185], v[46:47], s[74:75] op_sel_hi:[1,0]
	v_pk_mul_f32 v[186:187], v[48:49], s[74:75] op_sel_hi:[1,0]
	v_exp_f32_e32 v180, v180
	v_exp_f32_e32 v181, v181
	v_exp_f32_e32 v182, v182
	v_exp_f32_e32 v183, v183
	v_exp_f32_e32 v184, v184
	v_exp_f32_e32 v185, v185
	v_exp_f32_e32 v186, v186
	v_exp_f32_e32 v187, v187
	v_pk_fma_f32 v[188:189], v[122:123], s[24:25], v[236:237] op_sel_hi:[1,0,0]
	v_pk_fma_f32 v[190:191], v[124:125], s[24:25], v[236:237] op_sel_hi:[1,0,0]
	v_pk_fma_f32 v[192:193], v[118:119], s[24:25], v[236:237] op_sel_hi:[1,0,0]
	v_pk_fma_f32 v[194:195], v[120:121], s[24:25], v[236:237] op_sel_hi:[1,0,0]
	v_pk_add_f32 v[180:181], v[180:181], 1.0 op_sel_hi:[1,0]
	v_pk_add_f32 v[182:183], v[182:183], 1.0 op_sel_hi:[1,0]
	v_pk_add_f32 v[184:185], v[184:185], 1.0 op_sel_hi:[1,0]
	v_pk_add_f32 v[186:187], v[186:187], 1.0 op_sel_hi:[1,0]
	v_rcp_f32_e32 v180, v180
	v_rcp_f32_e32 v181, v181
	v_rcp_f32_e32 v182, v182
	v_rcp_f32_e32 v183, v183
	v_rcp_f32_e32 v184, v184
	v_rcp_f32_e32 v185, v185
	v_rcp_f32_e32 v186, v186
	v_rcp_f32_e32 v187, v187
	v_pk_fma_f32 v[188:189], v[122:123], v[188:189], s[22:23] op_sel_hi:[1,1,0]
	v_pk_fma_f32 v[190:191], v[124:125], v[190:191], s[22:23] op_sel_hi:[1,1,0]
	v_pk_fma_f32 v[192:193], v[118:119], v[192:193], s[22:23] op_sel_hi:[1,1,0]
	v_pk_fma_f32 v[194:195], v[120:121], v[194:195], s[22:23] op_sel_hi:[1,1,0]
	v_pk_fma_f32 v[188:189], v[122:123], v[188:189], -2.0 op_sel_hi:[1,1,0]
	v_pk_fma_f32 v[190:191], v[124:125], v[190:191], -2.0 op_sel_hi:[1,1,0]
	v_pk_fma_f32 v[192:193], v[118:119], v[192:193], -2.0 op_sel_hi:[1,1,0]
	v_pk_fma_f32 v[194:195], v[120:121], v[194:195], -2.0 op_sel_hi:[1,1,0]
	v_pk_fma_f32 v[188:189], v[122:123], v[188:189], -2.0 op_sel_hi:[1,1,0]
	v_pk_fma_f32 v[190:191], v[124:125], v[190:191], -2.0 op_sel_hi:[1,1,0]
	v_pk_fma_f32 v[192:193], v[118:119], v[192:193], -2.0 op_sel_hi:[1,1,0]
	v_pk_fma_f32 v[194:195], v[120:121], v[194:195], -2.0 op_sel_hi:[1,1,0]
	v_pk_mul_f32 v[188:189], v[122:123], v[188:189]
	v_pk_mul_f32 v[190:191], v[124:125], v[190:191]
	v_pk_mul_f32 v[192:193], v[118:119], v[192:193]
	v_pk_mul_f32 v[194:195], v[120:121], v[194:195]
	v_mul_f32_e32 v196, s17, v122
	v_mul_f32_e32 v197, s17, v123
	v_mul_f32_e32 v198, s17, v124
	v_mul_f32_e32 v199, s17, v125
	v_mul_f32_e32 v200, s17, v118
	v_mul_f32_e32 v201, s17, v119
	v_mul_f32_e32 v202, s17, v120
	v_mul_f32_e32 v203, s17, v121
	v_exp_f32_e32 v196, v196
	v_exp_f32_e32 v197, v197
	v_exp_f32_e32 v198, v198
	v_exp_f32_e32 v199, v199
	v_exp_f32_e32 v200, v200
	v_exp_f32_e32 v201, v201
	v_exp_f32_e32 v202, v202
	v_exp_f32_e32 v203, v203
	v_pk_add_f32 v[196:197], v[196:197], 1.0 op_sel_hi:[1,0] neg_lo:[1,0] neg_hi:[1,0]
	v_pk_add_f32 v[198:199], v[198:199], 1.0 op_sel_hi:[1,0] neg_lo:[1,0] neg_hi:[1,0]
	v_pk_add_f32 v[200:201], v[200:201], 1.0 op_sel_hi:[1,0] neg_lo:[1,0] neg_hi:[1,0]
	v_pk_add_f32 v[202:203], v[202:203], 1.0 op_sel_hi:[1,0] neg_lo:[1,0] neg_hi:[1,0]
	v_cmp_lt_f32_e32 vcc, s13, v122
	s_nop 1
	v_cndmask_b32_e32 v188, v196, v188, vcc
	v_cmp_lt_f32_e32 vcc, s13, v123
	s_nop 1
	v_cndmask_b32_e32 v189, v197, v189, vcc
	v_cmp_lt_f32_e32 vcc, s13, v124
	s_nop 1
	v_cndmask_b32_e32 v190, v198, v190, vcc
	v_cmp_lt_f32_e32 vcc, s13, v125
	s_nop 1
	v_cndmask_b32_e32 v191, v199, v191, vcc
	v_cmp_lt_f32_e32 vcc, s13, v118
	s_nop 1
	v_cndmask_b32_e32 v192, v200, v192, vcc
	v_cmp_lt_f32_e32 vcc, s13, v119
	s_nop 1
	v_cndmask_b32_e32 v193, v201, v193, vcc
	v_cmp_lt_f32_e32 vcc, s13, v120
	s_nop 1
	v_cndmask_b32_e32 v194, v202, v194, vcc
	v_cmp_lt_f32_e32 vcc, s13, v121
	s_nop 1
	v_cndmask_b32_e32 v195, v203, v195, vcc
	v_pk_mul_f32 v[228:229], v[122:123], s[74:75] op_sel_hi:[1,0] neg_lo:[0,1] neg_hi:[0,1]
	v_pk_mul_f32 v[230:231], v[124:125], s[74:75] op_sel_hi:[1,0] neg_lo:[0,1] neg_hi:[0,1]
	v_pk_mul_f32 v[232:233], v[118:119], s[74:75] op_sel_hi:[1,0] neg_lo:[0,1] neg_hi:[0,1]
	v_pk_mul_f32 v[234:235], v[120:121], s[74:75] op_sel_hi:[1,0] neg_lo:[0,1] neg_hi:[0,1]
	v_sqrt_f32_e32 v188, v188
	v_sqrt_f32_e32 v189, v189
	v_sqrt_f32_e32 v190, v190
	v_sqrt_f32_e32 v191, v191
	v_sqrt_f32_e32 v192, v192
	v_sqrt_f32_e32 v193, v193
	v_sqrt_f32_e32 v194, v194
	v_sqrt_f32_e32 v195, v195
	v_exp_f32_e32 v228, v228
	v_exp_f32_e32 v229, v229
	v_exp_f32_e32 v230, v230
	v_exp_f32_e32 v231, v231
	v_exp_f32_e32 v232, v232
	v_exp_f32_e32 v233, v233
	v_exp_f32_e32 v234, v234
	v_exp_f32_e32 v235, v235
	s_waitcnt vmcnt(15)
; __device__ __forceinline__ unsigned cvt_pk_bf16(float lo, float hi) { unsigned r; asm volatile("v_cvt_pk_bf16_f32 %0, %1, %2" : "=v"(r) : "v"(lo), "v"(hi)); return r; }
; __device__ __forceinline__ float bf_lo(unsigned w) { return __uint_as_float(w << 16); }
; __device__ __forceinline__ float bf_hi(unsigned w) { return __uint_as_float(w & 0xffff0000u); }
; __device__ __forceinline__ float fexp(float x) { return __builtin_amdgcn_exp2f(1.44269504f * x); }
;     __device__ __forceinline__ void operator()(AccMut acc, const Unit& u, int sw) const {
;     ...
;                         const unsigned wv = xw[2 * n + jp];
;                         f32x2 sq; sq.x = __builtin_amdgcn_sqrtf(em.x); sq.y = __builtin_amdgcn_sqrtf(em.y);
;                         const f32x2 b2 = sq * ig * (f32x2){bf_lo(wv), bf_hi(wv)};
;                         bt[4 * n + 2 * jp] = b2.x; bt[4 * n + 2 * jp + 1] = b2.y; }
;                 u32x4 w; w.x = cvt_pk_bf16(bt[0], bt[1]); w.y = cvt_pk_bf16(bt[2], bt[3]); w.z = cvt_pk_bf16(bt[4], bt[5]); w.w = cvt_pk_bf16(bt[6], bt[7]);
;                 *(u32x4*)(BT + off) = w; }
; __device__ __forceinline__ void scan1_phase(const bf16_t* LA, const bf16_t* BT, int sw, View vw) {
;     ...
;             for (int i = 0; i < 8; ++i) {
;                 const float l0 = bf_lo(lw[i].x), l1 = bf_hi(lw[i].x), l2 = bf_lo(lw[i].y), l3 = bf_hi(lw[i].y);
;                 S[0] += l0; S[1] += l1; S[2] += l2; S[3] += l3;
;                 Hc[0] = fexp(l0) * Hc[0] + bf_lo(bw[i].x); Hc[1] = fexp(l1) * Hc[1] + bf_hi(bw[i].x); Hc[2] = fexp(l2) * Hc[2] + bf_lo(bw[i].y); Hc[3] = fexp(l3) * Hc[3] + bf_hi(bw[i].y); }
	v_lshlrev_b32_e32 v196, 16, v144
	v_and_b32_e32 v197, 0xffff0000, v144
	v_lshlrev_b32_e32 v198, 16, v145
	v_and_b32_e32 v199, 0xffff0000, v145
	v_lshlrev_b32_e32 v200, 16, v146
	v_and_b32_e32 v201, 0xffff0000, v146
	v_lshlrev_b32_e32 v202, 16, v147
	v_and_b32_e32 v203, 0xffff0000, v147
	v_pk_mul_f32 v[188:189], v[188:189], v[180:181]
	v_pk_mul_f32 v[190:191], v[190:191], v[182:183]
	v_pk_mul_f32 v[192:193], v[192:193], v[184:185]
	v_pk_mul_f32 v[194:195], v[194:195], v[186:187]
	v_pk_mul_f32 v[188:189], v[188:189], v[196:197]
	v_pk_mul_f32 v[190:191], v[190:191], v[198:199]
	v_pk_mul_f32 v[192:193], v[192:193], v[200:201]
	v_pk_mul_f32 v[194:195], v[194:195], v[202:203]
	v_cvt_pk_bf16_f32 v208, v188, v189
	v_cvt_pk_bf16_f32 v209, v190, v191
	v_cvt_pk_bf16_f32 v210, v192, v193
	v_cvt_pk_bf16_f32 v211, v194, v195
	global_store_dwordx4 v172, v[208:211], s[10:11]
	v_pk_fma_f32 v[216:217], v[228:229], v[216:217], v[188:189]
	v_pk_fma_f32 v[218:219], v[230:231], v[218:219], v[190:191]
	v_pk_fma_f32 v[240:241], v[232:233], v[240:241], v[192:193]
	v_pk_fma_f32 v[242:243], v[234:235], v[242:243], v[194:195]
	v_pk_mul_f32 v[58:59], v[58:59], v[228:229]
	v_pk_mul_f32 v[60:61], v[60:61], v[230:231]
	v_pk_mul_f32 v[66:67], v[66:67], v[232:233]
	v_pk_mul_f32 v[68:69], v[68:69], v[234:235]
	v_pk_add_f32 v[204:205], v[204:205], v[122:123]
	v_pk_add_f32 v[206:207], v[206:207], v[124:125]
	v_pk_add_f32 v[220:221], v[220:221], v[118:119]
	v_pk_add_f32 v[222:223], v[222:223], v[120:121]
	v_pk_mul_f32 v[180:181], v[34:35], s[74:75] op_sel_hi:[1,0]
	v_pk_mul_f32 v[182:183], v[36:37], s[74:75] op_sel_hi:[1,0]
	v_pk_mul_f32 v[184:185], v[38:39], s[74:75] op_sel_hi:[1,0]
	v_pk_mul_f32 v[186:187], v[40:41], s[74:75] op_sel_hi:[1,0]
	v_exp_f32_e32 v180, v180
	v_exp_f32_e32 v181, v181
	v_exp_f32_e32 v182, v182
	v_exp_f32_e32 v183, v183
	v_exp_f32_e32 v184, v184
	v_exp_f32_e32 v185, v185
	v_exp_f32_e32 v186, v186
	v_exp_f32_e32 v187, v187
	v_pk_fma_f32 v[188:189], v[114:115], s[24:25], v[236:237] op_sel_hi:[1,0,0]
	v_pk_fma_f32 v[190:191], v[116:117], s[24:25], v[236:237] op_sel_hi:[1,0,0]
	v_pk_fma_f32 v[192:193], v[106:107], s[24:25], v[236:237] op_sel_hi:[1,0,0]
	v_pk_fma_f32 v[194:195], v[108:109], s[24:25], v[236:237] op_sel_hi:[1,0,0]
	v_pk_add_f32 v[180:181], v[180:181], 1.0 op_sel_hi:[1,0]
	v_pk_add_f32 v[182:183], v[182:183], 1.0 op_sel_hi:[1,0]
	v_pk_add_f32 v[184:185], v[184:185], 1.0 op_sel_hi:[1,0]
	v_pk_add_f32 v[186:187], v[186:187], 1.0 op_sel_hi:[1,0]
	v_rcp_f32_e32 v180, v180
	v_rcp_f32_e32 v181, v181
	v_rcp_f32_e32 v182, v182
	v_rcp_f32_e32 v183, v183
	v_rcp_f32_e32 v184, v184
	v_rcp_f32_e32 v185, v185
	v_rcp_f32_e32 v186, v186
	v_rcp_f32_e32 v187, v187
	v_pk_fma_f32 v[188:189], v[114:115], v[188:189], s[22:23] op_sel_hi:[1,1,0]
	v_pk_fma_f32 v[190:191], v[116:117], v[190:191], s[22:23] op_sel_hi:[1,1,0]
	v_pk_fma_f32 v[192:193], v[106:107], v[192:193], s[22:23] op_sel_hi:[1,1,0]
	v_pk_fma_f32 v[194:195], v[108:109], v[194:195], s[22:23] op_sel_hi:[1,1,0]
	v_pk_fma_f32 v[188:189], v[114:115], v[188:189], -2.0 op_sel_hi:[1,1,0]
	v_pk_fma_f32 v[190:191], v[116:117], v[190:191], -2.0 op_sel_hi:[1,1,0]
	v_pk_fma_f32 v[192:193], v[106:107], v[192:193], -2.0 op_sel_hi:[1,1,0]
	v_pk_fma_f32 v[194:195], v[108:109], v[194:195], -2.0 op_sel_hi:[1,1,0]
	v_pk_fma_f32 v[188:189], v[114:115], v[188:189], -2.0 op_sel_hi:[1,1,0]
	v_pk_fma_f32 v[190:191], v[116:117], v[190:191], -2.0 op_sel_hi:[1,1,0]
	v_pk_fma_f32 v[192:193], v[106:107], v[192:193], -2.0 op_sel_hi:[1,1,0]
	v_pk_fma_f32 v[194:195], v[108:109], v[194:195], -2.0 op_sel_hi:[1,1,0]
	v_pk_mul_f32 v[188:189], v[114:115], v[188:189]
	v_pk_mul_f32 v[190:191], v[116:117], v[190:191]
	v_pk_mul_f32 v[192:193], v[106:107], v[192:193]
	v_pk_mul_f32 v[194:195], v[108:109], v[194:195]
	v_mul_f32_e32 v196, s17, v114
	v_mul_f32_e32 v197, s17, v115
	v_mul_f32_e32 v198, s17, v116
	v_mul_f32_e32 v199, s17, v117
	v_mul_f32_e32 v200, s17, v106
	v_mul_f32_e32 v201, s17, v107
	v_mul_f32_e32 v202, s17, v108
	v_mul_f32_e32 v203, s17, v109
	v_exp_f32_e32 v196, v196
	v_exp_f32_e32 v197, v197
	v_exp_f32_e32 v198, v198
	v_exp_f32_e32 v199, v199
	v_exp_f32_e32 v200, v200
	v_exp_f32_e32 v201, v201
	v_exp_f32_e32 v202, v202
	v_exp_f32_e32 v203, v203
	v_pk_add_f32 v[196:197], v[196:197], 1.0 op_sel_hi:[1,0] neg_lo:[1,0] neg_hi:[1,0]
	v_pk_add_f32 v[198:199], v[198:199], 1.0 op_sel_hi:[1,0] neg_lo:[1,0] neg_hi:[1,0]
	v_pk_add_f32 v[200:201], v[200:201], 1.0 op_sel_hi:[1,0] neg_lo:[1,0] neg_hi:[1,0]
	v_pk_add_f32 v[202:203], v[202:203], 1.0 op_sel_hi:[1,0] neg_lo:[1,0] neg_hi:[1,0]
	v_cmp_lt_f32_e32 vcc, s13, v114
	s_nop 1
	v_cndmask_b32_e32 v188, v196, v188, vcc
	v_cmp_lt_f32_e32 vcc, s13, v115
	s_nop 1
	v_cndmask_b32_e32 v189, v197, v189, vcc
	v_cmp_lt_f32_e32 vcc, s13, v116
	s_nop 1
	v_cndmask_b32_e32 v190, v198, v190, vcc
	v_cmp_lt_f32_e32 vcc, s13, v117
	s_nop 1
	v_cndmask_b32_e32 v191, v199, v191, vcc
	v_cmp_lt_f32_e32 vcc, s13, v106
	s_nop 1
	v_cndmask_b32_e32 v192, v200, v192, vcc
	v_cmp_lt_f32_e32 vcc, s13, v107
	s_nop 1
	v_cndmask_b32_e32 v193, v201, v193, vcc
	v_cmp_lt_f32_e32 vcc, s13, v108
	s_nop 1
	v_cndmask_b32_e32 v194, v202, v194, vcc
	v_cmp_lt_f32_e32 vcc, s13, v109
	s_nop 1
	v_cndmask_b32_e32 v195, v203, v195, vcc
	v_pk_mul_f32 v[228:229], v[114:115], s[74:75] op_sel_hi:[1,0] neg_lo:[0,1] neg_hi:[0,1]
	v_pk_mul_f32 v[230:231], v[116:117], s[74:75] op_sel_hi:[1,0] neg_lo:[0,1] neg_hi:[0,1]
	v_pk_mul_f32 v[232:233], v[106:107], s[74:75] op_sel_hi:[1,0] neg_lo:[0,1] neg_hi:[0,1]
	v_pk_mul_f32 v[234:235], v[108:109], s[74:75] op_sel_hi:[1,0] neg_lo:[0,1] neg_hi:[0,1]
	v_sqrt_f32_e32 v188, v188
	v_sqrt_f32_e32 v189, v189
	v_sqrt_f32_e32 v190, v190
	v_sqrt_f32_e32 v191, v191
	v_sqrt_f32_e32 v192, v192
	v_sqrt_f32_e32 v193, v193
	v_sqrt_f32_e32 v194, v194
	v_sqrt_f32_e32 v195, v195
	v_exp_f32_e32 v228, v228
	v_exp_f32_e32 v229, v229
	v_exp_f32_e32 v230, v230
	v_exp_f32_e32 v231, v231
	v_exp_f32_e32 v232, v232
	v_exp_f32_e32 v233, v233
	v_exp_f32_e32 v234, v234
	v_exp_f32_e32 v235, v235
	s_waitcnt vmcnt(15)
; __device__ __forceinline__ unsigned cvt_pk_bf16(float lo, float hi) { unsigned r; asm volatile("v_cvt_pk_bf16_f32 %0, %1, %2" : "=v"(r) : "v"(lo), "v"(hi)); return r; }
; __device__ __forceinline__ float bf_lo(unsigned w) { return __uint_as_float(w << 16); }
; __device__ __forceinline__ float bf_hi(unsigned w) { return __uint_as_float(w & 0xffff0000u); }
; __device__ __forceinline__ float fexp(float x) { return __builtin_amdgcn_exp2f(1.44269504f * x); }
;     __device__ __forceinline__ void operator()(AccMut acc, const Unit& u, int sw) const {
;     ...
;                         const unsigned wv = xw[2 * n + jp];
;                         f32x2 sq; sq.x = __builtin_amdgcn_sqrtf(em.x); sq.y = __builtin_amdgcn_sqrtf(em.y);
;                         const f32x2 b2 = sq * ig * (f32x2){bf_lo(wv), bf_hi(wv)};
;                         bt[4 * n + 2 * jp] = b2.x; bt[4 * n + 2 * jp + 1] = b2.y; }
;                 u32x4 w; w.x = cvt_pk_bf16(bt[0], bt[1]); w.y = cvt_pk_bf16(bt[2], bt[3]); w.z = cvt_pk_bf16(bt[4], bt[5]); w.w = cvt_pk_bf16(bt[6], bt[7]);
;                 *(u32x4*)(BT + off) = w; }
; __device__ __forceinline__ void scan1_phase(const bf16_t* LA, const bf16_t* BT, int sw, View vw) {
;     ...
;             for (int i = 0; i < 8; ++i) {
;                 const float l0 = bf_lo(lw[i].x), l1 = bf_hi(lw[i].x), l2 = bf_lo(lw[i].y), l3 = bf_hi(lw[i].y);
;                 S[0] += l0; S[1] += l1; S[2] += l2; S[3] += l3;
;                 Hc[0] = fexp(l0) * Hc[0] + bf_lo(bw[i].x); Hc[1] = fexp(l1) * Hc[1] + bf_hi(bw[i].x); Hc[2] = fexp(l2) * Hc[2] + bf_lo(bw[i].y); Hc[3] = fexp(l3) * Hc[3] + bf_hi(bw[i].y); }
;         }
;         *(f32x4*)(CP + (size_t)bq * E + 4 * quad) = (f32x4){S[0], S[1], S[2], S[3]};
;         *(f32x4*)(CH + (size_t)bq * E + 4 * quad) = (f32x4){Hc[0], Hc[1], Hc[2], Hc[3]};
	v_lshlrev_b32_e32 v196, 16, v148
	v_and_b32_e32 v197, 0xffff0000, v148
	v_lshlrev_b32_e32 v198, 16, v149
	v_and_b32_e32 v199, 0xffff0000, v149
	v_lshlrev_b32_e32 v200, 16, v150
	v_and_b32_e32 v201, 0xffff0000, v150
	v_lshlrev_b32_e32 v202, 16, v151
	v_and_b32_e32 v203, 0xffff0000, v151
	v_pk_mul_f32 v[188:189], v[188:189], v[180:181]
	v_pk_mul_f32 v[190:191], v[190:191], v[182:183]
	v_pk_mul_f32 v[192:193], v[192:193], v[184:185]
	v_pk_mul_f32 v[194:195], v[194:195], v[186:187]
	v_pk_mul_f32 v[188:189], v[188:189], v[196:197]
	v_pk_mul_f32 v[190:191], v[190:191], v[198:199]
	v_pk_mul_f32 v[192:193], v[192:193], v[200:201]
	v_pk_mul_f32 v[194:195], v[194:195], v[202:203]
	v_cvt_pk_bf16_f32 v212, v188, v189
	v_cvt_pk_bf16_f32 v213, v190, v191
	v_cvt_pk_bf16_f32 v214, v192, v193
	v_cvt_pk_bf16_f32 v215, v194, v195
	global_store_dwordx4 v173, v[212:215], s[10:11]
	v_pk_fma_f32 v[216:217], v[228:229], v[216:217], v[188:189]
	v_pk_fma_f32 v[218:219], v[230:231], v[218:219], v[190:191]
	v_pk_fma_f32 v[240:241], v[232:233], v[240:241], v[192:193]
	v_pk_fma_f32 v[242:243], v[234:235], v[242:243], v[194:195]
	v_pk_mul_f32 v[58:59], v[58:59], v[228:229]
	v_pk_mul_f32 v[60:61], v[60:61], v[230:231]
	v_pk_mul_f32 v[66:67], v[66:67], v[232:233]
	v_pk_mul_f32 v[68:69], v[68:69], v[234:235]
	v_pk_add_f32 v[204:205], v[204:205], v[114:115]
	v_pk_add_f32 v[206:207], v[206:207], v[116:117]
	v_pk_add_f32 v[220:221], v[220:221], v[106:107]
	v_pk_add_f32 v[222:223], v[222:223], v[108:109]
	v_fmac_f32_dpp v216, v216, v58 row_shr:1 row_mask:0xf bank_mask:0xf
	v_fmac_f32_dpp v217, v217, v59 row_shr:1 row_mask:0xf bank_mask:0xf
	v_fmac_f32_dpp v218, v218, v60 row_shr:1 row_mask:0xf bank_mask:0xf
	v_fmac_f32_dpp v219, v219, v61 row_shr:1 row_mask:0xf bank_mask:0xf
	v_fmac_f32_dpp v240, v240, v66 row_shr:1 row_mask:0xf bank_mask:0xf
	v_fmac_f32_dpp v241, v241, v67 row_shr:1 row_mask:0xf bank_mask:0xf
	v_fmac_f32_dpp v242, v242, v68 row_shr:1 row_mask:0xf bank_mask:0xf
	v_fmac_f32_dpp v243, v243, v69 row_shr:1 row_mask:0xf bank_mask:0xf
	v_mul_f32_dpp v58, v58, v58 row_shr:1 row_mask:0xf bank_mask:0xf
	v_mul_f32_dpp v59, v59, v59 row_shr:1 row_mask:0xf bank_mask:0xf
	v_mul_f32_dpp v60, v60, v60 row_shr:1 row_mask:0xf bank_mask:0xf
	v_mul_f32_dpp v61, v61, v61 row_shr:1 row_mask:0xf bank_mask:0xf
	v_mul_f32_dpp v66, v66, v66 row_shr:1 row_mask:0xf bank_mask:0xf
	v_mul_f32_dpp v67, v67, v67 row_shr:1 row_mask:0xf bank_mask:0xf
	v_mul_f32_dpp v68, v68, v68 row_shr:1 row_mask:0xf bank_mask:0xf
	v_mul_f32_dpp v69, v69, v69 row_shr:1 row_mask:0xf bank_mask:0xf
	v_add_f32_dpp v204, v204, v204 row_shr:1 row_mask:0xf bank_mask:0xf
	v_add_f32_dpp v205, v205, v205 row_shr:1 row_mask:0xf bank_mask:0xf
	v_add_f32_dpp v206, v206, v206 row_shr:1 row_mask:0xf bank_mask:0xf
	v_add_f32_dpp v207, v207, v207 row_shr:1 row_mask:0xf bank_mask:0xf
	v_add_f32_dpp v220, v220, v220 row_shr:1 row_mask:0xf bank_mask:0xf
	v_add_f32_dpp v221, v221, v221 row_shr:1 row_mask:0xf bank_mask:0xf
	v_add_f32_dpp v222, v222, v222 row_shr:1 row_mask:0xf bank_mask:0xf
	v_add_f32_dpp v223, v223, v223 row_shr:1 row_mask:0xf bank_mask:0xf
	v_fmac_f32_dpp v216, v216, v58 row_shr:2 row_mask:0xf bank_mask:0xf
	v_fmac_f32_dpp v217, v217, v59 row_shr:2 row_mask:0xf bank_mask:0xf
	v_fmac_f32_dpp v218, v218, v60 row_shr:2 row_mask:0xf bank_mask:0xf
	v_fmac_f32_dpp v219, v219, v61 row_shr:2 row_mask:0xf bank_mask:0xf
	v_fmac_f32_dpp v240, v240, v66 row_shr:2 row_mask:0xf bank_mask:0xf
	v_fmac_f32_dpp v241, v241, v67 row_shr:2 row_mask:0xf bank_mask:0xf
	v_fmac_f32_dpp v242, v242, v68 row_shr:2 row_mask:0xf bank_mask:0xf
	v_fmac_f32_dpp v243, v243, v69 row_shr:2 row_mask:0xf bank_mask:0xf
	v_mul_f32_dpp v58, v58, v58 row_shr:2 row_mask:0xf bank_mask:0xf
	v_mul_f32_dpp v59, v59, v59 row_shr:2 row_mask:0xf bank_mask:0xf
	v_mul_f32_dpp v60, v60, v60 row_shr:2 row_mask:0xf bank_mask:0xf
	v_mul_f32_dpp v61, v61, v61 row_shr:2 row_mask:0xf bank_mask:0xf
	v_mul_f32_dpp v66, v66, v66 row_shr:2 row_mask:0xf bank_mask:0xf
	v_mul_f32_dpp v67, v67, v67 row_shr:2 row_mask:0xf bank_mask:0xf
	v_mul_f32_dpp v68, v68, v68 row_shr:2 row_mask:0xf bank_mask:0xf
	v_mul_f32_dpp v69, v69, v69 row_shr:2 row_mask:0xf bank_mask:0xf
	v_add_f32_dpp v204, v204, v204 row_shr:2 row_mask:0xf bank_mask:0xf
	v_add_f32_dpp v205, v205, v205 row_shr:2 row_mask:0xf bank_mask:0xf
	v_add_f32_dpp v206, v206, v206 row_shr:2 row_mask:0xf bank_mask:0xf
	v_add_f32_dpp v207, v207, v207 row_shr:2 row_mask:0xf bank_mask:0xf
	v_add_f32_dpp v220, v220, v220 row_shr:2 row_mask:0xf bank_mask:0xf
	v_add_f32_dpp v221, v221, v221 row_shr:2 row_mask:0xf bank_mask:0xf
	v_add_f32_dpp v222, v222, v222 row_shr:2 row_mask:0xf bank_mask:0xf
	v_add_f32_dpp v223, v223, v223 row_shr:2 row_mask:0xf bank_mask:0xf
	v_fmac_f32_dpp v216, v216, v58 row_shr:4 row_mask:0xf bank_mask:0xf
	v_fmac_f32_dpp v217, v217, v59 row_shr:4 row_mask:0xf bank_mask:0xf
	v_fmac_f32_dpp v218, v218, v60 row_shr:4 row_mask:0xf bank_mask:0xf
	v_fmac_f32_dpp v219, v219, v61 row_shr:4 row_mask:0xf bank_mask:0xf
	v_fmac_f32_dpp v240, v240, v66 row_shr:4 row_mask:0xf bank_mask:0xf
	v_fmac_f32_dpp v241, v241, v67 row_shr:4 row_mask:0xf bank_mask:0xf
	v_fmac_f32_dpp v242, v242, v68 row_shr:4 row_mask:0xf bank_mask:0xf
	v_fmac_f32_dpp v243, v243, v69 row_shr:4 row_mask:0xf bank_mask:0xf
	v_mul_f32_dpp v58, v58, v58 row_shr:4 row_mask:0xf bank_mask:0xf
	v_mul_f32_dpp v59, v59, v59 row_shr:4 row_mask:0xf bank_mask:0xf
	v_mul_f32_dpp v60, v60, v60 row_shr:4 row_mask:0xf bank_mask:0xf
	v_mul_f32_dpp v61, v61, v61 row_shr:4 row_mask:0xf bank_mask:0xf
	v_mul_f32_dpp v66, v66, v66 row_shr:4 row_mask:0xf bank_mask:0xf
; __device__ __forceinline__ float bf_lo(unsigned w) { return __uint_as_float(w << 16); }
; __device__ __forceinline__ float bf_hi(unsigned w) { return __uint_as_float(w & 0xffff0000u); }
; __device__ __forceinline__ float fexp(float x) { return __builtin_amdgcn_exp2f(1.44269504f * x); }
;     __device__ __forceinline__ void operator()(AccMut acc, const Unit& u, int sw) const {
;     ...
;                 float bt[8];
; #pragma unroll
;                 for (int n = 0; n < 2; ++n)
; #pragma unroll
;                     for (int jp = 0; jp < 2; ++jp) {
;                         const f32x2 z = (f32x2){acc[ai][1][m][n][2 * jp], acc[ai][1][m][n][2 * jp + 1]} * (-1.44269504f);
;                         f32x2 e; e.x = __builtin_amdgcn_exp2f(z.x); e.y = __builtin_amdgcn_exp2f(z.y); e = e + 1.0f;
;                         f32x2 ig; ig.x = __builtin_amdgcn_rcpf(e.x); ig.y = __builtin_amdgcn_rcpf(e.y);
;                         const f32x2 x2 = (f32x2){acc[ai][0][m][n][2 * jp], acc[ai][0][m][n][2 * jp + 1]} * 2.0f;
;                         f32x2 ser = x2 * (1.0f / 120.0f) + (1.0f / 24.0f); ser = ser * x2 + (1.0f / 6.0f); ser = ser * x2 + 0.5f; ser = ser * x2 + 1.0f; ser = ser * (-x2);
;                         f32x2 em = ser;
;                         if (__builtin_expect(__builtin_amdgcn_ballot_w64(x2.x <= -0.25f || x2.y <= -0.25f) != 0ull, 0)) {
;                             em.x = (x2.x > -0.25f) ? ser.x : (1.0f - fexp(x2.x)); em.y = (x2.y > -0.25f) ? ser.y : (1.0f - fexp(x2.y)); }
;                         const unsigned wv = xw[2 * n + jp];
;                         f32x2 sq; sq.x = __builtin_amdgcn_sqrtf(em.x); sq.y = __builtin_amdgcn_sqrtf(em.y);
; __device__ __forceinline__ void scan1_phase(const bf16_t* LA, const bf16_t* BT, int sw, View vw) {
;     ...
;             for (int i = 0; i < 8; ++i) {
;                 const float l0 = bf_lo(lw[i].x), l1 = bf_hi(lw[i].x), l2 = bf_lo(lw[i].y), l3 = bf_hi(lw[i].y);
;                 S[0] += l0; S[1] += l1; S[2] += l2; S[3] += l3;
;                 Hc[0] = fexp(l0) * Hc[0] + bf_lo(bw[i].x); Hc[1] = fexp(l1) * Hc[1] + bf_hi(bw[i].x); Hc[2] = fexp(l2) * Hc[2] + bf_lo(bw[i].y); Hc[3] = fexp(l3) * Hc[3] + bf_hi(bw[i].y); }
;         }
;         *(f32x4*)(CP + (size_t)bq * E + 4 * quad) = (f32x4){S[0], S[1], S[2], S[3]};
;         *(f32x4*)(CH + (size_t)bq * E + 4 * quad) = (f32x4){Hc[0], Hc[1], Hc[2], Hc[3]};
	v_mul_f32_dpp v67, v67, v67 row_shr:4 row_mask:0xf bank_mask:0xf
	v_mul_f32_dpp v68, v68, v68 row_shr:4 row_mask:0xf bank_mask:0xf
	v_mul_f32_dpp v69, v69, v69 row_shr:4 row_mask:0xf bank_mask:0xf
	v_add_f32_dpp v204, v204, v204 row_shr:4 row_mask:0xf bank_mask:0xf
	v_add_f32_dpp v205, v205, v205 row_shr:4 row_mask:0xf bank_mask:0xf
	v_add_f32_dpp v206, v206, v206 row_shr:4 row_mask:0xf bank_mask:0xf
	v_add_f32_dpp v207, v207, v207 row_shr:4 row_mask:0xf bank_mask:0xf
	v_add_f32_dpp v220, v220, v220 row_shr:4 row_mask:0xf bank_mask:0xf
	v_add_f32_dpp v221, v221, v221 row_shr:4 row_mask:0xf bank_mask:0xf
	v_add_f32_dpp v222, v222, v222 row_shr:4 row_mask:0xf bank_mask:0xf
	v_add_f32_dpp v223, v223, v223 row_shr:4 row_mask:0xf bank_mask:0xf
	v_fmac_f32_dpp v216, v216, v58 row_shr:8 row_mask:0xf bank_mask:0xf
	v_fmac_f32_dpp v217, v217, v59 row_shr:8 row_mask:0xf bank_mask:0xf
	v_fmac_f32_dpp v218, v218, v60 row_shr:8 row_mask:0xf bank_mask:0xf
	v_fmac_f32_dpp v219, v219, v61 row_shr:8 row_mask:0xf bank_mask:0xf
	v_fmac_f32_dpp v240, v240, v66 row_shr:8 row_mask:0xf bank_mask:0xf
	v_fmac_f32_dpp v241, v241, v67 row_shr:8 row_mask:0xf bank_mask:0xf
	v_fmac_f32_dpp v242, v242, v68 row_shr:8 row_mask:0xf bank_mask:0xf
	v_fmac_f32_dpp v243, v243, v69 row_shr:8 row_mask:0xf bank_mask:0xf
	v_add_f32_dpp v204, v204, v204 row_shr:8 row_mask:0xf bank_mask:0xf
	v_add_f32_dpp v205, v205, v205 row_shr:8 row_mask:0xf bank_mask:0xf
	v_add_f32_dpp v206, v206, v206 row_shr:8 row_mask:0xf bank_mask:0xf
	v_add_f32_dpp v207, v207, v207 row_shr:8 row_mask:0xf bank_mask:0xf
	v_add_f32_dpp v220, v220, v220 row_shr:8 row_mask:0xf bank_mask:0xf
	v_add_f32_dpp v221, v221, v221 row_shr:8 row_mask:0xf bank_mask:0xf
	v_add_f32_dpp v222, v222, v222 row_shr:8 row_mask:0xf bank_mask:0xf
	v_add_f32_dpp v223, v223, v223 row_shr:8 row_mask:0xf bank_mask:0xf
	v_mbcnt_lo_u32_b32 v180, -1, 0
	v_mbcnt_hi_u32_b32 v180, -1, v180
	v_and_b32_e32 v180, 15, v180
	v_cmp_eq_u32_e32 vcc, 15, v180
	v_add_u32_e32 v181, 0x0, v239
	v_add_u32_e32 v182, 0x400000, v239
	s_mov_b64 exec, vcc
	global_store_dwordx4 v181, v[204:207], s[26:27]
	global_store_dwordx4 v181, v[220:223], s[26:27] offset:16
	global_store_dwordx4 v182, v[216:219], s[26:27]
	global_store_dwordx4 v182, v[240:243], s[26:27] offset:16
	s_mov_b64 exec, -1
	v_pk_mul_f32 v[180:181], v[26:27], s[74:75] op_sel_hi:[1,0]
	v_pk_mul_f32 v[182:183], v[28:29], s[74:75] op_sel_hi:[1,0]
	v_pk_mul_f32 v[184:185], v[30:31], s[74:75] op_sel_hi:[1,0]
	v_pk_mul_f32 v[186:187], v[32:33], s[74:75] op_sel_hi:[1,0]
	v_exp_f32_e32 v180, v180
	v_exp_f32_e32 v181, v181
	v_exp_f32_e32 v182, v182
	v_exp_f32_e32 v183, v183
	v_exp_f32_e32 v184, v184
	v_exp_f32_e32 v185, v185
	v_exp_f32_e32 v186, v186
	v_exp_f32_e32 v187, v187
	v_pk_fma_f32 v[188:189], v[110:111], s[24:25], v[236:237] op_sel_hi:[1,0,0]
	v_pk_fma_f32 v[190:191], v[112:113], s[24:25], v[236:237] op_sel_hi:[1,0,0]
	v_pk_fma_f32 v[192:193], v[102:103], s[24:25], v[236:237] op_sel_hi:[1,0,0]
	v_pk_fma_f32 v[194:195], v[104:105], s[24:25], v[236:237] op_sel_hi:[1,0,0]
	v_pk_add_f32 v[180:181], v[180:181], 1.0 op_sel_hi:[1,0]
	v_pk_add_f32 v[182:183], v[182:183], 1.0 op_sel_hi:[1,0]
	v_pk_add_f32 v[184:185], v[184:185], 1.0 op_sel_hi:[1,0]
	v_pk_add_f32 v[186:187], v[186:187], 1.0 op_sel_hi:[1,0]
	v_rcp_f32_e32 v180, v180
	v_rcp_f32_e32 v181, v181
	v_rcp_f32_e32 v182, v182
	v_rcp_f32_e32 v183, v183
	v_rcp_f32_e32 v184, v184
	v_rcp_f32_e32 v185, v185
	v_rcp_f32_e32 v186, v186
	v_rcp_f32_e32 v187, v187
	v_pk_fma_f32 v[188:189], v[110:111], v[188:189], s[22:23] op_sel_hi:[1,1,0]
	v_pk_fma_f32 v[190:191], v[112:113], v[190:191], s[22:23] op_sel_hi:[1,1,0]
	v_pk_fma_f32 v[192:193], v[102:103], v[192:193], s[22:23] op_sel_hi:[1,1,0]
	v_pk_fma_f32 v[194:195], v[104:105], v[194:195], s[22:23] op_sel_hi:[1,1,0]
	v_pk_fma_f32 v[188:189], v[110:111], v[188:189], -2.0 op_sel_hi:[1,1,0]
	v_pk_fma_f32 v[190:191], v[112:113], v[190:191], -2.0 op_sel_hi:[1,1,0]
	v_pk_fma_f32 v[192:193], v[102:103], v[192:193], -2.0 op_sel_hi:[1,1,0]
	v_pk_fma_f32 v[194:195], v[104:105], v[194:195], -2.0 op_sel_hi:[1,1,0]
	v_pk_fma_f32 v[188:189], v[110:111], v[188:189], -2.0 op_sel_hi:[1,1,0]
	v_pk_fma_f32 v[190:191], v[112:113], v[190:191], -2.0 op_sel_hi:[1,1,0]
	v_pk_fma_f32 v[192:193], v[102:103], v[192:193], -2.0 op_sel_hi:[1,1,0]
	v_pk_fma_f32 v[194:195], v[104:105], v[194:195], -2.0 op_sel_hi:[1,1,0]
	v_pk_mul_f32 v[188:189], v[110:111], v[188:189]
	v_pk_mul_f32 v[190:191], v[112:113], v[190:191]
	v_pk_mul_f32 v[192:193], v[102:103], v[192:193]
	v_pk_mul_f32 v[194:195], v[104:105], v[194:195]
	v_mul_f32_e32 v196, s17, v110
	v_mul_f32_e32 v197, s17, v111
	v_mul_f32_e32 v198, s17, v112
	v_mul_f32_e32 v199, s17, v113
	v_mul_f32_e32 v200, s17, v102
	v_mul_f32_e32 v201, s17, v103
	v_mul_f32_e32 v202, s17, v104
	v_mul_f32_e32 v203, s17, v105
	v_exp_f32_e32 v196, v196
	v_exp_f32_e32 v197, v197
	v_exp_f32_e32 v198, v198
	v_exp_f32_e32 v199, v199
	v_exp_f32_e32 v200, v200
	v_exp_f32_e32 v201, v201
	v_exp_f32_e32 v202, v202
	v_exp_f32_e32 v203, v203
	v_pk_add_f32 v[196:197], v[196:197], 1.0 op_sel_hi:[1,0] neg_lo:[1,0] neg_hi:[1,0]
	v_pk_add_f32 v[198:199], v[198:199], 1.0 op_sel_hi:[1,0] neg_lo:[1,0] neg_hi:[1,0]
	v_pk_add_f32 v[200:201], v[200:201], 1.0 op_sel_hi:[1,0] neg_lo:[1,0] neg_hi:[1,0]
	v_pk_add_f32 v[202:203], v[202:203], 1.0 op_sel_hi:[1,0] neg_lo:[1,0] neg_hi:[1,0]
	v_cmp_lt_f32_e32 vcc, s13, v110
	s_nop 1
	v_cndmask_b32_e32 v188, v196, v188, vcc
	v_cmp_lt_f32_e32 vcc, s13, v111
	s_nop 1
	v_cndmask_b32_e32 v189, v197, v189, vcc
	v_cmp_lt_f32_e32 vcc, s13, v112
	s_nop 1
	v_cndmask_b32_e32 v190, v198, v190, vcc
	v_cmp_lt_f32_e32 vcc, s13, v113
	s_nop 1
	v_cndmask_b32_e32 v191, v199, v191, vcc
	v_cmp_lt_f32_e32 vcc, s13, v102
	s_nop 1
	v_cndmask_b32_e32 v192, v200, v192, vcc
	v_cmp_lt_f32_e32 vcc, s13, v103
	s_nop 1
	v_cndmask_b32_e32 v193, v201, v193, vcc
	v_cmp_lt_f32_e32 vcc, s13, v104
	s_nop 1
	v_cndmask_b32_e32 v194, v202, v194, vcc
	v_cmp_lt_f32_e32 vcc, s13, v105
	s_nop 1
	v_cndmask_b32_e32 v195, v203, v195, vcc
	v_pk_mul_f32 v[228:229], v[110:111], s[74:75] op_sel_hi:[1,0] neg_lo:[0,1] neg_hi:[0,1]
	v_pk_mul_f32 v[230:231], v[112:113], s[74:75] op_sel_hi:[1,0] neg_lo:[0,1] neg_hi:[0,1]
	v_pk_mul_f32 v[232:233], v[102:103], s[74:75] op_sel_hi:[1,0] neg_lo:[0,1] neg_hi:[0,1]
	v_pk_mul_f32 v[234:235], v[104:105], s[74:75] op_sel_hi:[1,0] neg_lo:[0,1] neg_hi:[0,1]
	v_sqrt_f32_e32 v188, v188
	v_sqrt_f32_e32 v189, v189
	v_sqrt_f32_e32 v190, v190
	v_sqrt_f32_e32 v191, v191
	v_sqrt_f32_e32 v192, v192
	v_sqrt_f32_e32 v193, v193
	v_sqrt_f32_e32 v194, v194
	v_sqrt_f32_e32 v195, v195
	v_exp_f32_e32 v26, v228
	v_exp_f32_e32 v27, v229
	v_exp_f32_e32 v28, v230
	v_exp_f32_e32 v29, v231
	v_exp_f32_e32 v30, v232
	v_exp_f32_e32 v31, v233
	v_exp_f32_e32 v32, v234
	v_exp_f32_e32 v33, v235
	s_waitcnt vmcnt(19)
; __device__ __forceinline__ unsigned cvt_pk_bf16(float lo, float hi) { unsigned r; asm volatile("v_cvt_pk_bf16_f32 %0, %1, %2" : "=v"(r) : "v"(lo), "v"(hi)); return r; }
; __device__ __forceinline__ float bf_lo(unsigned w) { return __uint_as_float(w << 16); }
; __device__ __forceinline__ float bf_hi(unsigned w) { return __uint_as_float(w & 0xffff0000u); }
; __device__ __forceinline__ float fexp(float x) { return __builtin_amdgcn_exp2f(1.44269504f * x); }
;     __device__ __forceinline__ void operator()(AccMut acc, const Unit& u, int sw) const {
;     ...
;                 float bt[8];
; #pragma unroll
;                 for (int n = 0; n < 2; ++n)
; #pragma unroll
;                     for (int jp = 0; jp < 2; ++jp) {
;                         const f32x2 z = (f32x2){acc[ai][1][m][n][2 * jp], acc[ai][1][m][n][2 * jp + 1]} * (-1.44269504f);
;                         f32x2 e; e.x = __builtin_amdgcn_exp2f(z.x); e.y = __builtin_amdgcn_exp2f(z.y); e = e + 1.0f;
;                         f32x2 ig; ig.x = __builtin_amdgcn_rcpf(e.x); ig.y = __builtin_amdgcn_rcpf(e.y);
;                         const f32x2 x2 = (f32x2){acc[ai][0][m][n][2 * jp], acc[ai][0][m][n][2 * jp + 1]} * 2.0f;
;                         f32x2 ser = x2 * (1.0f / 120.0f) + (1.0f / 24.0f); ser = ser * x2 + (1.0f / 6.0f); ser = ser * x2 + 0.5f; ser = ser * x2 + 1.0f; ser = ser * (-x2);
;                         f32x2 em = ser;
;                         if (__builtin_expect(__builtin_amdgcn_ballot_w64(x2.x <= -0.25f || x2.y <= -0.25f) != 0ull, 0)) {
;                             em.x = (x2.x > -0.25f) ? ser.x : (1.0f - fexp(x2.x)); em.y = (x2.y > -0.25f) ? ser.y : (1.0f - fexp(x2.y)); }
;                         const unsigned wv = xw[2 * n + jp];
;                         f32x2 sq; sq.x = __builtin_amdgcn_sqrtf(em.x); sq.y = __builtin_amdgcn_sqrtf(em.y);
;                         const f32x2 b2 = sq * ig * (f32x2){bf_lo(wv), bf_hi(wv)};
;                         bt[4 * n + 2 * jp] = b2.x; bt[4 * n + 2 * jp + 1] = b2.y; }
;                 u32x4 w; w.x = cvt_pk_bf16(bt[0], bt[1]); w.y = cvt_pk_bf16(bt[2], bt[3]); w.z = cvt_pk_bf16(bt[4], bt[5]); w.w = cvt_pk_bf16(bt[6], bt[7]);
;                 *(u32x4*)(BT + off) = w; }
	v_lshlrev_b32_e32 v196, 16, v152
	v_and_b32_e32 v197, 0xffff0000, v152
	v_lshlrev_b32_e32 v198, 16, v153
	v_and_b32_e32 v199, 0xffff0000, v153
	v_lshlrev_b32_e32 v200, 16, v154
	v_and_b32_e32 v201, 0xffff0000, v154
	v_lshlrev_b32_e32 v202, 16, v155
	v_and_b32_e32 v203, 0xffff0000, v155
	v_pk_mul_f32 v[188:189], v[188:189], v[180:181]
	v_pk_mul_f32 v[190:191], v[190:191], v[182:183]
	v_pk_mul_f32 v[192:193], v[192:193], v[184:185]
	v_pk_mul_f32 v[194:195], v[194:195], v[186:187]
	v_pk_mul_f32 v[216:217], v[188:189], v[196:197]
	v_pk_mul_f32 v[218:219], v[190:191], v[198:199]
	v_pk_mul_f32 v[240:241], v[192:193], v[200:201]
	v_pk_mul_f32 v[242:243], v[194:195], v[202:203]
	v_cvt_pk_bf16_f32 v208, v216, v217
	v_cvt_pk_bf16_f32 v209, v218, v219
	v_cvt_pk_bf16_f32 v210, v240, v241
	v_cvt_pk_bf16_f32 v211, v242, v243
	global_store_dwordx4 v176, v[208:211], s[10:11]
	v_pk_mul_f32 v[180:181], v[18:19], s[74:75] op_sel_hi:[1,0]
	v_pk_mul_f32 v[182:183], v[20:21], s[74:75] op_sel_hi:[1,0]
	v_pk_mul_f32 v[184:185], v[22:23], s[74:75] op_sel_hi:[1,0]
	v_pk_mul_f32 v[186:187], v[24:25], s[74:75] op_sel_hi:[1,0]
	v_exp_f32_e32 v180, v180
	v_exp_f32_e32 v181, v181
	v_exp_f32_e32 v182, v182
	v_exp_f32_e32 v183, v183
	v_exp_f32_e32 v184, v184
	v_exp_f32_e32 v185, v185
	v_exp_f32_e32 v186, v186
	v_exp_f32_e32 v187, v187
	v_pk_fma_f32 v[188:189], v[98:99], s[24:25], v[236:237] op_sel_hi:[1,0,0]
	v_pk_fma_f32 v[190:191], v[100:101], s[24:25], v[236:237] op_sel_hi:[1,0,0]
	v_pk_fma_f32 v[192:193], v[94:95], s[24:25], v[236:237] op_sel_hi:[1,0,0]
	v_pk_fma_f32 v[194:195], v[96:97], s[24:25], v[236:237] op_sel_hi:[1,0,0]
	v_pk_add_f32 v[180:181], v[180:181], 1.0 op_sel_hi:[1,0]
	v_pk_add_f32 v[182:183], v[182:183], 1.0 op_sel_hi:[1,0]
	v_pk_add_f32 v[184:185], v[184:185], 1.0 op_sel_hi:[1,0]
	v_pk_add_f32 v[186:187], v[186:187], 1.0 op_sel_hi:[1,0]
	v_rcp_f32_e32 v180, v180
	v_rcp_f32_e32 v181, v181
	v_rcp_f32_e32 v182, v182
	v_rcp_f32_e32 v183, v183
	v_rcp_f32_e32 v184, v184
	v_rcp_f32_e32 v185, v185
	v_rcp_f32_e32 v186, v186
	v_rcp_f32_e32 v187, v187
	v_pk_fma_f32 v[188:189], v[98:99], v[188:189], s[22:23] op_sel_hi:[1,1,0]
	v_pk_fma_f32 v[190:191], v[100:101], v[190:191], s[22:23] op_sel_hi:[1,1,0]
	v_pk_fma_f32 v[192:193], v[94:95], v[192:193], s[22:23] op_sel_hi:[1,1,0]
	v_pk_fma_f32 v[194:195], v[96:97], v[194:195], s[22:23] op_sel_hi:[1,1,0]
	v_pk_fma_f32 v[188:189], v[98:99], v[188:189], -2.0 op_sel_hi:[1,1,0]
	v_pk_fma_f32 v[190:191], v[100:101], v[190:191], -2.0 op_sel_hi:[1,1,0]
	v_pk_fma_f32 v[192:193], v[94:95], v[192:193], -2.0 op_sel_hi:[1,1,0]
	v_pk_fma_f32 v[194:195], v[96:97], v[194:195], -2.0 op_sel_hi:[1,1,0]
	v_pk_fma_f32 v[188:189], v[98:99], v[188:189], -2.0 op_sel_hi:[1,1,0]
	v_pk_fma_f32 v[190:191], v[100:101], v[190:191], -2.0 op_sel_hi:[1,1,0]
	v_pk_fma_f32 v[192:193], v[94:95], v[192:193], -2.0 op_sel_hi:[1,1,0]
	v_pk_fma_f32 v[194:195], v[96:97], v[194:195], -2.0 op_sel_hi:[1,1,0]
	v_pk_mul_f32 v[188:189], v[98:99], v[188:189]
	v_pk_mul_f32 v[190:191], v[100:101], v[190:191]
	v_pk_mul_f32 v[192:193], v[94:95], v[192:193]
	v_pk_mul_f32 v[194:195], v[96:97], v[194:195]
	v_mul_f32_e32 v196, s17, v98
	v_mul_f32_e32 v197, s17, v99
	v_mul_f32_e32 v198, s17, v100
	v_mul_f32_e32 v199, s17, v101
	v_mul_f32_e32 v200, s17, v94
	v_mul_f32_e32 v201, s17, v95
	v_mul_f32_e32 v202, s17, v96
	v_mul_f32_e32 v203, s17, v97
	v_exp_f32_e32 v196, v196
	v_exp_f32_e32 v197, v197
	v_exp_f32_e32 v198, v198
	v_exp_f32_e32 v199, v199
	v_exp_f32_e32 v200, v200
	v_exp_f32_e32 v201, v201
	v_exp_f32_e32 v202, v202
	v_exp_f32_e32 v203, v203
	v_pk_add_f32 v[196:197], v[196:197], 1.0 op_sel_hi:[1,0] neg_lo:[1,0] neg_hi:[1,0]
	v_pk_add_f32 v[198:199], v[198:199], 1.0 op_sel_hi:[1,0] neg_lo:[1,0] neg_hi:[1,0]
	v_pk_add_f32 v[200:201], v[200:201], 1.0 op_sel_hi:[1,0] neg_lo:[1,0] neg_hi:[1,0]
	v_pk_add_f32 v[202:203], v[202:203], 1.0 op_sel_hi:[1,0] neg_lo:[1,0] neg_hi:[1,0]
	v_cmp_lt_f32_e32 vcc, s13, v98
	s_nop 1
	v_cndmask_b32_e32 v188, v196, v188, vcc
	v_cmp_lt_f32_e32 vcc, s13, v99
	s_nop 1
	v_cndmask_b32_e32 v189, v197, v189, vcc
	v_cmp_lt_f32_e32 vcc, s13, v100
	s_nop 1
	v_cndmask_b32_e32 v190, v198, v190, vcc
	v_cmp_lt_f32_e32 vcc, s13, v101
	s_nop 1
	v_cndmask_b32_e32 v191, v199, v191, vcc
	v_cmp_lt_f32_e32 vcc, s13, v94
	s_nop 1
	v_cndmask_b32_e32 v192, v200, v192, vcc
	v_cmp_lt_f32_e32 vcc, s13, v95
	s_nop 1
	v_cndmask_b32_e32 v193, v201, v193, vcc
	v_cmp_lt_f32_e32 vcc, s13, v96
	s_nop 1
	v_cndmask_b32_e32 v194, v202, v194, vcc
	v_cmp_lt_f32_e32 vcc, s13, v97
	s_nop 1
	v_cndmask_b32_e32 v195, v203, v195, vcc
	v_pk_mul_f32 v[228:229], v[98:99], s[74:75] op_sel_hi:[1,0] neg_lo:[0,1] neg_hi:[0,1]
	v_pk_mul_f32 v[230:231], v[100:101], s[74:75] op_sel_hi:[1,0] neg_lo:[0,1] neg_hi:[0,1]
	v_pk_mul_f32 v[232:233], v[94:95], s[74:75] op_sel_hi:[1,0] neg_lo:[0,1] neg_hi:[0,1]
	v_pk_mul_f32 v[234:235], v[96:97], s[74:75] op_sel_hi:[1,0] neg_lo:[0,1] neg_hi:[0,1]
	v_sqrt_f32_e32 v188, v188
	v_sqrt_f32_e32 v189, v189
	v_sqrt_f32_e32 v190, v190
	v_sqrt_f32_e32 v191, v191
	v_sqrt_f32_e32 v192, v192
	v_sqrt_f32_e32 v193, v193
	v_sqrt_f32_e32 v194, v194
	v_sqrt_f32_e32 v195, v195
	v_exp_f32_e32 v228, v228
	v_exp_f32_e32 v229, v229
	v_exp_f32_e32 v230, v230
	v_exp_f32_e32 v231, v231
	v_exp_f32_e32 v232, v232
	v_exp_f32_e32 v233, v233
	v_exp_f32_e32 v234, v234
	v_exp_f32_e32 v235, v235
	s_waitcnt vmcnt(19)
; __device__ __forceinline__ unsigned cvt_pk_bf16(float lo, float hi) { unsigned r; asm volatile("v_cvt_pk_bf16_f32 %0, %1, %2" : "=v"(r) : "v"(lo), "v"(hi)); return r; }
; __device__ __forceinline__ float bf_lo(unsigned w) { return __uint_as_float(w << 16); }
; __device__ __forceinline__ float bf_hi(unsigned w) { return __uint_as_float(w & 0xffff0000u); }
; __device__ __forceinline__ float fexp(float x) { return __builtin_amdgcn_exp2f(1.44269504f * x); }
;     __device__ __forceinline__ void operator()(AccMut acc, const Unit& u, int sw) const {
;     ...
;                         const unsigned wv = xw[2 * n + jp];
;                         f32x2 sq; sq.x = __builtin_amdgcn_sqrtf(em.x); sq.y = __builtin_amdgcn_sqrtf(em.y);
;                         const f32x2 b2 = sq * ig * (f32x2){bf_lo(wv), bf_hi(wv)};
;                         bt[4 * n + 2 * jp] = b2.x; bt[4 * n + 2 * jp + 1] = b2.y; }
;                 u32x4 w; w.x = cvt_pk_bf16(bt[0], bt[1]); w.y = cvt_pk_bf16(bt[2], bt[3]); w.z = cvt_pk_bf16(bt[4], bt[5]); w.w = cvt_pk_bf16(bt[6], bt[7]);
;                 *(u32x4*)(BT + off) = w; }
; __device__ __forceinline__ void scan1_phase(const bf16_t* LA, const bf16_t* BT, int sw, View vw) {
;     ...
;             for (int i = 0; i < 8; ++i) {
;                 const float l0 = bf_lo(lw[i].x), l1 = bf_hi(lw[i].x), l2 = bf_lo(lw[i].y), l3 = bf_hi(lw[i].y);
;                 S[0] += l0; S[1] += l1; S[2] += l2; S[3] += l3;
;                 Hc[0] = fexp(l0) * Hc[0] + bf_lo(bw[i].x); Hc[1] = fexp(l1) * Hc[1] + bf_hi(bw[i].x); Hc[2] = fexp(l2) * Hc[2] + bf_lo(bw[i].y); Hc[3] = fexp(l3) * Hc[3] + bf_hi(bw[i].y); }
	v_lshlrev_b32_e32 v196, 16, v156
	v_and_b32_e32 v197, 0xffff0000, v156
	v_lshlrev_b32_e32 v198, 16, v157
	v_and_b32_e32 v199, 0xffff0000, v157
	v_lshlrev_b32_e32 v200, 16, v158
	v_and_b32_e32 v201, 0xffff0000, v158
	v_lshlrev_b32_e32 v202, 16, v159
	v_and_b32_e32 v203, 0xffff0000, v159
	v_pk_mul_f32 v[188:189], v[188:189], v[180:181]
	v_pk_mul_f32 v[190:191], v[190:191], v[182:183]
	v_pk_mul_f32 v[192:193], v[192:193], v[184:185]
	v_pk_mul_f32 v[194:195], v[194:195], v[186:187]
	v_pk_mul_f32 v[188:189], v[188:189], v[196:197]
	v_pk_mul_f32 v[190:191], v[190:191], v[198:199]
	v_pk_mul_f32 v[192:193], v[192:193], v[200:201]
	v_pk_mul_f32 v[194:195], v[194:195], v[202:203]
	v_cvt_pk_bf16_f32 v212, v188, v189
	v_cvt_pk_bf16_f32 v213, v190, v191
	v_cvt_pk_bf16_f32 v214, v192, v193
	v_cvt_pk_bf16_f32 v215, v194, v195
	global_store_dwordx4 v177, v[212:215], s[10:11]
	v_pk_fma_f32 v[216:217], v[228:229], v[216:217], v[188:189]
	v_pk_fma_f32 v[218:219], v[230:231], v[218:219], v[190:191]
	v_pk_fma_f32 v[240:241], v[232:233], v[240:241], v[192:193]
	v_pk_fma_f32 v[242:243], v[234:235], v[242:243], v[194:195]
	v_pk_mul_f32 v[26:27], v[26:27], v[228:229]
	v_pk_mul_f32 v[28:29], v[28:29], v[230:231]
	v_pk_mul_f32 v[30:31], v[30:31], v[232:233]
	v_pk_mul_f32 v[32:33], v[32:33], v[234:235]
	v_pk_add_f32 v[110:111], v[110:111], v[98:99]
	v_pk_add_f32 v[112:113], v[112:113], v[100:101]
	v_pk_add_f32 v[102:103], v[102:103], v[94:95]
	v_pk_add_f32 v[104:105], v[104:105], v[96:97]
	v_pk_mul_f32 v[180:181], v[10:11], s[74:75] op_sel_hi:[1,0]
	v_pk_mul_f32 v[182:183], v[12:13], s[74:75] op_sel_hi:[1,0]
	v_pk_mul_f32 v[184:185], v[14:15], s[74:75] op_sel_hi:[1,0]
	v_pk_mul_f32 v[186:187], v[16:17], s[74:75] op_sel_hi:[1,0]
	v_exp_f32_e32 v180, v180
	v_exp_f32_e32 v181, v181
	v_exp_f32_e32 v182, v182
	v_exp_f32_e32 v183, v183
	v_exp_f32_e32 v184, v184
	v_exp_f32_e32 v185, v185
	v_exp_f32_e32 v186, v186
	v_exp_f32_e32 v187, v187
	v_pk_fma_f32 v[188:189], v[90:91], s[24:25], v[236:237] op_sel_hi:[1,0,0]
	v_pk_fma_f32 v[190:191], v[92:93], s[24:25], v[236:237] op_sel_hi:[1,0,0]
	v_pk_fma_f32 v[192:193], v[86:87], s[24:25], v[236:237] op_sel_hi:[1,0,0]
	v_pk_fma_f32 v[194:195], v[88:89], s[24:25], v[236:237] op_sel_hi:[1,0,0]
	v_pk_add_f32 v[180:181], v[180:181], 1.0 op_sel_hi:[1,0]
	v_pk_add_f32 v[182:183], v[182:183], 1.0 op_sel_hi:[1,0]
	v_pk_add_f32 v[184:185], v[184:185], 1.0 op_sel_hi:[1,0]
	v_pk_add_f32 v[186:187], v[186:187], 1.0 op_sel_hi:[1,0]
	v_rcp_f32_e32 v180, v180
	v_rcp_f32_e32 v181, v181
	v_rcp_f32_e32 v182, v182
	v_rcp_f32_e32 v183, v183
	v_rcp_f32_e32 v184, v184
	v_rcp_f32_e32 v185, v185
	v_rcp_f32_e32 v186, v186
	v_rcp_f32_e32 v187, v187
	v_pk_fma_f32 v[188:189], v[90:91], v[188:189], s[22:23] op_sel_hi:[1,1,0]
	v_pk_fma_f32 v[190:191], v[92:93], v[190:191], s[22:23] op_sel_hi:[1,1,0]
	v_pk_fma_f32 v[192:193], v[86:87], v[192:193], s[22:23] op_sel_hi:[1,1,0]
	v_pk_fma_f32 v[194:195], v[88:89], v[194:195], s[22:23] op_sel_hi:[1,1,0]
	v_pk_fma_f32 v[188:189], v[90:91], v[188:189], -2.0 op_sel_hi:[1,1,0]
	v_pk_fma_f32 v[190:191], v[92:93], v[190:191], -2.0 op_sel_hi:[1,1,0]
	v_pk_fma_f32 v[192:193], v[86:87], v[192:193], -2.0 op_sel_hi:[1,1,0]
	v_pk_fma_f32 v[194:195], v[88:89], v[194:195], -2.0 op_sel_hi:[1,1,0]
	v_pk_fma_f32 v[188:189], v[90:91], v[188:189], -2.0 op_sel_hi:[1,1,0]
	v_pk_fma_f32 v[190:191], v[92:93], v[190:191], -2.0 op_sel_hi:[1,1,0]
	v_pk_fma_f32 v[192:193], v[86:87], v[192:193], -2.0 op_sel_hi:[1,1,0]
	v_pk_fma_f32 v[194:195], v[88:89], v[194:195], -2.0 op_sel_hi:[1,1,0]
	v_pk_mul_f32 v[188:189], v[90:91], v[188:189]
	v_pk_mul_f32 v[190:191], v[92:93], v[190:191]
	v_pk_mul_f32 v[192:193], v[86:87], v[192:193]
	v_pk_mul_f32 v[194:195], v[88:89], v[194:195]
	v_mul_f32_e32 v196, s17, v90
	v_mul_f32_e32 v197, s17, v91
	v_mul_f32_e32 v198, s17, v92
	v_mul_f32_e32 v199, s17, v93
	v_mul_f32_e32 v200, s17, v86
	v_mul_f32_e32 v201, s17, v87
	v_mul_f32_e32 v202, s17, v88
	v_mul_f32_e32 v203, s17, v89
	v_exp_f32_e32 v196, v196
	v_exp_f32_e32 v197, v197
	v_exp_f32_e32 v198, v198
	v_exp_f32_e32 v199, v199
	v_exp_f32_e32 v200, v200
	v_exp_f32_e32 v201, v201
	v_exp_f32_e32 v202, v202
	v_exp_f32_e32 v203, v203
	v_pk_add_f32 v[196:197], v[196:197], 1.0 op_sel_hi:[1,0] neg_lo:[1,0] neg_hi:[1,0]
	v_pk_add_f32 v[198:199], v[198:199], 1.0 op_sel_hi:[1,0] neg_lo:[1,0] neg_hi:[1,0]
	v_pk_add_f32 v[200:201], v[200:201], 1.0 op_sel_hi:[1,0] neg_lo:[1,0] neg_hi:[1,0]
	v_pk_add_f32 v[202:203], v[202:203], 1.0 op_sel_hi:[1,0] neg_lo:[1,0] neg_hi:[1,0]
	v_cmp_lt_f32_e32 vcc, s13, v90
	s_nop 1
	v_cndmask_b32_e32 v188, v196, v188, vcc
	v_cmp_lt_f32_e32 vcc, s13, v91
	s_nop 1
	v_cndmask_b32_e32 v189, v197, v189, vcc
	v_cmp_lt_f32_e32 vcc, s13, v92
	s_nop 1
	v_cndmask_b32_e32 v190, v198, v190, vcc
	v_cmp_lt_f32_e32 vcc, s13, v93
	s_nop 1
	v_cndmask_b32_e32 v191, v199, v191, vcc
	v_cmp_lt_f32_e32 vcc, s13, v86
	s_nop 1
	v_cndmask_b32_e32 v192, v200, v192, vcc
	v_cmp_lt_f32_e32 vcc, s13, v87
	s_nop 1
	v_cndmask_b32_e32 v193, v201, v193, vcc
	v_cmp_lt_f32_e32 vcc, s13, v88
	s_nop 1
	v_cndmask_b32_e32 v194, v202, v194, vcc
	v_cmp_lt_f32_e32 vcc, s13, v89
	s_nop 1
	v_cndmask_b32_e32 v195, v203, v195, vcc
	v_pk_mul_f32 v[228:229], v[90:91], s[74:75] op_sel_hi:[1,0] neg_lo:[0,1] neg_hi:[0,1]
	v_pk_mul_f32 v[230:231], v[92:93], s[74:75] op_sel_hi:[1,0] neg_lo:[0,1] neg_hi:[0,1]
	v_pk_mul_f32 v[232:233], v[86:87], s[74:75] op_sel_hi:[1,0] neg_lo:[0,1] neg_hi:[0,1]
	v_pk_mul_f32 v[234:235], v[88:89], s[74:75] op_sel_hi:[1,0] neg_lo:[0,1] neg_hi:[0,1]
	v_sqrt_f32_e32 v188, v188
	v_sqrt_f32_e32 v189, v189
	v_sqrt_f32_e32 v190, v190
	v_sqrt_f32_e32 v191, v191
	v_sqrt_f32_e32 v192, v192
	v_sqrt_f32_e32 v193, v193
	v_sqrt_f32_e32 v194, v194
	v_sqrt_f32_e32 v195, v195
	v_exp_f32_e32 v228, v228
	v_exp_f32_e32 v229, v229
	v_exp_f32_e32 v230, v230
	v_exp_f32_e32 v231, v231
	v_exp_f32_e32 v232, v232
	v_exp_f32_e32 v233, v233
	v_exp_f32_e32 v234, v234
	v_exp_f32_e32 v235, v235
	s_waitcnt vmcnt(19)
; __device__ __forceinline__ unsigned cvt_pk_bf16(float lo, float hi) { unsigned r; asm volatile("v_cvt_pk_bf16_f32 %0, %1, %2" : "=v"(r) : "v"(lo), "v"(hi)); return r; }
; __device__ __forceinline__ float bf_lo(unsigned w) { return __uint_as_float(w << 16); }
; __device__ __forceinline__ float bf_hi(unsigned w) { return __uint_as_float(w & 0xffff0000u); }
; __device__ __forceinline__ float fexp(float x) { return __builtin_amdgcn_exp2f(1.44269504f * x); }
;     __device__ __forceinline__ void operator()(AccMut acc, const Unit& u, int sw) const {
;     ...
;                         const unsigned wv = xw[2 * n + jp];
;                         f32x2 sq; sq.x = __builtin_amdgcn_sqrtf(em.x); sq.y = __builtin_amdgcn_sqrtf(em.y);
;                         const f32x2 b2 = sq * ig * (f32x2){bf_lo(wv), bf_hi(wv)};
;                         bt[4 * n + 2 * jp] = b2.x; bt[4 * n + 2 * jp + 1] = b2.y; }
;                 u32x4 w; w.x = cvt_pk_bf16(bt[0], bt[1]); w.y = cvt_pk_bf16(bt[2], bt[3]); w.z = cvt_pk_bf16(bt[4], bt[5]); w.w = cvt_pk_bf16(bt[6], bt[7]);
;                 *(u32x4*)(BT + off) = w; }
; __device__ __forceinline__ void scan1_phase(const bf16_t* LA, const bf16_t* BT, int sw, View vw) {
;     ...
;             for (int i = 0; i < 8; ++i) {
;                 const float l0 = bf_lo(lw[i].x), l1 = bf_hi(lw[i].x), l2 = bf_lo(lw[i].y), l3 = bf_hi(lw[i].y);
;                 S[0] += l0; S[1] += l1; S[2] += l2; S[3] += l3;
;                 Hc[0] = fexp(l0) * Hc[0] + bf_lo(bw[i].x); Hc[1] = fexp(l1) * Hc[1] + bf_hi(bw[i].x); Hc[2] = fexp(l2) * Hc[2] + bf_lo(bw[i].y); Hc[3] = fexp(l3) * Hc[3] + bf_hi(bw[i].y); }
	v_lshlrev_b32_e32 v196, 16, v160
	v_and_b32_e32 v197, 0xffff0000, v160
	v_lshlrev_b32_e32 v198, 16, v161
	v_and_b32_e32 v199, 0xffff0000, v161
	v_lshlrev_b32_e32 v200, 16, v162
	v_and_b32_e32 v201, 0xffff0000, v162
	v_lshlrev_b32_e32 v202, 16, v163
	v_and_b32_e32 v203, 0xffff0000, v163
	v_pk_mul_f32 v[188:189], v[188:189], v[180:181]
	v_pk_mul_f32 v[190:191], v[190:191], v[182:183]
	v_pk_mul_f32 v[192:193], v[192:193], v[184:185]
	v_pk_mul_f32 v[194:195], v[194:195], v[186:187]
	v_pk_mul_f32 v[188:189], v[188:189], v[196:197]
	v_pk_mul_f32 v[190:191], v[190:191], v[198:199]
	v_pk_mul_f32 v[192:193], v[192:193], v[200:201]
	v_pk_mul_f32 v[194:195], v[194:195], v[202:203]
	v_cvt_pk_bf16_f32 v208, v188, v189
	v_cvt_pk_bf16_f32 v209, v190, v191
	v_cvt_pk_bf16_f32 v210, v192, v193
	v_cvt_pk_bf16_f32 v211, v194, v195
	global_store_dwordx4 v178, v[208:211], s[10:11]
	v_pk_fma_f32 v[216:217], v[228:229], v[216:217], v[188:189]
	v_pk_fma_f32 v[218:219], v[230:231], v[218:219], v[190:191]
	v_pk_fma_f32 v[240:241], v[232:233], v[240:241], v[192:193]
	v_pk_fma_f32 v[242:243], v[234:235], v[242:243], v[194:195]
	v_pk_mul_f32 v[26:27], v[26:27], v[228:229]
	v_pk_mul_f32 v[28:29], v[28:29], v[230:231]
	v_pk_mul_f32 v[30:31], v[30:31], v[232:233]
	v_pk_mul_f32 v[32:33], v[32:33], v[234:235]
	v_pk_add_f32 v[110:111], v[110:111], v[90:91]
	v_pk_add_f32 v[112:113], v[112:113], v[92:93]
	v_pk_add_f32 v[102:103], v[102:103], v[86:87]
	v_pk_add_f32 v[104:105], v[104:105], v[88:89]
	v_pk_mul_f32 v[180:181], v[2:3], s[74:75] op_sel_hi:[1,0]
	v_pk_mul_f32 v[182:183], v[4:5], s[74:75] op_sel_hi:[1,0]
	v_pk_mul_f32 v[184:185], v[6:7], s[74:75] op_sel_hi:[1,0]
	v_pk_mul_f32 v[186:187], v[8:9], s[74:75] op_sel_hi:[1,0]
	v_exp_f32_e32 v180, v180
	v_exp_f32_e32 v181, v181
	v_exp_f32_e32 v182, v182
	v_exp_f32_e32 v183, v183
	v_exp_f32_e32 v184, v184
	v_exp_f32_e32 v185, v185
	v_exp_f32_e32 v186, v186
	v_exp_f32_e32 v187, v187
	v_pk_fma_f32 v[188:189], v[74:75], s[24:25], v[236:237] op_sel_hi:[1,0,0]
	v_pk_fma_f32 v[190:191], v[76:77], s[24:25], v[236:237] op_sel_hi:[1,0,0]
	v_pk_fma_f32 v[192:193], v[70:71], s[24:25], v[236:237] op_sel_hi:[1,0,0]
	v_pk_fma_f32 v[194:195], v[72:73], s[24:25], v[236:237] op_sel_hi:[1,0,0]
	v_pk_add_f32 v[180:181], v[180:181], 1.0 op_sel_hi:[1,0]
	v_pk_add_f32 v[182:183], v[182:183], 1.0 op_sel_hi:[1,0]
	v_pk_add_f32 v[184:185], v[184:185], 1.0 op_sel_hi:[1,0]
	v_pk_add_f32 v[186:187], v[186:187], 1.0 op_sel_hi:[1,0]
	v_rcp_f32_e32 v180, v180
	v_rcp_f32_e32 v181, v181
	v_rcp_f32_e32 v182, v182
	v_rcp_f32_e32 v183, v183
	v_rcp_f32_e32 v184, v184
	v_rcp_f32_e32 v185, v185
	v_rcp_f32_e32 v186, v186
	v_rcp_f32_e32 v187, v187
	v_pk_fma_f32 v[188:189], v[74:75], v[188:189], s[22:23] op_sel_hi:[1,1,0]
	v_pk_fma_f32 v[190:191], v[76:77], v[190:191], s[22:23] op_sel_hi:[1,1,0]
	v_pk_fma_f32 v[192:193], v[70:71], v[192:193], s[22:23] op_sel_hi:[1,1,0]
	v_pk_fma_f32 v[194:195], v[72:73], v[194:195], s[22:23] op_sel_hi:[1,1,0]
	v_pk_fma_f32 v[188:189], v[74:75], v[188:189], -2.0 op_sel_hi:[1,1,0]
	v_pk_fma_f32 v[190:191], v[76:77], v[190:191], -2.0 op_sel_hi:[1,1,0]
	v_pk_fma_f32 v[192:193], v[70:71], v[192:193], -2.0 op_sel_hi:[1,1,0]
	v_pk_fma_f32 v[194:195], v[72:73], v[194:195], -2.0 op_sel_hi:[1,1,0]
	v_pk_fma_f32 v[188:189], v[74:75], v[188:189], -2.0 op_sel_hi:[1,1,0]
	v_pk_fma_f32 v[190:191], v[76:77], v[190:191], -2.0 op_sel_hi:[1,1,0]
	v_pk_fma_f32 v[192:193], v[70:71], v[192:193], -2.0 op_sel_hi:[1,1,0]
	v_pk_fma_f32 v[194:195], v[72:73], v[194:195], -2.0 op_sel_hi:[1,1,0]
	v_pk_mul_f32 v[188:189], v[74:75], v[188:189]
	v_pk_mul_f32 v[190:191], v[76:77], v[190:191]
	v_pk_mul_f32 v[192:193], v[70:71], v[192:193]
	v_pk_mul_f32 v[194:195], v[72:73], v[194:195]
	v_mul_f32_e32 v196, s17, v74
	v_mul_f32_e32 v197, s17, v75
	v_mul_f32_e32 v198, s17, v76
	v_mul_f32_e32 v199, s17, v77
	v_mul_f32_e32 v200, s17, v70
	v_mul_f32_e32 v201, s17, v71
	v_mul_f32_e32 v202, s17, v72
	v_mul_f32_e32 v203, s17, v73
	v_exp_f32_e32 v196, v196
	v_exp_f32_e32 v197, v197
	v_exp_f32_e32 v198, v198
	v_exp_f32_e32 v199, v199
	v_exp_f32_e32 v200, v200
	v_exp_f32_e32 v201, v201
	v_exp_f32_e32 v202, v202
	v_exp_f32_e32 v203, v203
	v_pk_add_f32 v[196:197], v[196:197], 1.0 op_sel_hi:[1,0] neg_lo:[1,0] neg_hi:[1,0]
	v_pk_add_f32 v[198:199], v[198:199], 1.0 op_sel_hi:[1,0] neg_lo:[1,0] neg_hi:[1,0]
	v_pk_add_f32 v[200:201], v[200:201], 1.0 op_sel_hi:[1,0] neg_lo:[1,0] neg_hi:[1,0]
	v_pk_add_f32 v[202:203], v[202:203], 1.0 op_sel_hi:[1,0] neg_lo:[1,0] neg_hi:[1,0]
	v_cmp_lt_f32_e32 vcc, s13, v74
	s_nop 1
	v_cndmask_b32_e32 v188, v196, v188, vcc
	v_cmp_lt_f32_e32 vcc, s13, v75
	s_nop 1
	v_cndmask_b32_e32 v189, v197, v189, vcc
	v_cmp_lt_f32_e32 vcc, s13, v76
	s_nop 1
	v_cndmask_b32_e32 v190, v198, v190, vcc
	v_cmp_lt_f32_e32 vcc, s13, v77
	s_nop 1
	v_cndmask_b32_e32 v191, v199, v191, vcc
	v_cmp_lt_f32_e32 vcc, s13, v70
	s_nop 1
	v_cndmask_b32_e32 v192, v200, v192, vcc
	v_cmp_lt_f32_e32 vcc, s13, v71
	s_nop 1
	v_cndmask_b32_e32 v193, v201, v193, vcc
	v_cmp_lt_f32_e32 vcc, s13, v72
	s_nop 1
	v_cndmask_b32_e32 v194, v202, v194, vcc
	v_cmp_lt_f32_e32 vcc, s13, v73
	s_nop 1
	v_cndmask_b32_e32 v195, v203, v195, vcc
	v_pk_mul_f32 v[228:229], v[74:75], s[74:75] op_sel_hi:[1,0] neg_lo:[0,1] neg_hi:[0,1]
	v_pk_mul_f32 v[230:231], v[76:77], s[74:75] op_sel_hi:[1,0] neg_lo:[0,1] neg_hi:[0,1]
	v_pk_mul_f32 v[232:233], v[70:71], s[74:75] op_sel_hi:[1,0] neg_lo:[0,1] neg_hi:[0,1]
	v_pk_mul_f32 v[234:235], v[72:73], s[74:75] op_sel_hi:[1,0] neg_lo:[0,1] neg_hi:[0,1]
	v_sqrt_f32_e32 v188, v188
	v_sqrt_f32_e32 v189, v189
	v_sqrt_f32_e32 v190, v190
	v_sqrt_f32_e32 v191, v191
	v_sqrt_f32_e32 v192, v192
	v_sqrt_f32_e32 v193, v193
	v_sqrt_f32_e32 v194, v194
	v_sqrt_f32_e32 v195, v195
	v_exp_f32_e32 v228, v228
	v_exp_f32_e32 v229, v229
	v_exp_f32_e32 v230, v230
	v_exp_f32_e32 v231, v231
	v_exp_f32_e32 v232, v232
	v_exp_f32_e32 v233, v233
	v_exp_f32_e32 v234, v234
	v_exp_f32_e32 v235, v235
	s_waitcnt vmcnt(19)
; __device__ __forceinline__ unsigned cvt_pk_bf16(float lo, float hi) { unsigned r; asm volatile("v_cvt_pk_bf16_f32 %0, %1, %2" : "=v"(r) : "v"(lo), "v"(hi)); return r; }
; __device__ __forceinline__ float bf_lo(unsigned w) { return __uint_as_float(w << 16); }
; __device__ __forceinline__ float bf_hi(unsigned w) { return __uint_as_float(w & 0xffff0000u); }
; __device__ __forceinline__ float fexp(float x) { return __builtin_amdgcn_exp2f(1.44269504f * x); }
;     __device__ __forceinline__ void operator()(AccMut acc, const Unit& u, int sw) const {
;     ...
;                         const unsigned wv = xw[2 * n + jp];
;                         f32x2 sq; sq.x = __builtin_amdgcn_sqrtf(em.x); sq.y = __builtin_amdgcn_sqrtf(em.y);
;                         const f32x2 b2 = sq * ig * (f32x2){bf_lo(wv), bf_hi(wv)};
;                         bt[4 * n + 2 * jp] = b2.x; bt[4 * n + 2 * jp + 1] = b2.y; }
;                 u32x4 w; w.x = cvt_pk_bf16(bt[0], bt[1]); w.y = cvt_pk_bf16(bt[2], bt[3]); w.z = cvt_pk_bf16(bt[4], bt[5]); w.w = cvt_pk_bf16(bt[6], bt[7]);
;                 *(u32x4*)(BT + off) = w; }
; __device__ __forceinline__ void scan1_phase(const bf16_t* LA, const bf16_t* BT, int sw, View vw) {
;     ...
;             for (int i = 0; i < 8; ++i) {
;                 const float l0 = bf_lo(lw[i].x), l1 = bf_hi(lw[i].x), l2 = bf_lo(lw[i].y), l3 = bf_hi(lw[i].y);
;                 S[0] += l0; S[1] += l1; S[2] += l2; S[3] += l3;
;                 Hc[0] = fexp(l0) * Hc[0] + bf_lo(bw[i].x); Hc[1] = fexp(l1) * Hc[1] + bf_hi(bw[i].x); Hc[2] = fexp(l2) * Hc[2] + bf_lo(bw[i].y); Hc[3] = fexp(l3) * Hc[3] + bf_hi(bw[i].y); }
;         }
;         *(f32x4*)(CP + (size_t)bq * E + 4 * quad) = (f32x4){S[0], S[1], S[2], S[3]};
;         *(f32x4*)(CH + (size_t)bq * E + 4 * quad) = (f32x4){Hc[0], Hc[1], Hc[2], Hc[3]};
	v_lshlrev_b32_e32 v196, 16, v164
	v_and_b32_e32 v197, 0xffff0000, v164
	v_lshlrev_b32_e32 v198, 16, v165
	v_and_b32_e32 v199, 0xffff0000, v165
	v_lshlrev_b32_e32 v200, 16, v166
	v_and_b32_e32 v201, 0xffff0000, v166
	v_lshlrev_b32_e32 v202, 16, v167
	v_and_b32_e32 v203, 0xffff0000, v167
	v_pk_mul_f32 v[188:189], v[188:189], v[180:181]
	v_pk_mul_f32 v[190:191], v[190:191], v[182:183]
	v_pk_mul_f32 v[192:193], v[192:193], v[184:185]
	v_pk_mul_f32 v[194:195], v[194:195], v[186:187]
	v_pk_mul_f32 v[188:189], v[188:189], v[196:197]
	v_pk_mul_f32 v[190:191], v[190:191], v[198:199]
	v_pk_mul_f32 v[192:193], v[192:193], v[200:201]
	v_pk_mul_f32 v[194:195], v[194:195], v[202:203]
	v_cvt_pk_bf16_f32 v212, v188, v189
	v_cvt_pk_bf16_f32 v213, v190, v191
	v_cvt_pk_bf16_f32 v214, v192, v193
	v_cvt_pk_bf16_f32 v215, v194, v195
	global_store_dwordx4 v179, v[212:215], s[10:11]
	v_pk_fma_f32 v[216:217], v[228:229], v[216:217], v[188:189]
	v_pk_fma_f32 v[218:219], v[230:231], v[218:219], v[190:191]
	v_pk_fma_f32 v[240:241], v[232:233], v[240:241], v[192:193]
	v_pk_fma_f32 v[242:243], v[234:235], v[242:243], v[194:195]
	v_pk_mul_f32 v[26:27], v[26:27], v[228:229]
	v_pk_mul_f32 v[28:29], v[28:29], v[230:231]
	v_pk_mul_f32 v[30:31], v[30:31], v[232:233]
	v_pk_mul_f32 v[32:33], v[32:33], v[234:235]
	v_pk_add_f32 v[110:111], v[110:111], v[74:75]
	v_pk_add_f32 v[112:113], v[112:113], v[76:77]
	v_pk_add_f32 v[102:103], v[102:103], v[70:71]
	v_pk_add_f32 v[104:105], v[104:105], v[72:73]
	v_fmac_f32_dpp v216, v216, v26 row_shr:1 row_mask:0xf bank_mask:0xf
	v_fmac_f32_dpp v217, v217, v27 row_shr:1 row_mask:0xf bank_mask:0xf
	v_fmac_f32_dpp v218, v218, v28 row_shr:1 row_mask:0xf bank_mask:0xf
	v_fmac_f32_dpp v219, v219, v29 row_shr:1 row_mask:0xf bank_mask:0xf
	v_fmac_f32_dpp v240, v240, v30 row_shr:1 row_mask:0xf bank_mask:0xf
	v_fmac_f32_dpp v241, v241, v31 row_shr:1 row_mask:0xf bank_mask:0xf
	v_fmac_f32_dpp v242, v242, v32 row_shr:1 row_mask:0xf bank_mask:0xf
	v_fmac_f32_dpp v243, v243, v33 row_shr:1 row_mask:0xf bank_mask:0xf
	v_mul_f32_dpp v26, v26, v26 row_shr:1 row_mask:0xf bank_mask:0xf
	v_mul_f32_dpp v27, v27, v27 row_shr:1 row_mask:0xf bank_mask:0xf
	v_mul_f32_dpp v28, v28, v28 row_shr:1 row_mask:0xf bank_mask:0xf
	v_mul_f32_dpp v29, v29, v29 row_shr:1 row_mask:0xf bank_mask:0xf
	v_mul_f32_dpp v30, v30, v30 row_shr:1 row_mask:0xf bank_mask:0xf
	v_mul_f32_dpp v31, v31, v31 row_shr:1 row_mask:0xf bank_mask:0xf
	v_mul_f32_dpp v32, v32, v32 row_shr:1 row_mask:0xf bank_mask:0xf
	v_mul_f32_dpp v33, v33, v33 row_shr:1 row_mask:0xf bank_mask:0xf
	v_add_f32_dpp v110, v110, v110 row_shr:1 row_mask:0xf bank_mask:0xf
	v_add_f32_dpp v111, v111, v111 row_shr:1 row_mask:0xf bank_mask:0xf
	v_add_f32_dpp v112, v112, v112 row_shr:1 row_mask:0xf bank_mask:0xf
	v_add_f32_dpp v113, v113, v113 row_shr:1 row_mask:0xf bank_mask:0xf
	v_add_f32_dpp v102, v102, v102 row_shr:1 row_mask:0xf bank_mask:0xf
	v_add_f32_dpp v103, v103, v103 row_shr:1 row_mask:0xf bank_mask:0xf
	v_add_f32_dpp v104, v104, v104 row_shr:1 row_mask:0xf bank_mask:0xf
	v_add_f32_dpp v105, v105, v105 row_shr:1 row_mask:0xf bank_mask:0xf
	v_fmac_f32_dpp v216, v216, v26 row_shr:2 row_mask:0xf bank_mask:0xf
	v_fmac_f32_dpp v217, v217, v27 row_shr:2 row_mask:0xf bank_mask:0xf
	v_fmac_f32_dpp v218, v218, v28 row_shr:2 row_mask:0xf bank_mask:0xf
	v_fmac_f32_dpp v219, v219, v29 row_shr:2 row_mask:0xf bank_mask:0xf
	v_fmac_f32_dpp v240, v240, v30 row_shr:2 row_mask:0xf bank_mask:0xf
	v_fmac_f32_dpp v241, v241, v31 row_shr:2 row_mask:0xf bank_mask:0xf
	v_fmac_f32_dpp v242, v242, v32 row_shr:2 row_mask:0xf bank_mask:0xf
	v_fmac_f32_dpp v243, v243, v33 row_shr:2 row_mask:0xf bank_mask:0xf
	v_mul_f32_dpp v26, v26, v26 row_shr:2 row_mask:0xf bank_mask:0xf
	v_mul_f32_dpp v27, v27, v27 row_shr:2 row_mask:0xf bank_mask:0xf
	v_mul_f32_dpp v28, v28, v28 row_shr:2 row_mask:0xf bank_mask:0xf
	v_mul_f32_dpp v29, v29, v29 row_shr:2 row_mask:0xf bank_mask:0xf
	v_mul_f32_dpp v30, v30, v30 row_shr:2 row_mask:0xf bank_mask:0xf
; __device__ __forceinline__ float bf_lo(unsigned w) { return __uint_as_float(w << 16); }
; __device__ __forceinline__ float bf_hi(unsigned w) { return __uint_as_float(w & 0xffff0000u); }
; __device__ __forceinline__ float fexp(float x) { return __builtin_amdgcn_exp2f(1.44269504f * x); }
; __device__ __forceinline__ void scan1_phase(const bf16_t* LA, const bf16_t* BT, int sw, View vw) {
;     ...
;             for (int i = 0; i < 8; ++i) {
;                 const float l0 = bf_lo(lw[i].x), l1 = bf_hi(lw[i].x), l2 = bf_lo(lw[i].y), l3 = bf_hi(lw[i].y);
;                 S[0] += l0; S[1] += l1; S[2] += l2; S[3] += l3;
;                 Hc[0] = fexp(l0) * Hc[0] + bf_lo(bw[i].x); Hc[1] = fexp(l1) * Hc[1] + bf_hi(bw[i].x); Hc[2] = fexp(l2) * Hc[2] + bf_lo(bw[i].y); Hc[3] = fexp(l3) * Hc[3] + bf_hi(bw[i].y); }
;         }
;         *(f32x4*)(CP + (size_t)bq * E + 4 * quad) = (f32x4){S[0], S[1], S[2], S[3]};
;         *(f32x4*)(CH + (size_t)bq * E + 4 * quad) = (f32x4){Hc[0], Hc[1], Hc[2], Hc[3]};
	v_mul_f32_dpp v31, v31, v31 row_shr:2 row_mask:0xf bank_mask:0xf
	v_mul_f32_dpp v32, v32, v32 row_shr:2 row_mask:0xf bank_mask:0xf
	v_mul_f32_dpp v33, v33, v33 row_shr:2 row_mask:0xf bank_mask:0xf
	v_add_f32_dpp v110, v110, v110 row_shr:2 row_mask:0xf bank_mask:0xf
	v_add_f32_dpp v111, v111, v111 row_shr:2 row_mask:0xf bank_mask:0xf
	v_add_f32_dpp v112, v112, v112 row_shr:2 row_mask:0xf bank_mask:0xf
	v_add_f32_dpp v113, v113, v113 row_shr:2 row_mask:0xf bank_mask:0xf
	v_add_f32_dpp v102, v102, v102 row_shr:2 row_mask:0xf bank_mask:0xf
	v_add_f32_dpp v103, v103, v103 row_shr:2 row_mask:0xf bank_mask:0xf
	v_add_f32_dpp v104, v104, v104 row_shr:2 row_mask:0xf bank_mask:0xf
	v_add_f32_dpp v105, v105, v105 row_shr:2 row_mask:0xf bank_mask:0xf
	v_fmac_f32_dpp v216, v216, v26 row_shr:4 row_mask:0xf bank_mask:0xf
	v_fmac_f32_dpp v217, v217, v27 row_shr:4 row_mask:0xf bank_mask:0xf
	v_fmac_f32_dpp v218, v218, v28 row_shr:4 row_mask:0xf bank_mask:0xf
	v_fmac_f32_dpp v219, v219, v29 row_shr:4 row_mask:0xf bank_mask:0xf
	v_fmac_f32_dpp v240, v240, v30 row_shr:4 row_mask:0xf bank_mask:0xf
	v_fmac_f32_dpp v241, v241, v31 row_shr:4 row_mask:0xf bank_mask:0xf
	v_fmac_f32_dpp v242, v242, v32 row_shr:4 row_mask:0xf bank_mask:0xf
	v_fmac_f32_dpp v243, v243, v33 row_shr:4 row_mask:0xf bank_mask:0xf
	v_mul_f32_dpp v26, v26, v26 row_shr:4 row_mask:0xf bank_mask:0xf
	v_mul_f32_dpp v27, v27, v27 row_shr:4 row_mask:0xf bank_mask:0xf
	v_mul_f32_dpp v28, v28, v28 row_shr:4 row_mask:0xf bank_mask:0xf
	v_mul_f32_dpp v29, v29, v29 row_shr:4 row_mask:0xf bank_mask:0xf
	v_mul_f32_dpp v30, v30, v30 row_shr:4 row_mask:0xf bank_mask:0xf
	v_mul_f32_dpp v31, v31, v31 row_shr:4 row_mask:0xf bank_mask:0xf
	v_mul_f32_dpp v32, v32, v32 row_shr:4 row_mask:0xf bank_mask:0xf
	v_mul_f32_dpp v33, v33, v33 row_shr:4 row_mask:0xf bank_mask:0xf
	v_add_f32_dpp v110, v110, v110 row_shr:4 row_mask:0xf bank_mask:0xf
	v_add_f32_dpp v111, v111, v111 row_shr:4 row_mask:0xf bank_mask:0xf
	v_add_f32_dpp v112, v112, v112 row_shr:4 row_mask:0xf bank_mask:0xf
	v_add_f32_dpp v113, v113, v113 row_shr:4 row_mask:0xf bank_mask:0xf
	v_add_f32_dpp v102, v102, v102 row_shr:4 row_mask:0xf bank_mask:0xf
	v_add_f32_dpp v103, v103, v103 row_shr:4 row_mask:0xf bank_mask:0xf
	v_add_f32_dpp v104, v104, v104 row_shr:4 row_mask:0xf bank_mask:0xf
	v_add_f32_dpp v105, v105, v105 row_shr:4 row_mask:0xf bank_mask:0xf
	v_fmac_f32_dpp v216, v216, v26 row_shr:8 row_mask:0xf bank_mask:0xf
	v_fmac_f32_dpp v217, v217, v27 row_shr:8 row_mask:0xf bank_mask:0xf
	v_fmac_f32_dpp v218, v218, v28 row_shr:8 row_mask:0xf bank_mask:0xf
	v_fmac_f32_dpp v219, v219, v29 row_shr:8 row_mask:0xf bank_mask:0xf
	v_fmac_f32_dpp v240, v240, v30 row_shr:8 row_mask:0xf bank_mask:0xf
	v_fmac_f32_dpp v241, v241, v31 row_shr:8 row_mask:0xf bank_mask:0xf
	v_fmac_f32_dpp v242, v242, v32 row_shr:8 row_mask:0xf bank_mask:0xf
	v_fmac_f32_dpp v243, v243, v33 row_shr:8 row_mask:0xf bank_mask:0xf
	v_add_f32_dpp v110, v110, v110 row_shr:8 row_mask:0xf bank_mask:0xf
	v_add_f32_dpp v111, v111, v111 row_shr:8 row_mask:0xf bank_mask:0xf
	v_add_f32_dpp v112, v112, v112 row_shr:8 row_mask:0xf bank_mask:0xf
	v_add_f32_dpp v113, v113, v113 row_shr:8 row_mask:0xf bank_mask:0xf
	v_add_f32_dpp v102, v102, v102 row_shr:8 row_mask:0xf bank_mask:0xf
	v_add_f32_dpp v103, v103, v103 row_shr:8 row_mask:0xf bank_mask:0xf
	v_add_f32_dpp v104, v104, v104 row_shr:8 row_mask:0xf bank_mask:0xf
	v_add_f32_dpp v105, v105, v105 row_shr:8 row_mask:0xf bank_mask:0xf
	v_mbcnt_lo_u32_b32 v180, -1, 0
	v_mbcnt_hi_u32_b32 v180, -1, v180
	v_and_b32_e32 v180, 15, v180
	v_cmp_eq_u32_e32 vcc, 15, v180
	v_add_u32_e32 v181, 0x4000, v239
	v_add_u32_e32 v182, 0x404000, v239
	s_mov_b64 exec, vcc
	global_store_dwordx4 v181, v[110:113], s[26:27]
	global_store_dwordx4 v181, v[102:105], s[26:27] offset:16
	global_store_dwordx4 v182, v[216:219], s[26:27]
	global_store_dwordx4 v182, v[240:243], s[26:27] offset:16
	s_mov_b64 exec, -1
	s_branch .Lgate_epi_done

; #define VIEW() (ctlw[12] ? View{(int)__builtin_amdgcn_readfirstlane((int)ctlw[11]), 32, (int)__builtin_amdgcn_readfirstlane((int)ctlw[10]) * (M / 8), M / 8} : View{lbid(), lgrid(), 0, M})
; __global__ void __launch_bounds__(512, 2) mega_fwd(Args a) {
;     ...
;             { int nst_ = 2; asm volatile("" : "+s"(nst_));
;               for (int st_ = 0; st_ < nst_; ++st_) {
;                 const View vw = VIEW(); const size_t ro = (size_t)vw.row0;
;                 if (st_ == 0) scan1_phase(WSB(WS_R1), WSB(WS_R4), sw, vw);
;                 else { pg8::Gemm g{WSB(WS_H) + ro * D, WSW(2 * MiB), D, D, D, 0}; pg8::StaticOrder S; S.init(vw.MR / 256, E / 256, vw.vG, vw.vb);
;                        pg8::EpiPlain<0> Ep{WSB(WS_R3) + ro * E, E}; pg8::gemm_phase(lds, g, S, Ep, sw); } } }
.LBB0_551:
	s_or_b64 exec, exec, s[0:1]
	s_mov_b32 s15, 2
	s_waitcnt lgkmcnt(0)
	s_barrier
	s_cmp_lt_i32 s15, 1
	s_cbranch_scc1 .LBB0_579
	s_mov_b32 s26, 1
	s_branch .LBB0_555
